# GEMM loops: hipcc per-phase s_setprio flips removed, one static s_setprio 1 for waves 4-7 at kernel entry (waves 0-3 variant measured slower)
# speedup vs baseline: 1.0664x; 1.0058x over previous
; #define LAS __attribute__((address_space(3)))
; __device__ __forceinline__ int ogrid() { int g = gridDim.x; asm volatile("" : "+s"(g)); return g; }
; __device__ __forceinline__ unsigned xb_add(unsigned* p, unsigned v) { return __hip_atomic_fetch_add(p, v, __ATOMIC_RELAXED, __HIP_MEMORY_SCOPE_AGENT); }
; __device__ __forceinline__ unsigned xb_xcc_id() { return (unsigned)__builtin_amdgcn_s_getreg((3 << 11) | 20) & 0xFu; }
; __device__ __forceinline__ XcdBarrier xcd_barrier_post(unsigned* bar, volatile LAS unsigned* st) {
;     XcdBarrier b; b.bar = bar; b.x = xb_xcc_id(); b.st = st;
;     if (threadIdx.x == 0) (void)xb_add(&bar[XB_XCNT(b.x)], 1u);
;     return b;
; __global__ void __launch_bounds__(NTHREADS, 2) fwd_megakernel(Params P) {
;     extern __shared__ __attribute__((aligned(16))) unsigned char lds_raw[];
;     LAS unsigned char* lds = (LAS unsigned char*)lds_raw;
;     cg::grid_group grid = cg::this_grid();
;     const int G = ogrid(), bid = blockIdx.x;
;     volatile LAS unsigned* xst = (volatile LAS unsigned*)(lds + 131072);
;     if (threadIdx.x < 4) xst[threadIdx.x] = 0u;
;     __syncthreads();
;     (void)xcd_barrier_post((unsigned*)(P.ws + WS_CTL), xst);
_Z14fwd_megakernel6Params:
	s_load_dwordx2 s[52:53], s[0:1], 0x90
	s_load_dwordx4 s[28:31], s[0:1], 0x80
	s_load_dword s3, s[0:1], 0x98
	s_add_u32 s8, s0, 0x90
	v_and_b32_e32 v232, 0x3ff, v0
	s_waitcnt lgkmcnt(0)
	v_writelane_b32 v254, s52, 0
	s_addc_u32 s9, s1, 0
	v_cmp_gt_u32_e32 vcc, 4, v232
	v_writelane_b32 v254, s53, 1
	s_and_saveexec_b64 s[4:5], vcc
	v_lshl_add_u32 v1, v232, 2, 0
	v_add_u32_e32 v1, 0x20000, v1
	v_mov_b32_e32 v2, 0
	ds_write_b32 v1, v2
	s_or_b64 exec, exec, s[4:5]
	v_readfirstlane_b32 s98, v232
	s_lshr_b32 s98, s98, 8
	s_cmp_eq_u32 s98, 0
	s_cbranch_scc1 .Lprio_done
	s_setprio 1
.Lprio_done:
	s_waitcnt lgkmcnt(0)
	s_barrier
	s_getreg_b32 s10, hwreg(HW_REG_XCC_ID, 0, 4)
	v_cmp_eq_u32_e64 s[88:89], 0, v232
	s_and_saveexec_b64 s[4:5], s[88:89]
	s_cbranch_execz .LBB0_5
	s_mov_b64 s[6:7], exec
	v_mbcnt_lo_u32_b32 v1, s6, 0
	v_mbcnt_hi_u32_b32 v1, s7, v1
	v_cmp_eq_u32_e32 vcc, 0, v1
	s_and_b64 s[12:13], exec, vcc
	s_mov_b64 exec, s[12:13]
	s_cbranch_execz .LBB0_5
	s_lshl_b32 s10, s10, 8
	s_and_b32 s10, s10, 0xf00
	s_bcnt1_i32_b64 s6, s[6:7]
	v_mov_b32_e32 v1, s10
	v_mov_b32_e32 v2, s6
	global_atomic_add v1, v2, s[30:31] offset:1024

; #define PG8_STAGE(bufoff, gbase, voff) do { _Pragma("unroll") for (int _i = 0; _i < 2; ++_i) \
;         __builtin_amdgcn_global_load_lds((const unsigned*)((const char*)(gbase) + (voff)[_i]), (LAS unsigned*)(lds + (bufoff) + ldsw + _i * 8192), 16, 0, 0); } while (0)
; #define PG8_LDA(dst, b, h) do { _Pragma("unroll") for (int m = 0; m < 4; ++m) _Pragma("unroll") for (int k = 0; k < 2; ++k) dst[m][k] = *(const LAS bf16x8*)(lds + PG8_SA(b, h) + aoff + m * 2048 + k * 1024); } while (0)
; #define PG8_LDB(dst, b, h) do { _Pragma("unroll") for (int n = 0; n < 2; ++n) _Pragma("unroll") for (int k = 0; k < 2; ++k) dst[n][k] = *(const LAS bf16x8*)(lds + PG8_SB(b, h) + boff + n * 2048 + k * 1024); } while (0)
; #define PG8_MMA(ai, bj, At, Bt) do { __builtin_amdgcn_s_setprio(1); _Pragma("unroll") for (int m = 0; m < 4; ++m) _Pragma("unroll") for (int n = 0; n < 2; ++n) _Pragma("unroll") for (int k = 0; k < 2; ++k) \
;         acc[ai][bj][m][n] = __builtin_amdgcn_mfma_f32_16x16x32_bf16(Bt[n][k], At[m][k], acc[ai][bj][m][n], 0, 0, 0); __builtin_amdgcn_s_setprio(0); } while (0)
; #define PG8_WAIT_V(n) asm volatile("s_waitcnt vmcnt(" #n ")" ::: "memory")
; #define PG8_WAIT_L(n) asm volatile("s_waitcnt lgkmcnt(" #n ")" ::: "memory")
; #define PG8_BAR __builtin_amdgcn_s_barrier()
; #define PG8_SCHED __builtin_amdgcn_sched_barrier(0)
; template <class Epi, class Sched>
; __device__ __forceinline__ void gemm_phase(LAS unsigned char* lds, const Gemm g, const Sched& S, const Epi& E) {
;     ...
;             PG8_LDB(B0, 0, 0); PG8_SCHED; PG8_LDA(At, 0, 0); PG8_STAGE(PG8_SA(1, 1), a1 + hstep, voffA);
;             PG8_WAIT_L(8); PG8_BAR; PG8_WAIT_L(0); PG8_MMA(0, 0, At, B0); PG8_BAR; PG8_SCHED;
;             PG8_LDB(B1, 0, 1); PG8_STAGE(PG8_SB(0, 0), b2, voffB);
;             PG8_BAR; PG8_WAIT_L(0); PG8_MMA(0, 1, At, B1); PG8_BAR;
;             PG8_LDA(At, 0, 1); PG8_STAGE(PG8_SA(0, 0), a2, voffA);
;             PG8_BAR; PG8_WAIT_L(0); PG8_MMA(1, 0, At, B0); PG8_BAR; PG8_SCHED;
;             PG8_STAGE(PG8_SB(0, 1), b2 + hstep, voffB);
;             PG8_WAIT_V(6); PG8_BAR; PG8_MMA(1, 1, At, B1); PG8_BAR;
.LBB0_286:
	s_add_u32 s28, vcc_lo, 0xfffc0080
	s_addc_u32 s29, vcc_hi, -1
	s_add_i32 s38, 0, 0x10000
	v_add_u32_e32 v142, s38, v171
	ds_read_b128 v[130:133], v142
	ds_read_b128 v[134:137], v142 offset:1024
	ds_read_b128 v[138:141], v142 offset:2048
	ds_read_b128 v[142:145], v142 offset:3072
	s_cmp_eq_u32 s47, 12
	s_cselect_b32 s97, s83, s29
	s_cselect_b32 s96, s16, s28
	s_cselect_b32 s29, s45, s17
	s_cselect_b32 s28, s88, s89
	v_lshl_add_u64 v[168:169], vcc, 0, v[152:153]
	s_add_i32 m0, s58, 0xc000
	ds_read_b128 v[156:159], v175
	ds_read_b128 v[160:163], v175 offset:1024
	ds_read_b128 v[164:167], v175 offset:2048
	ds_read_b128 v[176:179], v175 offset:3072
	ds_read_b128 v[180:183], v175 offset:4096
	ds_read_b128 v[184:187], v175 offset:5120
	ds_read_b128 v[188:191], v175 offset:6144
	ds_read_b128 v[192:195], v175 offset:7168
	global_load_lds_dwordx4 v[168:169], off
	v_lshl_add_u64 v[168:169], vcc, 0, v[154:155]
	s_add_i32 m0, s58, 0xe000
	s_nop 0
	global_load_lds_dwordx4 v[168:169], off
	s_waitcnt lgkmcnt(8)
	s_barrier
	s_waitcnt lgkmcnt(0)
	s_waitcnt lgkmcnt(0)
	v_mfma_f32_16x16x32_bf16 v[126:129], v[130:133], v[156:159], v[126:129]
	v_mfma_f32_16x16x32_bf16 v[122:125], v[138:141], v[156:159], v[122:125]
	v_mfma_f32_16x16x32_bf16 v[118:121], v[130:133], v[164:167], v[118:121]
	v_mfma_f32_16x16x32_bf16 v[110:113], v[138:141], v[164:167], v[110:113]
	v_mfma_f32_16x16x32_bf16 v[102:105], v[130:133], v[180:183], v[102:105]
	v_mfma_f32_16x16x32_bf16 v[94:97], v[138:141], v[180:183], v[94:97]
	v_mfma_f32_16x16x32_bf16 v[86:89], v[130:133], v[188:191], v[86:89]
	v_mfma_f32_16x16x32_bf16 v[78:81], v[138:141], v[188:191], v[78:81]
	v_mfma_f32_16x16x32_bf16 v[126:129], v[134:137], v[160:163], v[126:129]
	v_mfma_f32_16x16x32_bf16 v[122:125], v[142:145], v[160:163], v[122:125]
	v_mfma_f32_16x16x32_bf16 v[118:121], v[134:137], v[176:179], v[118:121]
	v_mfma_f32_16x16x32_bf16 v[110:113], v[142:145], v[176:179], v[110:113]
	v_mfma_f32_16x16x32_bf16 v[102:105], v[134:137], v[184:187], v[102:105]
	v_mfma_f32_16x16x32_bf16 v[94:97], v[142:145], v[184:187], v[94:97]
	v_mfma_f32_16x16x32_bf16 v[86:89], v[134:137], v[192:195], v[86:89]
	v_mfma_f32_16x16x32_bf16 v[78:81], v[142:145], v[192:195], v[78:81]
	s_barrier
	s_add_i32 s33, 0, 0x14000
	v_add_u32_e32 v168, s33, v171
	s_add_i32 s38, s38, s27
	ds_read_b128 v[196:199], v168
	ds_read_b128 v[200:203], v168 offset:1024
	ds_read_b128 v[204:207], v168 offset:2048
	ds_read_b128 v[208:211], v168 offset:3072
	v_lshl_add_u64 v[168:169], s[28:29], 0, v[0:1]
	s_mov_b32 m0, s38
	v_lshl_add_u64 v[212:213], s[28:29], 0, v[150:151]
	global_load_lds_dwordx4 v[168:169], off
	s_add_i32 m0, s38, 0x2000
	s_nop 0
	global_load_lds_dwordx4 v[212:213], off
	s_barrier
	s_waitcnt lgkmcnt(0)
	s_waitcnt lgkmcnt(0)
	v_mfma_f32_16x16x32_bf16 v[114:117], v[196:199], v[156:159], v[114:117]
	v_mfma_f32_16x16x32_bf16 v[106:109], v[204:207], v[156:159], v[106:109]
	v_mfma_f32_16x16x32_bf16 v[98:101], v[196:199], v[164:167], v[98:101]
	v_mfma_f32_16x16x32_bf16 v[90:93], v[204:207], v[164:167], v[90:93]
	v_mfma_f32_16x16x32_bf16 v[82:85], v[196:199], v[180:183], v[82:85]
	v_mfma_f32_16x16x32_bf16 v[74:77], v[204:207], v[180:183], v[74:77]
	v_mfma_f32_16x16x32_bf16 v[70:73], v[196:199], v[188:191], v[70:73]
	v_mfma_f32_16x16x32_bf16 v[66:69], v[204:207], v[188:191], v[66:69]
	v_mfma_f32_16x16x32_bf16 v[114:117], v[200:203], v[160:163], v[114:117]
	v_mfma_f32_16x16x32_bf16 v[106:109], v[208:211], v[160:163], v[106:109]
	v_mfma_f32_16x16x32_bf16 v[98:101], v[200:203], v[176:179], v[98:101]
	v_mfma_f32_16x16x32_bf16 v[90:93], v[208:211], v[176:179], v[90:93]
	v_mfma_f32_16x16x32_bf16 v[82:85], v[200:203], v[184:187], v[82:85]
	v_mfma_f32_16x16x32_bf16 v[74:77], v[208:211], v[184:187], v[74:77]
	v_mfma_f32_16x16x32_bf16 v[70:73], v[200:203], v[192:195], v[70:73]
	v_mfma_f32_16x16x32_bf16 v[66:69], v[208:211], v[192:195], v[66:69]
	s_mov_b32 m0, s58
	v_lshl_add_u64 v[214:215], s[96:97], 0, v[146:147]
	s_barrier
	ds_read_b128 v[156:159], v175 offset:16384
	ds_read_b128 v[160:163], v175 offset:17408
	ds_read_b128 v[164:167], v175 offset:18432
	ds_read_b128 v[176:179], v175 offset:19456
	ds_read_b128 v[180:183], v175 offset:20480
	ds_read_b128 v[184:187], v175 offset:21504
	ds_read_b128 v[188:191], v175 offset:22528
	ds_read_b128 v[192:195], v175 offset:23552
	global_load_lds_dwordx4 v[214:215], off
	v_lshl_add_u64 v[216:217], s[96:97], 0, v[148:149]
	s_mov_b32 m0, s72
	s_nop 0
	global_load_lds_dwordx4 v[216:217], off
	s_barrier
	s_waitcnt lgkmcnt(0)
	s_waitcnt lgkmcnt(0)
	v_mfma_f32_16x16x32_bf16 v[62:65], v[130:133], v[156:159], v[62:65]
	v_mfma_f32_16x16x32_bf16 v[58:61], v[138:141], v[156:159], v[58:61]
	v_mfma_f32_16x16x32_bf16 v[54:57], v[130:133], v[164:167], v[54:57]
	v_mfma_f32_16x16x32_bf16 v[46:49], v[138:141], v[164:167], v[46:49]
	v_mfma_f32_16x16x32_bf16 v[34:37], v[130:133], v[180:183], v[34:37]
	v_mfma_f32_16x16x32_bf16 v[26:29], v[138:141], v[180:183], v[26:29]
	v_mfma_f32_16x16x32_bf16 v[22:25], v[130:133], v[188:191], v[22:25]
	v_mfma_f32_16x16x32_bf16 v[14:17], v[138:141], v[188:191], v[14:17]
	v_mfma_f32_16x16x32_bf16 v[62:65], v[134:137], v[160:163], v[62:65]
	v_mfma_f32_16x16x32_bf16 v[58:61], v[142:145], v[160:163], v[58:61]
	v_mfma_f32_16x16x32_bf16 v[54:57], v[134:137], v[176:179], v[54:57]
	v_mfma_f32_16x16x32_bf16 v[46:49], v[142:145], v[176:179], v[46:49]
	v_mfma_f32_16x16x32_bf16 v[34:37], v[134:137], v[184:187], v[34:37]
	v_mfma_f32_16x16x32_bf16 v[26:29], v[142:145], v[184:187], v[26:29]
	v_mfma_f32_16x16x32_bf16 v[22:25], v[134:137], v[192:195], v[22:25]
	v_mfma_f32_16x16x32_bf16 v[14:17], v[142:145], v[192:195], v[14:17]
	s_barrier
; #define PG8_STAGE(bufoff, gbase, voff) do { _Pragma("unroll") for (int _i = 0; _i < 2; ++_i) \
;         __builtin_amdgcn_global_load_lds((const unsigned*)((const char*)(gbase) + (voff)[_i]), (LAS unsigned*)(lds + (bufoff) + ldsw + _i * 8192), 16, 0, 0); } while (0)
; #define PG8_LDA(dst, b, h) do { _Pragma("unroll") for (int m = 0; m < 4; ++m) _Pragma("unroll") for (int k = 0; k < 2; ++k) dst[m][k] = *(const LAS bf16x8*)(lds + PG8_SA(b, h) + aoff + m * 2048 + k * 1024); } while (0)
; #define PG8_LDB(dst, b, h) do { _Pragma("unroll") for (int n = 0; n < 2; ++n) _Pragma("unroll") for (int k = 0; k < 2; ++k) dst[n][k] = *(const LAS bf16x8*)(lds + PG8_SB(b, h) + boff + n * 2048 + k * 1024); } while (0)
; #define PG8_MMA(ai, bj, At, Bt) do { __builtin_amdgcn_s_setprio(1); _Pragma("unroll") for (int m = 0; m < 4; ++m) _Pragma("unroll") for (int n = 0; n < 2; ++n) _Pragma("unroll") for (int k = 0; k < 2; ++k) \
;         acc[ai][bj][m][n] = __builtin_amdgcn_mfma_f32_16x16x32_bf16(Bt[n][k], At[m][k], acc[ai][bj][m][n], 0, 0, 0); __builtin_amdgcn_s_setprio(0); } while (0)
; #define PG8_WAIT_V(n) asm volatile("s_waitcnt vmcnt(" #n ")" ::: "memory")
; #define PG8_WAIT_L(n) asm volatile("s_waitcnt lgkmcnt(" #n ")" ::: "memory")
; #define PG8_BAR __builtin_amdgcn_s_barrier()
; #define PG8_SCHED __builtin_amdgcn_sched_barrier(0)
; template <class Epi, class Sched>
; __device__ __forceinline__ void gemm_phase(LAS unsigned char* lds, const Gemm g, const Sched& S, const Epi& E) {
;     ...
;             PG8_STAGE(PG8_SB(0, 1), b2 + hstep, voffB);
;             PG8_WAIT_V(6); PG8_BAR; PG8_MMA(1, 1, At, B1); PG8_BAR;
;             PG8_LDB(B0, 1, 0); PG8_SCHED; PG8_LDA(At, 1, 0); PG8_STAGE(PG8_SA(0, 1), a2 + hstep, voffA);
;             PG8_WAIT_L(8); PG8_BAR; PG8_WAIT_L(0); PG8_MMA(0, 0, At, B0); PG8_BAR; PG8_SCHED;
;             PG8_LDB(B1, 1, 1); PG8_STAGE(PG8_SB(1, 0), b3, voffB);
;             PG8_BAR; PG8_WAIT_L(0); PG8_MMA(0, 1, At, B1); PG8_BAR;
;             PG8_LDA(At, 1, 1); PG8_STAGE(PG8_SA(1, 0), a3, voffA);
;             PG8_BAR; PG8_WAIT_L(0); PG8_MMA(1, 0, At, B0); PG8_BAR; PG8_SCHED;
	s_add_u32 s38, s28, 0x40000
	s_addc_u32 s39, s29, 0
	s_add_i32 s33, s33, s27
	v_lshl_add_u64 v[130:131], s[38:39], 0, v[0:1]
	s_mov_b32 m0, s33
	s_nop 0
	global_load_lds_dwordx4 v[130:131], off
	v_lshl_add_u64 v[130:131], s[38:39], 0, v[150:151]
	s_add_i32 m0, s33, 0x2000
	s_nop 0
	global_load_lds_dwordx4 v[130:131], off
	s_waitcnt vmcnt(6)
	s_barrier
	v_mfma_f32_16x16x32_bf16 v[50:53], v[196:199], v[156:159], v[50:53]
	v_mfma_f32_16x16x32_bf16 v[42:45], v[204:207], v[156:159], v[42:45]
	v_mfma_f32_16x16x32_bf16 v[38:41], v[196:199], v[164:167], v[38:41]
	v_mfma_f32_16x16x32_bf16 v[30:33], v[204:207], v[164:167], v[30:33]
	v_mfma_f32_16x16x32_bf16 v[18:21], v[196:199], v[180:183], v[18:21]
	v_mfma_f32_16x16x32_bf16 v[10:13], v[204:207], v[180:183], v[10:13]
	v_mfma_f32_16x16x32_bf16 v[6:9], v[196:199], v[188:191], v[6:9]
	v_mfma_f32_16x16x32_bf16 v[2:5], v[204:207], v[188:191], v[2:5]
	v_mfma_f32_16x16x32_bf16 v[50:53], v[200:203], v[160:163], v[50:53]
	v_mfma_f32_16x16x32_bf16 v[42:45], v[208:211], v[160:163], v[42:45]
	v_mfma_f32_16x16x32_bf16 v[38:41], v[200:203], v[176:179], v[38:41]
	v_mfma_f32_16x16x32_bf16 v[30:33], v[208:211], v[176:179], v[30:33]
	v_mfma_f32_16x16x32_bf16 v[18:21], v[200:203], v[184:187], v[18:21]
	v_mfma_f32_16x16x32_bf16 v[10:13], v[208:211], v[184:187], v[10:13]
	v_mfma_f32_16x16x32_bf16 v[6:9], v[200:203], v[192:195], v[6:9]
	v_mfma_f32_16x16x32_bf16 v[2:5], v[208:211], v[192:195], v[2:5]
	s_add_i32 s33, 0, 0x18000
	v_add_u32_e32 v142, s33, v171
	s_barrier
	ds_read_b128 v[130:133], v142
	ds_read_b128 v[134:137], v142 offset:1024
	ds_read_b128 v[138:141], v142 offset:2048
	ds_read_b128 v[142:145], v142 offset:3072
	s_add_u32 s38, s96, 0x40000
	s_addc_u32 s39, s97, 0
	s_mov_b32 m0, s73
	v_lshl_add_u64 v[196:197], s[38:39], 0, v[146:147]
	ds_read_b128 v[156:159], v175 offset:32768
	ds_read_b128 v[160:163], v175 offset:33792
	ds_read_b128 v[164:167], v175 offset:34816
	ds_read_b128 v[176:179], v175 offset:35840
	ds_read_b128 v[180:183], v175 offset:36864
	ds_read_b128 v[184:187], v175 offset:37888
	ds_read_b128 v[188:191], v175 offset:38912
	ds_read_b128 v[192:195], v175 offset:39936
	global_load_lds_dwordx4 v[196:197], off
	v_lshl_add_u64 v[196:197], s[38:39], 0, v[148:149]
	s_mov_b32 m0, s85
	s_nop 0
	global_load_lds_dwordx4 v[196:197], off
	s_waitcnt lgkmcnt(8)
	s_barrier
	s_waitcnt lgkmcnt(0)
	s_waitcnt lgkmcnt(0)
	v_mfma_f32_16x16x32_bf16 v[126:129], v[130:133], v[156:159], v[126:129]
	v_mfma_f32_16x16x32_bf16 v[122:125], v[138:141], v[156:159], v[122:125]
	v_mfma_f32_16x16x32_bf16 v[118:121], v[130:133], v[164:167], v[118:121]
	v_mfma_f32_16x16x32_bf16 v[110:113], v[138:141], v[164:167], v[110:113]
	v_mfma_f32_16x16x32_bf16 v[102:105], v[130:133], v[180:183], v[102:105]
	v_mfma_f32_16x16x32_bf16 v[94:97], v[138:141], v[180:183], v[94:97]
	v_mfma_f32_16x16x32_bf16 v[86:89], v[130:133], v[188:191], v[86:89]
	v_mfma_f32_16x16x32_bf16 v[78:81], v[138:141], v[188:191], v[78:81]
	v_mfma_f32_16x16x32_bf16 v[126:129], v[134:137], v[160:163], v[126:129]
	v_mfma_f32_16x16x32_bf16 v[122:125], v[142:145], v[160:163], v[122:125]
	v_mfma_f32_16x16x32_bf16 v[118:121], v[134:137], v[176:179], v[118:121]
	v_mfma_f32_16x16x32_bf16 v[110:113], v[142:145], v[176:179], v[110:113]
	v_mfma_f32_16x16x32_bf16 v[102:105], v[134:137], v[184:187], v[102:105]
	v_mfma_f32_16x16x32_bf16 v[94:97], v[142:145], v[184:187], v[94:97]
	v_mfma_f32_16x16x32_bf16 v[86:89], v[134:137], v[192:195], v[86:89]
	v_mfma_f32_16x16x32_bf16 v[78:81], v[142:145], v[192:195], v[78:81]
	s_barrier
	s_add_i32 s38, 0, 0x1c000
	s_add_i32 s33, s33, s27
	v_add_u32_e32 v208, s38, v171
	v_lshl_add_u64 v[168:169], v[168:169], 0, s[62:63]
	s_mov_b32 m0, s33
	ds_read_b128 v[196:199], v208
	ds_read_b128 v[200:203], v208 offset:1024
	ds_read_b128 v[204:207], v208 offset:2048
	ds_read_b128 v[208:211], v208 offset:3072
	global_load_lds_dwordx4 v[168:169], off
	v_lshl_add_u64 v[168:169], v[212:213], 0, s[62:63]
	s_add_i32 m0, s33, 0x2000
	s_nop 0
	global_load_lds_dwordx4 v[168:169], off
	s_barrier
	s_waitcnt lgkmcnt(0)
	s_waitcnt lgkmcnt(0)
	v_mfma_f32_16x16x32_bf16 v[114:117], v[196:199], v[156:159], v[114:117]
	v_mfma_f32_16x16x32_bf16 v[106:109], v[204:207], v[156:159], v[106:109]
	v_mfma_f32_16x16x32_bf16 v[98:101], v[196:199], v[164:167], v[98:101]
	v_mfma_f32_16x16x32_bf16 v[90:93], v[204:207], v[164:167], v[90:93]
	v_mfma_f32_16x16x32_bf16 v[82:85], v[196:199], v[180:183], v[82:85]
	v_mfma_f32_16x16x32_bf16 v[74:77], v[204:207], v[180:183], v[74:77]
	v_mfma_f32_16x16x32_bf16 v[70:73], v[196:199], v[188:191], v[70:73]
	v_mfma_f32_16x16x32_bf16 v[66:69], v[204:207], v[188:191], v[66:69]
	v_mfma_f32_16x16x32_bf16 v[114:117], v[200:203], v[160:163], v[114:117]
	v_mfma_f32_16x16x32_bf16 v[106:109], v[208:211], v[160:163], v[106:109]
	v_mfma_f32_16x16x32_bf16 v[98:101], v[200:203], v[176:179], v[98:101]
	v_mfma_f32_16x16x32_bf16 v[90:93], v[208:211], v[176:179], v[90:93]
	v_mfma_f32_16x16x32_bf16 v[82:85], v[200:203], v[184:187], v[82:85]
	v_mfma_f32_16x16x32_bf16 v[74:77], v[208:211], v[184:187], v[74:77]
	v_mfma_f32_16x16x32_bf16 v[70:73], v[200:203], v[192:195], v[70:73]
	v_mfma_f32_16x16x32_bf16 v[66:69], v[208:211], v[192:195], v[66:69]
	s_mov_b32 m0, s95
	v_lshl_add_u64 v[168:169], v[214:215], 0, s[62:63]
	s_barrier
	ds_read_b128 v[156:159], v175 offset:49152
	ds_read_b128 v[160:163], v175 offset:50176
	ds_read_b128 v[164:167], v175 offset:51200
	ds_read_b128 v[176:179], v175 offset:52224
	ds_read_b128 v[180:183], v175 offset:53248
	ds_read_b128 v[184:187], v175 offset:54272
	ds_read_b128 v[188:191], v175 offset:55296
	ds_read_b128 v[192:195], v175 offset:56320
	global_load_lds_dwordx4 v[168:169], off
	v_lshl_add_u64 v[168:169], v[216:217], 0, s[62:63]
	s_mov_b32 m0, s51
	s_nop 0
	global_load_lds_dwordx4 v[168:169], off
	s_barrier
; #define LAS __attribute__((address_space(3)))
; __device__ __forceinline__ unsigned cvt_pk_bf16(float lo, float hi) { const f32v2_t v = {lo, hi}; const bf16v2_t r = __builtin_convertvector(v, bf16v2_t); return __builtin_bit_cast(unsigned, r); }
; #define PG8_STAGE(bufoff, gbase, voff) do { _Pragma("unroll") for (int _i = 0; _i < 2; ++_i) \
;         __builtin_amdgcn_global_load_lds((const unsigned*)((const char*)(gbase) + (voff)[_i]), (LAS unsigned*)(lds + (bufoff) + ldsw + _i * 8192), 16, 0, 0); } while (0)
; #define PG8_MMA(ai, bj, At, Bt) do { __builtin_amdgcn_s_setprio(1); _Pragma("unroll") for (int m = 0; m < 4; ++m) _Pragma("unroll") for (int n = 0; n < 2; ++n) _Pragma("unroll") for (int k = 0; k < 2; ++k) \
;         acc[ai][bj][m][n] = __builtin_amdgcn_mfma_f32_16x16x32_bf16(Bt[n][k], At[m][k], acc[ai][bj][m][n], 0, 0, 0); __builtin_amdgcn_s_setprio(0); } while (0)
; #define PG8_WAIT_V(n) asm volatile("s_waitcnt vmcnt(" #n ")" ::: "memory")
; template <class Epi, class Sched>
; __device__ __forceinline__ void gemm_phase(LAS unsigned char* lds, const Gemm g, const Sched& S, const Epi& E) {
;     ...
;             PG8_BAR; PG8_WAIT_L(0); PG8_MMA(1, 0, At, B0); PG8_BAR; PG8_SCHED;
;             PG8_STAGE(PG8_SB(1, 1), b3 + hstep, voffB);
;             PG8_WAIT_V(6); PG8_BAR; PG8_MMA(1, 1, At, B1); PG8_BAR;
;         }
;     __device__ __forceinline__ void operator()(const f32x4 (&acc)[2][2][4][2], const Unit& u, int wr, int wc, int fr, int fq) const {
;         const int row0 = u.pm * BM + wr * 64 + fr, col0 = u.pn * BM + wc * 32 + 8 * fq;
;         f32x4 sc[2][2];
; #pragma unroll
;         for (int bj = 0; bj < 2; ++bj)
; #pragma unroll
;             for (int n = 0; n < 2; ++n) sc[bj][n] = *(const LAS f32x4*)(rl + u.idx * 256 + wc * 32 + 8 * fq + bj * HALF + 4 * n);
; #pragma unroll
;         for (int ai = 0; ai < 2; ++ai)
; #pragma unroll
;             for (int m = 0; m < 4; ++m) { const int row = row0 + ai * HALF + m * 16; bf16_t* rowp = O + (size_t)row * ldc + col0;
; #pragma unroll
;                 for (int bj = 0; bj < 2; ++bj) { const f32x4 v0 = acc[ai][bj][m][0] * sc[bj][0], v1 = acc[ai][bj][m][1] * sc[bj][1];
;                     u32x4 w; w.x = cvt_pk_bf16(v0[0], v0[1]); w.y = cvt_pk_bf16(v0[2], v0[3]); w.z = cvt_pk_bf16(v1[0], v1[1]); w.w = cvt_pk_bf16(v1[2], v1[3]);
;                     *(u32x4*)(rowp + bj * HALF) = w; } }
	s_waitcnt lgkmcnt(0)
	s_waitcnt lgkmcnt(0)
	v_mfma_f32_16x16x32_bf16 v[62:65], v[130:133], v[156:159], v[62:65]
	v_mfma_f32_16x16x32_bf16 v[58:61], v[138:141], v[156:159], v[58:61]
	v_mfma_f32_16x16x32_bf16 v[54:57], v[130:133], v[164:167], v[54:57]
	v_mfma_f32_16x16x32_bf16 v[46:49], v[138:141], v[164:167], v[46:49]
	v_mfma_f32_16x16x32_bf16 v[34:37], v[130:133], v[180:183], v[34:37]
	v_mfma_f32_16x16x32_bf16 v[26:29], v[138:141], v[180:183], v[26:29]
	v_mfma_f32_16x16x32_bf16 v[22:25], v[130:133], v[188:191], v[22:25]
	v_mfma_f32_16x16x32_bf16 v[14:17], v[138:141], v[188:191], v[14:17]
	v_mfma_f32_16x16x32_bf16 v[62:65], v[134:137], v[160:163], v[62:65]
	v_mfma_f32_16x16x32_bf16 v[58:61], v[142:145], v[160:163], v[58:61]
	v_mfma_f32_16x16x32_bf16 v[54:57], v[134:137], v[176:179], v[54:57]
	v_mfma_f32_16x16x32_bf16 v[46:49], v[142:145], v[176:179], v[46:49]
	v_mfma_f32_16x16x32_bf16 v[34:37], v[134:137], v[184:187], v[34:37]
	v_mfma_f32_16x16x32_bf16 v[26:29], v[142:145], v[184:187], v[26:29]
	v_mfma_f32_16x16x32_bf16 v[22:25], v[134:137], v[192:195], v[22:25]
	v_mfma_f32_16x16x32_bf16 v[14:17], v[142:145], v[192:195], v[14:17]
	s_barrier
	s_add_u32 s28, s28, 0x40080
	s_addc_u32 s29, s29, 0
	s_add_i32 s33, s38, s27
	v_lshl_add_u64 v[130:131], s[28:29], 0, v[0:1]
	s_mov_b32 m0, s33
	s_nop 0
	global_load_lds_dwordx4 v[130:131], off
	v_lshl_add_u64 v[130:131], s[28:29], 0, v[150:151]
	s_add_i32 m0, s33, 0x2000
	s_nop 0
	global_load_lds_dwordx4 v[130:131], off
	s_waitcnt vmcnt(6)
	s_barrier
	v_mfma_f32_16x16x32_bf16 v[50:53], v[196:199], v[156:159], v[50:53]
	v_mfma_f32_16x16x32_bf16 v[42:45], v[204:207], v[156:159], v[42:45]
	v_mfma_f32_16x16x32_bf16 v[38:41], v[196:199], v[164:167], v[38:41]
	v_mfma_f32_16x16x32_bf16 v[30:33], v[204:207], v[164:167], v[30:33]
	v_mfma_f32_16x16x32_bf16 v[18:21], v[196:199], v[180:183], v[18:21]
	v_mfma_f32_16x16x32_bf16 v[10:13], v[204:207], v[180:183], v[10:13]
	v_mfma_f32_16x16x32_bf16 v[6:9], v[196:199], v[188:191], v[6:9]
	v_mfma_f32_16x16x32_bf16 v[2:5], v[204:207], v[188:191], v[2:5]
	v_mfma_f32_16x16x32_bf16 v[50:53], v[200:203], v[160:163], v[50:53]
	v_mfma_f32_16x16x32_bf16 v[42:45], v[208:211], v[160:163], v[42:45]
	v_mfma_f32_16x16x32_bf16 v[38:41], v[200:203], v[176:179], v[38:41]
	v_mfma_f32_16x16x32_bf16 v[30:33], v[208:211], v[176:179], v[30:33]
	v_mfma_f32_16x16x32_bf16 v[18:21], v[200:203], v[184:187], v[18:21]
	v_mfma_f32_16x16x32_bf16 v[10:13], v[208:211], v[184:187], v[10:13]
	v_mfma_f32_16x16x32_bf16 v[6:9], v[200:203], v[192:195], v[6:9]
	v_mfma_f32_16x16x32_bf16 v[2:5], v[208:211], v[192:195], v[2:5]
	s_add_i32 s47, s47, 2
	s_add_u32 vcc_lo, vcc_lo, 0x100
	s_addc_u32 vcc_hi, vcc_hi, 0
	s_add_u32 s89, s89, 0x100
	s_addc_u32 s17, s17, 0
	s_cmp_gt_u32 s47, 13
	s_barrier
	s_cbranch_scc0 .LBB0_286
	s_lshl_b32 s16, s94, 8
	v_add_u32_e32 v156, s16, v170
	s_cmp_lg_u32 s10, 0
	v_lshl_or_b32 v164, s84, 8, v174
	v_or_b32_e32 v162, 16, v156
	v_or_b32_e32 v160, 32, v156
	v_or_b32_e32 v158, 48, v156
	s_cbranch_scc0 .LBB0_289
	v_lshl_add_u32 v134, s11, 10, v172
	ds_read_b128 v[142:145], v134
	ds_read_b128 v[138:141], v134 offset:16
	ds_read_b128 v[130:133], v134 offset:512
	ds_read_b128 v[134:137], v134 offset:528
	v_ashrrev_i32_e32 v157, 31, v156
	v_ashrrev_i32_e32 v165, 31, v164
	v_lshlrev_b64 v[166:167], 15, v[156:157]
	v_lshl_add_u64 v[166:167], s[42:43], 0, v[166:167]
	v_lshlrev_b64 v[168:169], 1, v[164:165]
	s_waitcnt lgkmcnt(0)
	v_pk_mul_f32 v[178:179], v[128:129], v[144:145]
	v_pk_mul_f32 v[176:177], v[126:127], v[142:143]
	v_pk_mul_f32 v[180:181], v[124:125], v[140:141]
	v_pk_mul_f32 v[182:183], v[122:123], v[138:139]
	v_lshl_add_u64 v[166:167], v[166:167], 0, v[168:169]
	v_cvt_pk_bf16_f32 v176, v176, v177
	v_cvt_pk_bf16_f32 v177, v178, v179
	v_cvt_pk_bf16_f32 v178, v182, v183
	v_cvt_pk_bf16_f32 v179, v180, v181
	global_store_dwordx4 v[166:167], v[176:179], off
	v_pk_mul_f32 v[180:181], v[108:109], v[136:137]
	v_pk_mul_f32 v[182:183], v[106:107], v[134:135]
	v_pk_mul_f32 v[178:179], v[116:117], v[132:133]
	v_pk_mul_f32 v[176:177], v[114:115], v[130:131]
	v_ashrrev_i32_e32 v163, 31, v162
	v_cvt_pk_bf16_f32 v176, v176, v177
	v_cvt_pk_bf16_f32 v177, v178, v179
	v_cvt_pk_bf16_f32 v178, v182, v183
	v_cvt_pk_bf16_f32 v179, v180, v181
	global_store_dwordx4 v[166:167], v[176:179], off offset:256
	v_pk_mul_f32 v[182:183], v[112:113], v[140:141]
	v_pk_mul_f32 v[184:185], v[110:111], v[138:139]
	v_lshlrev_b64 v[176:177], 15, v[162:163]
	v_lshl_add_u64 v[176:177], s[42:43], 0, v[176:177]
	v_lshl_add_u64 v[180:181], v[176:177], 0, v[168:169]
	v_pk_mul_f32 v[178:179], v[120:121], v[144:145]
	v_pk_mul_f32 v[176:177], v[118:119], v[142:143]
	v_ashrrev_i32_e32 v161, 31, v160
	v_cvt_pk_bf16_f32 v176, v176, v177
	v_cvt_pk_bf16_f32 v177, v178, v179
	v_cvt_pk_bf16_f32 v178, v184, v185
	v_cvt_pk_bf16_f32 v179, v182, v183
	global_store_dwordx4 v[180:181], v[176:179], off
	v_pk_mul_f32 v[182:183], v[92:93], v[136:137]
	v_pk_mul_f32 v[184:185], v[90:91], v[134:135]
	v_pk_mul_f32 v[178:179], v[100:101], v[132:133]
	v_pk_mul_f32 v[176:177], v[98:99], v[130:131]
	v_ashrrev_i32_e32 v159, 31, v158
	v_cvt_pk_bf16_f32 v176, v176, v177
	v_cvt_pk_bf16_f32 v177, v178, v179
	v_cvt_pk_bf16_f32 v178, v184, v185
	v_cvt_pk_bf16_f32 v179, v182, v183
	global_store_dwordx4 v[180:181], v[176:179], off offset:256
	v_pk_mul_f32 v[182:183], v[96:97], v[140:141]
; #define LAS __attribute__((address_space(3)))
; __device__ __forceinline__ unsigned cvt_pk_bf16(float lo, float hi) { const f32v2_t v = {lo, hi}; const bf16v2_t r = __builtin_convertvector(v, bf16v2_t); return __builtin_bit_cast(unsigned, r); }
;     __device__ __forceinline__ void operator()(const f32x4 (&acc)[2][2][4][2], const Unit& u, int wr, int wc, int fr, int fq) const { if (u.kind == 0) e0(acc, u, wr, wc, fr, fq); else e1(acc, u, wr, wc, fr, fq); }
;     __device__ __forceinline__ void operator()(const f32x4 (&acc)[2][2][4][2], const Unit& u, int wr, int wc, int fr, int fq) const {
;         const int row0 = u.pm * BM + wr * 64 + fr, col0 = u.pn * BM + wc * 32 + 8 * fq;
;         f32x4 sc[2][2];
; #pragma unroll
;         for (int bj = 0; bj < 2; ++bj)
; #pragma unroll
;             for (int n = 0; n < 2; ++n) sc[bj][n] = *(const LAS f32x4*)(rl + u.idx * 256 + wc * 32 + 8 * fq + bj * HALF + 4 * n);
; #pragma unroll
;         for (int ai = 0; ai < 2; ++ai)
; #pragma unroll
;             for (int m = 0; m < 4; ++m) { const int row = row0 + ai * HALF + m * 16; bf16_t* rowp = O + (size_t)row * ldc + col0;
; #pragma unroll
;                 for (int bj = 0; bj < 2; ++bj) { const f32x4 v0 = acc[ai][bj][m][0] * sc[bj][0], v1 = acc[ai][bj][m][1] * sc[bj][1];
;                     u32x4 w; w.x = cvt_pk_bf16(v0[0], v0[1]); w.y = cvt_pk_bf16(v0[2], v0[3]); w.z = cvt_pk_bf16(v1[0], v1[1]); w.w = cvt_pk_bf16(v1[2], v1[3]);
;                     *(u32x4*)(rowp + bj * HALF) = w; } }
	v_pk_mul_f32 v[184:185], v[94:95], v[138:139]
	v_lshlrev_b64 v[176:177], 15, v[160:161]
	v_lshl_add_u64 v[176:177], s[42:43], 0, v[176:177]
	v_lshl_add_u64 v[180:181], v[176:177], 0, v[168:169]
	v_pk_mul_f32 v[178:179], v[104:105], v[144:145]
	v_pk_mul_f32 v[176:177], v[102:103], v[142:143]
	s_mov_b32 s10, 0x400000
	v_cvt_pk_bf16_f32 v176, v176, v177
	v_cvt_pk_bf16_f32 v177, v178, v179
	v_cvt_pk_bf16_f32 v178, v184, v185
	v_cvt_pk_bf16_f32 v179, v182, v183
	global_store_dwordx4 v[180:181], v[176:179], off
	v_pk_mul_f32 v[182:183], v[76:77], v[136:137]
	v_pk_mul_f32 v[184:185], v[74:75], v[134:135]
	v_pk_mul_f32 v[178:179], v[84:85], v[132:133]
	v_pk_mul_f32 v[176:177], v[82:83], v[130:131]
	s_mov_b64 s[16:17], 0x400000
	v_cvt_pk_bf16_f32 v176, v176, v177
	v_cvt_pk_bf16_f32 v177, v178, v179
	v_cvt_pk_bf16_f32 v178, v184, v185
	v_cvt_pk_bf16_f32 v179, v182, v183
	global_store_dwordx4 v[180:181], v[176:179], off offset:256
	v_pk_mul_f32 v[180:181], v[80:81], v[140:141]
	v_pk_mul_f32 v[182:183], v[78:79], v[138:139]
	v_lshlrev_b64 v[176:177], 15, v[158:159]
	v_lshl_add_u64 v[176:177], s[42:43], 0, v[176:177]
	v_lshl_add_u64 v[168:169], v[176:177], 0, v[168:169]
	v_pk_mul_f32 v[178:179], v[88:89], v[144:145]
	v_pk_mul_f32 v[176:177], v[86:87], v[142:143]
	s_nop 0
	v_cvt_pk_bf16_f32 v176, v176, v177
	v_cvt_pk_bf16_f32 v177, v178, v179
	v_cvt_pk_bf16_f32 v178, v182, v183
	v_cvt_pk_bf16_f32 v179, v180, v181
	global_store_dwordx4 v[168:169], v[176:179], off
	v_pk_mul_f32 v[180:181], v[68:69], v[136:137]
	v_pk_mul_f32 v[182:183], v[66:67], v[134:135]
	v_pk_mul_f32 v[178:179], v[72:73], v[132:133]
	v_pk_mul_f32 v[176:177], v[70:71], v[130:131]
	s_nop 0
	v_cvt_pk_bf16_f32 v176, v176, v177
	v_cvt_pk_bf16_f32 v177, v178, v179
	v_cvt_pk_bf16_f32 v178, v182, v183
	v_cvt_pk_bf16_f32 v179, v180, v181
	global_store_dwordx4 v[168:169], v[176:179], off offset:256
	v_pk_mul_f32 v[180:181], v[60:61], v[140:141]
	v_pk_mul_f32 v[182:183], v[58:59], v[138:139]
	v_pk_mul_f32 v[178:179], v[64:65], v[144:145]
	v_pk_mul_f32 v[176:177], v[62:63], v[142:143]
	v_lshl_add_u64 v[168:169], v[166:167], 0, s[16:17]
	v_cvt_pk_bf16_f32 v176, v176, v177
	v_cvt_pk_bf16_f32 v177, v178, v179
	v_cvt_pk_bf16_f32 v179, v180, v181
	v_add_co_u32_e32 v180, vcc, s10, v166
	v_cvt_pk_bf16_f32 v178, v182, v183
	s_nop 0
	v_addc_co_u32_e32 v181, vcc, 0, v167, vcc
	global_store_dwordx4 v[180:181], v[176:179], off
	v_pk_mul_f32 v[180:181], v[44:45], v[136:137]
	v_pk_mul_f32 v[182:183], v[42:43], v[134:135]
	v_pk_mul_f32 v[178:179], v[52:53], v[132:133]
	v_pk_mul_f32 v[176:177], v[50:51], v[130:131]
	s_mov_b32 s10, 0x480000
	v_cvt_pk_bf16_f32 v176, v176, v177
	v_cvt_pk_bf16_f32 v177, v178, v179
	v_cvt_pk_bf16_f32 v178, v182, v183
	v_cvt_pk_bf16_f32 v179, v180, v181
	global_store_dwordx4 v[168:169], v[176:179], off offset:256
	v_pk_mul_f32 v[180:181], v[48:49], v[140:141]
	v_pk_mul_f32 v[182:183], v[46:47], v[138:139]
	v_pk_mul_f32 v[178:179], v[56:57], v[144:145]
	v_pk_mul_f32 v[176:177], v[54:55], v[142:143]
	s_mov_b64 s[16:17], 0x480000
	v_cvt_pk_bf16_f32 v176, v176, v177
	v_cvt_pk_bf16_f32 v177, v178, v179
	v_cvt_pk_bf16_f32 v179, v180, v181
	v_add_co_u32_e32 v180, vcc, s10, v166
	v_cvt_pk_bf16_f32 v178, v182, v183
	s_nop 0
	v_addc_co_u32_e32 v181, vcc, 0, v167, vcc
	global_store_dwordx4 v[180:181], v[176:179], off
	v_pk_mul_f32 v[180:181], v[32:33], v[136:137]
	v_pk_mul_f32 v[182:183], v[30:31], v[134:135]
	v_pk_mul_f32 v[178:179], v[40:41], v[132:133]
	v_pk_mul_f32 v[176:177], v[38:39], v[130:131]
	v_lshl_add_u64 v[168:169], v[166:167], 0, s[16:17]
	v_cvt_pk_bf16_f32 v176, v176, v177
	v_cvt_pk_bf16_f32 v177, v178, v179
	v_cvt_pk_bf16_f32 v178, v182, v183
	v_cvt_pk_bf16_f32 v179, v180, v181
	global_store_dwordx4 v[168:169], v[176:179], off offset:256
	v_pk_mul_f32 v[180:181], v[28:29], v[140:141]
	s_mov_b32 s10, 0x500000
	v_pk_mul_f32 v[178:179], v[36:37], v[144:145]
	v_pk_mul_f32 v[176:177], v[34:35], v[142:143]
	v_pk_mul_f32 v[182:183], v[26:27], v[138:139]
	v_cvt_pk_bf16_f32 v176, v176, v177
	v_cvt_pk_bf16_f32 v177, v178, v179
	v_cvt_pk_bf16_f32 v179, v180, v181
	v_add_co_u32_e32 v180, vcc, s10, v166
	v_cvt_pk_bf16_f32 v178, v182, v183
	s_nop 0
	v_addc_co_u32_e32 v181, vcc, 0, v167, vcc
	s_mov_b64 s[16:17], 0x500000
	global_store_dwordx4 v[180:181], v[176:179], off
	v_pk_mul_f32 v[180:181], v[12:13], v[136:137]
	v_pk_mul_f32 v[182:183], v[10:11], v[134:135]
	v_pk_mul_f32 v[178:179], v[20:21], v[132:133]
	v_pk_mul_f32 v[176:177], v[18:19], v[130:131]
	v_lshl_add_u64 v[168:169], v[166:167], 0, s[16:17]
	v_cvt_pk_bf16_f32 v176, v176, v177
	v_cvt_pk_bf16_f32 v177, v178, v179
	v_cvt_pk_bf16_f32 v178, v182, v183
	v_cvt_pk_bf16_f32 v179, v180, v181
	v_pk_mul_f32 v[142:143], v[22:23], v[142:143]
	s_mov_b32 s10, 0x580000
	global_store_dwordx4 v[168:169], v[176:179], off offset:256
	v_pk_mul_f32 v[144:145], v[24:25], v[144:145]
	s_mov_b64 s[16:17], 0x580000
	v_pk_mul_f32 v[176:177], v[16:17], v[140:141]
	v_pk_mul_f32 v[140:141], v[14:15], v[138:139]
	v_cvt_pk_bf16_f32 v138, v142, v143
	v_add_co_u32_e32 v142, vcc, s10, v166
	v_cvt_pk_bf16_f32 v139, v144, v145
	v_cvt_pk_bf16_f32 v140, v140, v141
	v_cvt_pk_bf16_f32 v141, v176, v177
	v_addc_co_u32_e32 v143, vcc, 0, v167, vcc
	v_lshl_add_u64 v[168:169], v[166:167], 0, s[16:17]
	global_store_dwordx4 v[142:143], v[138:141], off
	s_cbranch_execnz .LBB0_279
	s_branch .LBB0_278

; #define PG8_STAGE(bufoff, gbase, voff) do { _Pragma("unroll") for (int _i = 0; _i < 2; ++_i) \
;         __builtin_amdgcn_global_load_lds((const unsigned*)((const char*)(gbase) + (voff)[_i]), (LAS unsigned*)(lds + (bufoff) + ldsw + _i * 8192), 16, 0, 0); } while (0)
; #define PG8_LDA(dst, b, h) do { _Pragma("unroll") for (int m = 0; m < 4; ++m) _Pragma("unroll") for (int k = 0; k < 2; ++k) dst[m][k] = *(const LAS bf16x8*)(lds + PG8_SA(b, h) + aoff + m * 2048 + k * 1024); } while (0)
; #define PG8_LDB(dst, b, h) do { _Pragma("unroll") for (int n = 0; n < 2; ++n) _Pragma("unroll") for (int k = 0; k < 2; ++k) dst[n][k] = *(const LAS bf16x8*)(lds + PG8_SB(b, h) + boff + n * 2048 + k * 1024); } while (0)
; #define PG8_MMA(ai, bj, At, Bt) do { __builtin_amdgcn_s_setprio(1); _Pragma("unroll") for (int m = 0; m < 4; ++m) _Pragma("unroll") for (int n = 0; n < 2; ++n) _Pragma("unroll") for (int k = 0; k < 2; ++k) \
;         acc[ai][bj][m][n] = __builtin_amdgcn_mfma_f32_16x16x32_bf16(Bt[n][k], At[m][k], acc[ai][bj][m][n], 0, 0, 0); __builtin_amdgcn_s_setprio(0); } while (0)
; #define PG8_WAIT_V(n) asm volatile("s_waitcnt vmcnt(" #n ")" ::: "memory")
; #define PG8_WAIT_L(n) asm volatile("s_waitcnt lgkmcnt(" #n ")" ::: "memory")
; #define PG8_BAR __builtin_amdgcn_s_barrier()
; #define PG8_SCHED __builtin_amdgcn_sched_barrier(0)
; template <class Epi, class Sched>
; __device__ __forceinline__ void gemm_phase(LAS unsigned char* lds, const Gemm g, const Sched& S, const Epi& E) {
;     ...
;             PG8_LDB(B0, 0, 0); PG8_SCHED; PG8_LDA(At, 0, 0); PG8_STAGE(PG8_SA(1, 1), a1 + hstep, voffA);
;             PG8_WAIT_L(8); PG8_BAR; PG8_WAIT_L(0); PG8_MMA(0, 0, At, B0); PG8_BAR; PG8_SCHED;
;             PG8_LDB(B1, 0, 1); PG8_STAGE(PG8_SB(0, 0), b2, voffB);
;             PG8_BAR; PG8_WAIT_L(0); PG8_MMA(0, 1, At, B1); PG8_BAR;
;             PG8_LDA(At, 0, 1); PG8_STAGE(PG8_SA(0, 0), a2, voffA);
;             PG8_BAR; PG8_WAIT_L(0); PG8_MMA(1, 0, At, B0); PG8_BAR; PG8_SCHED;
;             PG8_STAGE(PG8_SB(0, 1), b2 + hstep, voffB);
;             PG8_WAIT_V(6); PG8_BAR; PG8_MMA(1, 1, At, B1); PG8_BAR;
.LBB0_560:
	s_add_u32 s10, s42, vcc_lo
	s_addc_u32 s11, s43, vcc_hi
	s_add_u32 s10, s10, 0x100
	s_addc_u32 s11, s11, 0
	s_add_u32 s16, s73, vcc_lo
	s_addc_u32 s17, s27, vcc_hi
	s_cmpk_eq_i32 vcc_lo, 0xb00
	s_cselect_b32 s45, s7, s11
	s_cselect_b32 s44, s6, s10
	s_cselect_b32 s29, s1, s17
	s_cselect_b32 s28, s0, s16
	s_add_i32 s10, 0, 0x10000
	v_add_u32_e32 v0, s10, v173
	ds_read_b128 v[132:135], v0
	ds_read_b128 v[176:179], v0 offset:1024
	ds_read_b128 v[180:183], v0 offset:2048
	ds_read_b128 v[184:187], v0 offset:3072
	v_lshl_add_u64 v[2:3], v[168:169], 0, vcc
	s_add_i32 m0, s83, 0xc000
	ds_read_b128 v[188:191], v175
	ds_read_b128 v[192:195], v175 offset:1024
	ds_read_b128 v[196:199], v175 offset:2048
	ds_read_b128 v[200:203], v175 offset:3072
	ds_read_b128 v[204:207], v175 offset:4096
	ds_read_b128 v[208:211], v175 offset:5120
	ds_read_b128 v[212:215], v175 offset:6144
	ds_read_b128 v[216:219], v175 offset:7168
	global_load_lds_dwordx4 v[2:3], off
	v_lshl_add_u64 v[2:3], v[170:171], 0, vcc
	s_add_i32 m0, s83, 0xe000
	s_nop 0
	global_load_lds_dwordx4 v[2:3], off
	s_waitcnt lgkmcnt(8)
	s_barrier
	s_waitcnt lgkmcnt(0)
	s_waitcnt lgkmcnt(0)
	v_mfma_f32_16x16x32_bf16 v[128:131], v[132:135], v[188:191], v[128:131]
	v_mfma_f32_16x16x32_bf16 v[124:127], v[180:183], v[188:191], v[124:127]
	v_mfma_f32_16x16x32_bf16 v[112:115], v[132:135], v[196:199], v[112:115]
	v_mfma_f32_16x16x32_bf16 v[108:111], v[180:183], v[196:199], v[108:111]
	v_mfma_f32_16x16x32_bf16 v[96:99], v[132:135], v[204:207], v[96:99]
	v_mfma_f32_16x16x32_bf16 v[92:95], v[180:183], v[204:207], v[92:95]
	v_mfma_f32_16x16x32_bf16 v[80:83], v[132:135], v[212:215], v[80:83]
	v_mfma_f32_16x16x32_bf16 v[76:79], v[180:183], v[212:215], v[76:79]
	v_mfma_f32_16x16x32_bf16 v[128:131], v[176:179], v[192:195], v[128:131]
	v_mfma_f32_16x16x32_bf16 v[124:127], v[184:187], v[192:195], v[124:127]
	v_mfma_f32_16x16x32_bf16 v[112:115], v[176:179], v[200:203], v[112:115]
	v_mfma_f32_16x16x32_bf16 v[108:111], v[184:187], v[200:203], v[108:111]
	v_mfma_f32_16x16x32_bf16 v[96:99], v[176:179], v[208:211], v[96:99]
	v_mfma_f32_16x16x32_bf16 v[92:95], v[184:187], v[208:211], v[92:95]
	v_mfma_f32_16x16x32_bf16 v[80:83], v[176:179], v[216:219], v[80:83]
	v_mfma_f32_16x16x32_bf16 v[76:79], v[184:187], v[216:219], v[76:79]
	s_barrier
	s_add_i32 s16, 0, 0x14000
	s_add_i32 s10, s10, s82
	v_add_u32_e32 v0, s16, v173
	v_lshl_add_u64 v[136:137], s[28:29], 0, v[142:143]
	s_mov_b32 m0, s10
	ds_read_b128 v[220:223], v0
	ds_read_b128 v[224:227], v0 offset:1024
	ds_read_b128 v[228:231], v0 offset:2048
	ds_read_b128 v[248:251], v0 offset:3072
	global_load_lds_dwordx4 v[136:137], off
	v_lshl_add_u64 v[236:237], s[28:29], 0, v[138:139]
	s_add_i32 m0, s10, 0x2000
	s_nop 0
	global_load_lds_dwordx4 v[236:237], off
	s_barrier
	s_waitcnt lgkmcnt(0)
	s_waitcnt lgkmcnt(0)
	v_mfma_f32_16x16x32_bf16 v[120:123], v[220:223], v[188:191], v[120:123]
	v_mfma_f32_16x16x32_bf16 v[116:119], v[228:231], v[188:191], v[116:119]
	v_mfma_f32_16x16x32_bf16 v[104:107], v[220:223], v[196:199], v[104:107]
	v_mfma_f32_16x16x32_bf16 v[100:103], v[228:231], v[196:199], v[100:103]
	v_mfma_f32_16x16x32_bf16 v[88:91], v[220:223], v[204:207], v[88:91]
	v_mfma_f32_16x16x32_bf16 v[84:87], v[228:231], v[204:207], v[84:87]
	v_mfma_f32_16x16x32_bf16 v[72:75], v[220:223], v[212:215], v[72:75]
	v_mfma_f32_16x16x32_bf16 v[68:71], v[228:231], v[212:215], v[68:71]
	v_mfma_f32_16x16x32_bf16 v[120:123], v[224:227], v[192:195], v[120:123]
	v_mfma_f32_16x16x32_bf16 v[116:119], v[248:251], v[192:195], v[116:119]
	v_mfma_f32_16x16x32_bf16 v[104:107], v[224:227], v[200:203], v[104:107]
	v_mfma_f32_16x16x32_bf16 v[100:103], v[248:251], v[200:203], v[100:103]
	v_mfma_f32_16x16x32_bf16 v[88:91], v[224:227], v[208:211], v[88:91]
	v_mfma_f32_16x16x32_bf16 v[84:87], v[248:251], v[208:211], v[84:87]
	v_mfma_f32_16x16x32_bf16 v[72:75], v[224:227], v[216:219], v[72:75]
	v_mfma_f32_16x16x32_bf16 v[68:71], v[248:251], v[216:219], v[68:71]
	s_mov_b32 m0, s83
	v_lshl_add_u64 v[238:239], s[44:45], 0, v[144:145]
	s_barrier
	ds_read_b128 v[188:191], v175 offset:16384
	ds_read_b128 v[192:195], v175 offset:17408
	ds_read_b128 v[196:199], v175 offset:18432
	ds_read_b128 v[200:203], v175 offset:19456
	ds_read_b128 v[204:207], v175 offset:20480
	ds_read_b128 v[208:211], v175 offset:21504
	ds_read_b128 v[212:215], v175 offset:22528
	ds_read_b128 v[216:219], v175 offset:23552
	global_load_lds_dwordx4 v[238:239], off
	v_lshl_add_u64 v[252:253], s[44:45], 0, v[140:141]
	s_mov_b32 m0, s84
	s_nop 0
	global_load_lds_dwordx4 v[252:253], off
	s_barrier
	s_waitcnt lgkmcnt(0)
	s_waitcnt lgkmcnt(0)
	v_mfma_f32_16x16x32_bf16 v[64:67], v[132:135], v[188:191], v[64:67]
	v_mfma_f32_16x16x32_bf16 v[60:63], v[180:183], v[188:191], v[60:63]
	v_mfma_f32_16x16x32_bf16 v[48:51], v[132:135], v[196:199], v[48:51]
	v_mfma_f32_16x16x32_bf16 v[44:47], v[180:183], v[196:199], v[44:47]
	v_mfma_f32_16x16x32_bf16 v[32:35], v[132:135], v[204:207], v[32:35]
	v_mfma_f32_16x16x32_bf16 v[28:31], v[180:183], v[204:207], v[28:31]
	v_mfma_f32_16x16x32_bf16 v[16:19], v[132:135], v[212:215], v[16:19]
	v_mfma_f32_16x16x32_bf16 v[12:15], v[180:183], v[212:215], v[12:15]
	v_mfma_f32_16x16x32_bf16 v[64:67], v[176:179], v[192:195], v[64:67]
	v_mfma_f32_16x16x32_bf16 v[60:63], v[184:187], v[192:195], v[60:63]
	v_mfma_f32_16x16x32_bf16 v[48:51], v[176:179], v[200:203], v[48:51]
	v_mfma_f32_16x16x32_bf16 v[44:47], v[184:187], v[200:203], v[44:47]
	v_mfma_f32_16x16x32_bf16 v[32:35], v[176:179], v[208:211], v[32:35]
	v_mfma_f32_16x16x32_bf16 v[28:31], v[184:187], v[208:211], v[28:31]
	v_mfma_f32_16x16x32_bf16 v[16:19], v[176:179], v[216:219], v[16:19]
	v_mfma_f32_16x16x32_bf16 v[12:15], v[184:187], v[216:219], v[12:15]
	s_barrier
; #define PG8_STAGE(bufoff, gbase, voff) do { _Pragma("unroll") for (int _i = 0; _i < 2; ++_i) \
;         __builtin_amdgcn_global_load_lds((const unsigned*)((const char*)(gbase) + (voff)[_i]), (LAS unsigned*)(lds + (bufoff) + ldsw + _i * 8192), 16, 0, 0); } while (0)
; #define PG8_LDA(dst, b, h) do { _Pragma("unroll") for (int m = 0; m < 4; ++m) _Pragma("unroll") for (int k = 0; k < 2; ++k) dst[m][k] = *(const LAS bf16x8*)(lds + PG8_SA(b, h) + aoff + m * 2048 + k * 1024); } while (0)
; #define PG8_LDB(dst, b, h) do { _Pragma("unroll") for (int n = 0; n < 2; ++n) _Pragma("unroll") for (int k = 0; k < 2; ++k) dst[n][k] = *(const LAS bf16x8*)(lds + PG8_SB(b, h) + boff + n * 2048 + k * 1024); } while (0)
; #define PG8_MMA(ai, bj, At, Bt) do { __builtin_amdgcn_s_setprio(1); _Pragma("unroll") for (int m = 0; m < 4; ++m) _Pragma("unroll") for (int n = 0; n < 2; ++n) _Pragma("unroll") for (int k = 0; k < 2; ++k) \
;         acc[ai][bj][m][n] = __builtin_amdgcn_mfma_f32_16x16x32_bf16(Bt[n][k], At[m][k], acc[ai][bj][m][n], 0, 0, 0); __builtin_amdgcn_s_setprio(0); } while (0)
; #define PG8_WAIT_V(n) asm volatile("s_waitcnt vmcnt(" #n ")" ::: "memory")
; #define PG8_WAIT_L(n) asm volatile("s_waitcnt lgkmcnt(" #n ")" ::: "memory")
; #define PG8_BAR __builtin_amdgcn_s_barrier()
; #define PG8_SCHED __builtin_amdgcn_sched_barrier(0)
; template <class Epi, class Sched>
; __device__ __forceinline__ void gemm_phase(LAS unsigned char* lds, const Gemm g, const Sched& S, const Epi& E) {
;     ...
;             PG8_STAGE(PG8_SB(0, 1), b2 + hstep, voffB);
;             PG8_WAIT_V(6); PG8_BAR; PG8_MMA(1, 1, At, B1); PG8_BAR;
;             PG8_LDB(B0, 1, 0); PG8_SCHED; PG8_LDA(At, 1, 0); PG8_STAGE(PG8_SA(0, 1), a2 + hstep, voffA);
;             PG8_WAIT_L(8); PG8_BAR; PG8_WAIT_L(0); PG8_MMA(0, 0, At, B0); PG8_BAR; PG8_SCHED;
;             PG8_LDB(B1, 1, 1); PG8_STAGE(PG8_SB(1, 0), b3, voffB);
;             PG8_BAR; PG8_WAIT_L(0); PG8_MMA(0, 1, At, B1); PG8_BAR;
;             PG8_LDA(At, 1, 1); PG8_STAGE(PG8_SA(1, 0), a3, voffA);
;             PG8_BAR; PG8_WAIT_L(0); PG8_MMA(1, 0, At, B0); PG8_BAR; PG8_SCHED;
	s_add_u32 s10, s28, 0x60000
	s_addc_u32 s11, s29, 0
	s_add_i32 s16, s16, s82
	v_lshl_add_u64 v[2:3], s[10:11], 0, v[142:143]
	s_mov_b32 m0, s16
	s_nop 0
	global_load_lds_dwordx4 v[2:3], off
	v_lshl_add_u64 v[2:3], s[10:11], 0, v[138:139]
	s_add_i32 m0, s16, 0x2000
	s_nop 0
	global_load_lds_dwordx4 v[2:3], off
	s_waitcnt vmcnt(6)
	s_barrier
	v_mfma_f32_16x16x32_bf16 v[56:59], v[220:223], v[188:191], v[56:59]
	v_mfma_f32_16x16x32_bf16 v[52:55], v[228:231], v[188:191], v[52:55]
	v_mfma_f32_16x16x32_bf16 v[40:43], v[220:223], v[196:199], v[40:43]
	v_mfma_f32_16x16x32_bf16 v[36:39], v[228:231], v[196:199], v[36:39]
	v_mfma_f32_16x16x32_bf16 v[24:27], v[220:223], v[204:207], v[24:27]
	v_mfma_f32_16x16x32_bf16 v[20:23], v[228:231], v[204:207], v[20:23]
	v_mfma_f32_16x16x32_bf16 v[8:11], v[220:223], v[212:215], v[8:11]
	v_mfma_f32_16x16x32_bf16 v[2:5], v[228:231], v[212:215], v[4:7]
	v_mfma_f32_16x16x32_bf16 v[56:59], v[224:227], v[192:195], v[56:59]
	v_mfma_f32_16x16x32_bf16 v[52:55], v[248:251], v[192:195], v[52:55]
	v_mfma_f32_16x16x32_bf16 v[40:43], v[224:227], v[200:203], v[40:43]
	v_mfma_f32_16x16x32_bf16 v[36:39], v[248:251], v[200:203], v[36:39]
	v_mfma_f32_16x16x32_bf16 v[24:27], v[224:227], v[208:211], v[24:27]
	v_mfma_f32_16x16x32_bf16 v[20:23], v[248:251], v[208:211], v[20:23]
	v_mfma_f32_16x16x32_bf16 v[8:11], v[224:227], v[216:219], v[8:11]
	v_mfma_f32_16x16x32_bf16 v[2:5], v[248:251], v[216:219], v[2:5]
	s_add_i32 s16, 0, 0x18000
	v_add_u32_e32 v0, s16, v173
	s_barrier
	ds_read_b128 v[132:135], v0
	ds_read_b128 v[176:179], v0 offset:1024
	ds_read_b128 v[180:183], v0 offset:2048
	ds_read_b128 v[184:187], v0 offset:3072
	s_add_u32 s10, s44, 0x60000
	s_addc_u32 s11, s45, 0
	s_mov_b32 m0, s85
	v_lshl_add_u64 v[6:7], s[10:11], 0, v[144:145]
	ds_read_b128 v[188:191], v175 offset:32768
	ds_read_b128 v[192:195], v175 offset:33792
	ds_read_b128 v[196:199], v175 offset:34816
	ds_read_b128 v[200:203], v175 offset:35840
	ds_read_b128 v[204:207], v175 offset:36864
	ds_read_b128 v[208:211], v175 offset:37888
	ds_read_b128 v[212:215], v175 offset:38912
	ds_read_b128 v[216:219], v175 offset:39936
	global_load_lds_dwordx4 v[6:7], off
	v_lshl_add_u64 v[6:7], s[10:11], 0, v[140:141]
	s_mov_b32 m0, s86
	s_nop 0
	global_load_lds_dwordx4 v[6:7], off
	s_waitcnt lgkmcnt(8)
	s_barrier
	s_waitcnt lgkmcnt(0)
	s_waitcnt lgkmcnt(0)
	v_mfma_f32_16x16x32_bf16 v[128:131], v[132:135], v[188:191], v[128:131]
	v_mfma_f32_16x16x32_bf16 v[124:127], v[180:183], v[188:191], v[124:127]
	v_mfma_f32_16x16x32_bf16 v[112:115], v[132:135], v[196:199], v[112:115]
	v_mfma_f32_16x16x32_bf16 v[108:111], v[180:183], v[196:199], v[108:111]
	v_mfma_f32_16x16x32_bf16 v[96:99], v[132:135], v[204:207], v[96:99]
	v_mfma_f32_16x16x32_bf16 v[92:95], v[180:183], v[204:207], v[92:95]
	v_mfma_f32_16x16x32_bf16 v[80:83], v[132:135], v[212:215], v[80:83]
	v_mfma_f32_16x16x32_bf16 v[76:79], v[180:183], v[212:215], v[76:79]
	v_mfma_f32_16x16x32_bf16 v[128:131], v[176:179], v[192:195], v[128:131]
	v_mfma_f32_16x16x32_bf16 v[124:127], v[184:187], v[192:195], v[124:127]
	v_mfma_f32_16x16x32_bf16 v[112:115], v[176:179], v[200:203], v[112:115]
	v_mfma_f32_16x16x32_bf16 v[108:111], v[184:187], v[200:203], v[108:111]
	v_mfma_f32_16x16x32_bf16 v[96:99], v[176:179], v[208:211], v[96:99]
	v_mfma_f32_16x16x32_bf16 v[92:95], v[184:187], v[208:211], v[92:95]
	v_mfma_f32_16x16x32_bf16 v[80:83], v[176:179], v[216:219], v[80:83]
	v_mfma_f32_16x16x32_bf16 v[76:79], v[184:187], v[216:219], v[76:79]
	s_barrier
	s_add_i32 s17, 0, 0x1c000
	s_add_i32 s10, s16, s82
	v_add_u32_e32 v0, s17, v173
	v_lshl_add_u64 v[6:7], v[136:137], 0, s[62:63]
	s_mov_b32 m0, s10
	ds_read_b128 v[220:223], v0
	ds_read_b128 v[224:227], v0 offset:1024
	ds_read_b128 v[228:231], v0 offset:2048
	ds_read_b128 v[248:251], v0 offset:3072
	global_load_lds_dwordx4 v[6:7], off
	v_lshl_add_u64 v[6:7], v[236:237], 0, s[62:63]
	s_add_i32 m0, s10, 0x2000
	s_nop 0
	global_load_lds_dwordx4 v[6:7], off
	s_barrier
; #define PG8_STAGE(bufoff, gbase, voff) do { _Pragma("unroll") for (int _i = 0; _i < 2; ++_i) \
;         __builtin_amdgcn_global_load_lds((const unsigned*)((const char*)(gbase) + (voff)[_i]), (LAS unsigned*)(lds + (bufoff) + ldsw + _i * 8192), 16, 0, 0); } while (0)
; #define PG8_LDA(dst, b, h) do { _Pragma("unroll") for (int m = 0; m < 4; ++m) _Pragma("unroll") for (int k = 0; k < 2; ++k) dst[m][k] = *(const LAS bf16x8*)(lds + PG8_SA(b, h) + aoff + m * 2048 + k * 1024); } while (0)
; #define PG8_MMA(ai, bj, At, Bt) do { __builtin_amdgcn_s_setprio(1); _Pragma("unroll") for (int m = 0; m < 4; ++m) _Pragma("unroll") for (int n = 0; n < 2; ++n) _Pragma("unroll") for (int k = 0; k < 2; ++k) \
;         acc[ai][bj][m][n] = __builtin_amdgcn_mfma_f32_16x16x32_bf16(Bt[n][k], At[m][k], acc[ai][bj][m][n], 0, 0, 0); __builtin_amdgcn_s_setprio(0); } while (0)
; #define PG8_WAIT_V(n) asm volatile("s_waitcnt vmcnt(" #n ")" ::: "memory")
; #define PG8_WAIT_L(n) asm volatile("s_waitcnt lgkmcnt(" #n ")" ::: "memory")
; #define PG8_BAR __builtin_amdgcn_s_barrier()
; #define PG8_SCHED __builtin_amdgcn_sched_barrier(0)
; template <class Epi, class Sched>
; __device__ __forceinline__ void gemm_phase(LAS unsigned char* lds, const Gemm g, const Sched& S, const Epi& E) {
;     ...
;             PG8_LDA(At, 1, 1); PG8_STAGE(PG8_SA(1, 0), a3, voffA);
;             PG8_BAR; PG8_WAIT_L(0); PG8_MMA(1, 0, At, B0); PG8_BAR; PG8_SCHED;
;             PG8_STAGE(PG8_SB(1, 1), b3 + hstep, voffB);
;             PG8_WAIT_V(6); PG8_BAR; PG8_MMA(1, 1, At, B1); PG8_BAR;
;         }
	s_waitcnt lgkmcnt(0)
	s_waitcnt lgkmcnt(0)
	v_mfma_f32_16x16x32_bf16 v[120:123], v[220:223], v[188:191], v[120:123]
	v_mfma_f32_16x16x32_bf16 v[116:119], v[228:231], v[188:191], v[116:119]
	v_mfma_f32_16x16x32_bf16 v[104:107], v[220:223], v[196:199], v[104:107]
	v_mfma_f32_16x16x32_bf16 v[100:103], v[228:231], v[196:199], v[100:103]
	v_mfma_f32_16x16x32_bf16 v[88:91], v[220:223], v[204:207], v[88:91]
	v_mfma_f32_16x16x32_bf16 v[84:87], v[228:231], v[204:207], v[84:87]
	v_mfma_f32_16x16x32_bf16 v[72:75], v[220:223], v[212:215], v[72:75]
	v_mfma_f32_16x16x32_bf16 v[68:71], v[228:231], v[212:215], v[68:71]
	v_mfma_f32_16x16x32_bf16 v[120:123], v[224:227], v[192:195], v[120:123]
	v_mfma_f32_16x16x32_bf16 v[116:119], v[248:251], v[192:195], v[116:119]
	v_mfma_f32_16x16x32_bf16 v[104:107], v[224:227], v[200:203], v[104:107]
	v_mfma_f32_16x16x32_bf16 v[100:103], v[248:251], v[200:203], v[100:103]
	v_mfma_f32_16x16x32_bf16 v[88:91], v[224:227], v[208:211], v[88:91]
	v_mfma_f32_16x16x32_bf16 v[84:87], v[248:251], v[208:211], v[84:87]
	v_mfma_f32_16x16x32_bf16 v[72:75], v[224:227], v[216:219], v[72:75]
	v_mfma_f32_16x16x32_bf16 v[68:71], v[248:251], v[216:219], v[68:71]
	s_mov_b32 m0, s87
	v_lshl_add_u64 v[6:7], v[238:239], 0, s[62:63]
	s_barrier
	ds_read_b128 v[188:191], v175 offset:49152
	ds_read_b128 v[192:195], v175 offset:50176
	ds_read_b128 v[196:199], v175 offset:51200
	ds_read_b128 v[200:203], v175 offset:52224
	ds_read_b128 v[204:207], v175 offset:53248
	ds_read_b128 v[208:211], v175 offset:54272
	ds_read_b128 v[212:215], v175 offset:55296
	ds_read_b128 v[216:219], v175 offset:56320
	global_load_lds_dwordx4 v[6:7], off
	v_lshl_add_u64 v[6:7], v[252:253], 0, s[62:63]
	s_mov_b32 m0, s88
	s_nop 0
	global_load_lds_dwordx4 v[6:7], off
	s_barrier
	s_waitcnt lgkmcnt(0)
	s_waitcnt lgkmcnt(0)
	v_mfma_f32_16x16x32_bf16 v[64:67], v[132:135], v[188:191], v[64:67]
	v_mfma_f32_16x16x32_bf16 v[60:63], v[180:183], v[188:191], v[60:63]
	v_mfma_f32_16x16x32_bf16 v[48:51], v[132:135], v[196:199], v[48:51]
	v_mfma_f32_16x16x32_bf16 v[44:47], v[180:183], v[196:199], v[44:47]
	v_mfma_f32_16x16x32_bf16 v[32:35], v[132:135], v[204:207], v[32:35]
	v_mfma_f32_16x16x32_bf16 v[28:31], v[180:183], v[204:207], v[28:31]
	v_mfma_f32_16x16x32_bf16 v[16:19], v[132:135], v[212:215], v[16:19]
	v_mfma_f32_16x16x32_bf16 v[12:15], v[180:183], v[212:215], v[12:15]
	v_mfma_f32_16x16x32_bf16 v[64:67], v[176:179], v[192:195], v[64:67]
	v_mfma_f32_16x16x32_bf16 v[60:63], v[184:187], v[192:195], v[60:63]
	v_mfma_f32_16x16x32_bf16 v[48:51], v[176:179], v[200:203], v[48:51]
	v_mfma_f32_16x16x32_bf16 v[44:47], v[184:187], v[200:203], v[44:47]
	v_mfma_f32_16x16x32_bf16 v[32:35], v[176:179], v[208:211], v[32:35]
	v_mfma_f32_16x16x32_bf16 v[28:31], v[184:187], v[208:211], v[28:31]
	v_mfma_f32_16x16x32_bf16 v[16:19], v[176:179], v[216:219], v[16:19]
	v_mfma_f32_16x16x32_bf16 v[12:15], v[184:187], v[216:219], v[12:15]
	s_barrier
	s_add_u32 s10, s28, 0x60080
	s_addc_u32 s11, s29, 0
	s_add_i32 s16, s17, s82
	v_lshl_add_u64 v[6:7], s[10:11], 0, v[142:143]
	s_mov_b32 m0, s16
	s_nop 0
	global_load_lds_dwordx4 v[6:7], off
	v_lshl_add_u64 v[6:7], s[10:11], 0, v[138:139]
	s_add_i32 m0, s16, 0x2000
	s_nop 0
	global_load_lds_dwordx4 v[6:7], off
	s_waitcnt vmcnt(6)
	s_barrier
	v_mfma_f32_16x16x32_bf16 v[56:59], v[220:223], v[188:191], v[56:59]
	v_mfma_f32_16x16x32_bf16 v[52:55], v[228:231], v[188:191], v[52:55]
	v_mfma_f32_16x16x32_bf16 v[40:43], v[220:223], v[196:199], v[40:43]
	v_mfma_f32_16x16x32_bf16 v[36:39], v[228:231], v[196:199], v[36:39]
	v_mfma_f32_16x16x32_bf16 v[24:27], v[220:223], v[204:207], v[24:27]
	v_mfma_f32_16x16x32_bf16 v[20:23], v[228:231], v[204:207], v[20:23]
	v_mfma_f32_16x16x32_bf16 v[6:9], v[220:223], v[212:215], v[8:11]
	v_mfma_f32_16x16x32_bf16 v[2:5], v[228:231], v[212:215], v[2:5]
	v_mfma_f32_16x16x32_bf16 v[56:59], v[224:227], v[192:195], v[56:59]
	v_mfma_f32_16x16x32_bf16 v[52:55], v[248:251], v[192:195], v[52:55]
	v_mfma_f32_16x16x32_bf16 v[40:43], v[224:227], v[200:203], v[40:43]
	v_mfma_f32_16x16x32_bf16 v[36:39], v[248:251], v[200:203], v[36:39]
	v_mfma_f32_16x16x32_bf16 v[24:27], v[224:227], v[208:211], v[24:27]
	v_mfma_f32_16x16x32_bf16 v[20:23], v[248:251], v[208:211], v[20:23]
	v_mfma_f32_16x16x32_bf16 v[8:11], v[224:227], v[216:219], v[6:9]
	v_mfma_f32_16x16x32_bf16 v[4:7], v[248:251], v[216:219], v[2:5]
	s_add_i32 s25, s25, 2
	s_add_u32 vcc_lo, vcc_lo, 0x100
	s_addc_u32 vcc_hi, vcc_hi, 0
	s_cmp_gt_u32 s25, 21
	s_barrier
	s_cbranch_scc1 .LBB0_548

; #define PG8_STAGE(bufoff, gbase, voff) do { _Pragma("unroll") for (int _i = 0; _i < 2; ++_i) \
;         __builtin_amdgcn_global_load_lds((const unsigned*)((const char*)(gbase) + (voff)[_i]), (LAS unsigned*)(lds + (bufoff) + ldsw + _i * 8192), 16, 0, 0); } while (0)
; #define PG8_LDA(dst, b, h) do { _Pragma("unroll") for (int m = 0; m < 4; ++m) _Pragma("unroll") for (int k = 0; k < 2; ++k) dst[m][k] = *(const LAS bf16x8*)(lds + PG8_SA(b, h) + aoff + m * 2048 + k * 1024); } while (0)
; #define PG8_LDB(dst, b, h) do { _Pragma("unroll") for (int n = 0; n < 2; ++n) _Pragma("unroll") for (int k = 0; k < 2; ++k) dst[n][k] = *(const LAS bf16x8*)(lds + PG8_SB(b, h) + boff + n * 2048 + k * 1024); } while (0)
; #define PG8_MMA(ai, bj, At, Bt) do { __builtin_amdgcn_s_setprio(1); _Pragma("unroll") for (int m = 0; m < 4; ++m) _Pragma("unroll") for (int n = 0; n < 2; ++n) _Pragma("unroll") for (int k = 0; k < 2; ++k) \
;         acc[ai][bj][m][n] = __builtin_amdgcn_mfma_f32_16x16x32_bf16(Bt[n][k], At[m][k], acc[ai][bj][m][n], 0, 0, 0); __builtin_amdgcn_s_setprio(0); } while (0)
; #define PG8_WAIT_V(n) asm volatile("s_waitcnt vmcnt(" #n ")" ::: "memory")
; #define PG8_WAIT_L(n) asm volatile("s_waitcnt lgkmcnt(" #n ")" ::: "memory")
; #define PG8_BAR __builtin_amdgcn_s_barrier()
; #define PG8_SCHED __builtin_amdgcn_sched_barrier(0)
; template <class Epi, class Sched>
; __device__ __forceinline__ void gemm_phase(LAS unsigned char* lds, const Gemm g, const Sched& S, const Epi& E) {
;     ...
;             PG8_LDB(B0, 0, 0); PG8_SCHED; PG8_LDA(At, 0, 0); PG8_STAGE(PG8_SA(1, 1), a1 + hstep, voffA);
;             PG8_WAIT_L(8); PG8_BAR; PG8_WAIT_L(0); PG8_MMA(0, 0, At, B0); PG8_BAR; PG8_SCHED;
;             PG8_LDB(B1, 0, 1); PG8_STAGE(PG8_SB(0, 0), b2, voffB);
;             PG8_BAR; PG8_WAIT_L(0); PG8_MMA(0, 1, At, B1); PG8_BAR;
;             PG8_LDA(At, 0, 1); PG8_STAGE(PG8_SA(0, 0), a2, voffA);
;             PG8_BAR; PG8_WAIT_L(0); PG8_MMA(1, 0, At, B0); PG8_BAR; PG8_SCHED;
;             PG8_STAGE(PG8_SB(0, 1), b2 + hstep, voffB);
;             PG8_WAIT_V(6); PG8_BAR; PG8_MMA(1, 1, At, B1); PG8_BAR;
.LBB0_631:
	s_add_u32 s38, s44, 0xfffc0080
	s_addc_u32 s39, s45, -1
	s_add_i32 s47, 0, 0x10000
	v_add_u32_e32 v144, s47, v147
	ds_read_b128 v[140:143], v144
	ds_read_b128 v[152:155], v144 offset:1024
	ds_read_b128 v[156:159], v144 offset:2048
	ds_read_b128 v[160:163], v144 offset:3072
	s_cmp_eq_u32 s17, 12
	s_cselect_b32 s79, s10, s39
	s_cselect_b32 s78, s11, s38
	s_cselect_b32 s69, s16, s51
	s_cselect_b32 s68, s29, s34
	v_lshl_add_u64 v[144:145], s[44:45], 0, v[136:137]
	s_add_i32 m0, s1, 0xc000
	ds_read_b128 v[164:167], v151
	ds_read_b128 v[168:171], v151 offset:1024
	ds_read_b128 v[172:175], v151 offset:2048
	ds_read_b128 v[176:179], v151 offset:3072
	ds_read_b128 v[180:183], v151 offset:4096
	ds_read_b128 v[184:187], v151 offset:5120
	ds_read_b128 v[188:191], v151 offset:6144
	ds_read_b128 v[192:195], v151 offset:7168
	global_load_lds_dwordx4 v[144:145], off
	v_lshl_add_u64 v[144:145], s[44:45], 0, v[138:139]
	s_add_i32 m0, s1, 0xe000
	s_nop 0
	global_load_lds_dwordx4 v[144:145], off
	s_waitcnt lgkmcnt(8)
	s_barrier
	s_waitcnt lgkmcnt(0)
	s_waitcnt lgkmcnt(0)
	v_mfma_f32_16x16x32_bf16 v[126:129], v[140:143], v[164:167], v[126:129]
	v_mfma_f32_16x16x32_bf16 v[122:125], v[156:159], v[164:167], v[122:125]
	v_mfma_f32_16x16x32_bf16 v[110:113], v[140:143], v[172:175], v[110:113]
	v_mfma_f32_16x16x32_bf16 v[106:109], v[156:159], v[172:175], v[106:109]
	v_mfma_f32_16x16x32_bf16 v[94:97], v[140:143], v[180:183], v[94:97]
	v_mfma_f32_16x16x32_bf16 v[90:93], v[156:159], v[180:183], v[90:93]
	v_mfma_f32_16x16x32_bf16 v[78:81], v[140:143], v[188:191], v[78:81]
	v_mfma_f32_16x16x32_bf16 v[74:77], v[156:159], v[188:191], v[74:77]
	v_mfma_f32_16x16x32_bf16 v[126:129], v[152:155], v[168:171], v[126:129]
	v_mfma_f32_16x16x32_bf16 v[122:125], v[160:163], v[168:171], v[122:125]
	v_mfma_f32_16x16x32_bf16 v[110:113], v[152:155], v[176:179], v[110:113]
	v_mfma_f32_16x16x32_bf16 v[106:109], v[160:163], v[176:179], v[106:109]
	v_mfma_f32_16x16x32_bf16 v[94:97], v[152:155], v[184:187], v[94:97]
	v_mfma_f32_16x16x32_bf16 v[90:93], v[160:163], v[184:187], v[90:93]
	v_mfma_f32_16x16x32_bf16 v[78:81], v[152:155], v[192:195], v[78:81]
	v_mfma_f32_16x16x32_bf16 v[74:77], v[160:163], v[192:195], v[74:77]
	s_barrier
	s_add_i32 s38, 0, 0x14000
	v_add_u32_e32 v144, s38, v147
	s_add_i32 s39, s47, s46
	ds_read_b128 v[196:199], v144
	ds_read_b128 v[200:203], v144 offset:1024
	ds_read_b128 v[204:207], v144 offset:2048
	ds_read_b128 v[208:211], v144 offset:3072
	v_lshl_add_u64 v[144:145], s[68:69], 0, v[0:1]
	s_mov_b32 m0, s39
	v_lshl_add_u64 v[212:213], s[68:69], 0, v[134:135]
	global_load_lds_dwordx4 v[144:145], off
	s_add_i32 m0, s39, 0x2000
	s_nop 0
	global_load_lds_dwordx4 v[212:213], off
	s_barrier
	s_waitcnt lgkmcnt(0)
	s_waitcnt lgkmcnt(0)
	v_mfma_f32_16x16x32_bf16 v[118:121], v[196:199], v[164:167], v[118:121]
	v_mfma_f32_16x16x32_bf16 v[114:117], v[204:207], v[164:167], v[114:117]
	v_mfma_f32_16x16x32_bf16 v[102:105], v[196:199], v[172:175], v[102:105]
	v_mfma_f32_16x16x32_bf16 v[98:101], v[204:207], v[172:175], v[98:101]
	v_mfma_f32_16x16x32_bf16 v[86:89], v[196:199], v[180:183], v[86:89]
	v_mfma_f32_16x16x32_bf16 v[82:85], v[204:207], v[180:183], v[82:85]
	v_mfma_f32_16x16x32_bf16 v[70:73], v[196:199], v[188:191], v[70:73]
	v_mfma_f32_16x16x32_bf16 v[66:69], v[204:207], v[188:191], v[66:69]
	v_mfma_f32_16x16x32_bf16 v[118:121], v[200:203], v[168:171], v[118:121]
	v_mfma_f32_16x16x32_bf16 v[114:117], v[208:211], v[168:171], v[114:117]
	v_mfma_f32_16x16x32_bf16 v[102:105], v[200:203], v[176:179], v[102:105]
	v_mfma_f32_16x16x32_bf16 v[98:101], v[208:211], v[176:179], v[98:101]
	v_mfma_f32_16x16x32_bf16 v[86:89], v[200:203], v[184:187], v[86:89]
	v_mfma_f32_16x16x32_bf16 v[82:85], v[208:211], v[184:187], v[82:85]
	v_mfma_f32_16x16x32_bf16 v[70:73], v[200:203], v[192:195], v[70:73]
	v_mfma_f32_16x16x32_bf16 v[66:69], v[208:211], v[192:195], v[66:69]
	s_mov_b32 m0, s1
	v_lshl_add_u64 v[214:215], s[78:79], 0, v[130:131]
	s_barrier
	ds_read_b128 v[164:167], v151 offset:16384
	ds_read_b128 v[168:171], v151 offset:17408
	ds_read_b128 v[172:175], v151 offset:18432
	ds_read_b128 v[176:179], v151 offset:19456
	ds_read_b128 v[180:183], v151 offset:20480
	ds_read_b128 v[184:187], v151 offset:21504
	ds_read_b128 v[188:191], v151 offset:22528
	ds_read_b128 v[192:195], v151 offset:23552
	global_load_lds_dwordx4 v[214:215], off
	v_lshl_add_u64 v[216:217], s[78:79], 0, v[132:133]
	s_mov_b32 m0, s72
	s_nop 0
	global_load_lds_dwordx4 v[216:217], off
	s_barrier
	s_waitcnt lgkmcnt(0)
	s_waitcnt lgkmcnt(0)
	v_mfma_f32_16x16x32_bf16 v[62:65], v[140:143], v[164:167], v[62:65]
	v_mfma_f32_16x16x32_bf16 v[58:61], v[156:159], v[164:167], v[58:61]
	v_mfma_f32_16x16x32_bf16 v[46:49], v[140:143], v[172:175], v[46:49]
	v_mfma_f32_16x16x32_bf16 v[42:45], v[156:159], v[172:175], v[42:45]
	v_mfma_f32_16x16x32_bf16 v[30:33], v[140:143], v[180:183], v[30:33]
	v_mfma_f32_16x16x32_bf16 v[26:29], v[156:159], v[180:183], v[26:29]
	v_mfma_f32_16x16x32_bf16 v[14:17], v[140:143], v[188:191], v[14:17]
	v_mfma_f32_16x16x32_bf16 v[10:13], v[156:159], v[188:191], v[10:13]
	v_mfma_f32_16x16x32_bf16 v[62:65], v[152:155], v[168:171], v[62:65]
	v_mfma_f32_16x16x32_bf16 v[58:61], v[160:163], v[168:171], v[58:61]
	v_mfma_f32_16x16x32_bf16 v[46:49], v[152:155], v[176:179], v[46:49]
	v_mfma_f32_16x16x32_bf16 v[42:45], v[160:163], v[176:179], v[42:45]
	v_mfma_f32_16x16x32_bf16 v[30:33], v[152:155], v[184:187], v[30:33]
	v_mfma_f32_16x16x32_bf16 v[26:29], v[160:163], v[184:187], v[26:29]
	v_mfma_f32_16x16x32_bf16 v[14:17], v[152:155], v[192:195], v[14:17]
	v_mfma_f32_16x16x32_bf16 v[10:13], v[160:163], v[192:195], v[10:13]
	s_barrier
; #define PG8_STAGE(bufoff, gbase, voff) do { _Pragma("unroll") for (int _i = 0; _i < 2; ++_i) \
;         __builtin_amdgcn_global_load_lds((const unsigned*)((const char*)(gbase) + (voff)[_i]), (LAS unsigned*)(lds + (bufoff) + ldsw + _i * 8192), 16, 0, 0); } while (0)
; #define PG8_LDA(dst, b, h) do { _Pragma("unroll") for (int m = 0; m < 4; ++m) _Pragma("unroll") for (int k = 0; k < 2; ++k) dst[m][k] = *(const LAS bf16x8*)(lds + PG8_SA(b, h) + aoff + m * 2048 + k * 1024); } while (0)
; #define PG8_LDB(dst, b, h) do { _Pragma("unroll") for (int n = 0; n < 2; ++n) _Pragma("unroll") for (int k = 0; k < 2; ++k) dst[n][k] = *(const LAS bf16x8*)(lds + PG8_SB(b, h) + boff + n * 2048 + k * 1024); } while (0)
; #define PG8_MMA(ai, bj, At, Bt) do { __builtin_amdgcn_s_setprio(1); _Pragma("unroll") for (int m = 0; m < 4; ++m) _Pragma("unroll") for (int n = 0; n < 2; ++n) _Pragma("unroll") for (int k = 0; k < 2; ++k) \
;         acc[ai][bj][m][n] = __builtin_amdgcn_mfma_f32_16x16x32_bf16(Bt[n][k], At[m][k], acc[ai][bj][m][n], 0, 0, 0); __builtin_amdgcn_s_setprio(0); } while (0)
; #define PG8_WAIT_V(n) asm volatile("s_waitcnt vmcnt(" #n ")" ::: "memory")
; #define PG8_WAIT_L(n) asm volatile("s_waitcnt lgkmcnt(" #n ")" ::: "memory")
; #define PG8_BAR __builtin_amdgcn_s_barrier()
; #define PG8_SCHED __builtin_amdgcn_sched_barrier(0)
; template <class Epi, class Sched>
; __device__ __forceinline__ void gemm_phase(LAS unsigned char* lds, const Gemm g, const Sched& S, const Epi& E) {
;     ...
;             PG8_STAGE(PG8_SB(0, 1), b2 + hstep, voffB);
;             PG8_WAIT_V(6); PG8_BAR; PG8_MMA(1, 1, At, B1); PG8_BAR;
;             PG8_LDB(B0, 1, 0); PG8_SCHED; PG8_LDA(At, 1, 0); PG8_STAGE(PG8_SA(0, 1), a2 + hstep, voffA);
;             PG8_WAIT_L(8); PG8_BAR; PG8_WAIT_L(0); PG8_MMA(0, 0, At, B0); PG8_BAR; PG8_SCHED;
;             PG8_LDB(B1, 1, 1); PG8_STAGE(PG8_SB(1, 0), b3, voffB);
;             PG8_BAR; PG8_WAIT_L(0); PG8_MMA(0, 1, At, B1); PG8_BAR;
;             PG8_LDA(At, 1, 1); PG8_STAGE(PG8_SA(1, 0), a3, voffA);
	s_add_u32 s82, s68, 0x40000
	s_addc_u32 s83, s69, 0
	s_add_i32 s38, s38, s46
	v_lshl_add_u64 v[140:141], s[82:83], 0, v[0:1]
	s_mov_b32 m0, s38
	s_nop 0
	global_load_lds_dwordx4 v[140:141], off
	v_lshl_add_u64 v[140:141], s[82:83], 0, v[134:135]
	s_add_i32 m0, s38, 0x2000
	s_nop 0
	global_load_lds_dwordx4 v[140:141], off
	s_waitcnt vmcnt(6)
	s_barrier
	v_mfma_f32_16x16x32_bf16 v[54:57], v[196:199], v[164:167], v[54:57]
	v_mfma_f32_16x16x32_bf16 v[50:53], v[204:207], v[164:167], v[50:53]
	v_mfma_f32_16x16x32_bf16 v[38:41], v[196:199], v[172:175], v[38:41]
	v_mfma_f32_16x16x32_bf16 v[34:37], v[204:207], v[172:175], v[34:37]
	v_mfma_f32_16x16x32_bf16 v[22:25], v[196:199], v[180:183], v[22:25]
	v_mfma_f32_16x16x32_bf16 v[18:21], v[204:207], v[180:183], v[18:21]
	v_mfma_f32_16x16x32_bf16 v[6:9], v[196:199], v[188:191], v[6:9]
	v_mfma_f32_16x16x32_bf16 v[2:5], v[204:207], v[188:191], v[2:5]
	v_mfma_f32_16x16x32_bf16 v[54:57], v[200:203], v[168:171], v[54:57]
	v_mfma_f32_16x16x32_bf16 v[50:53], v[208:211], v[168:171], v[50:53]
	v_mfma_f32_16x16x32_bf16 v[38:41], v[200:203], v[176:179], v[38:41]
	v_mfma_f32_16x16x32_bf16 v[34:37], v[208:211], v[176:179], v[34:37]
	v_mfma_f32_16x16x32_bf16 v[22:25], v[200:203], v[184:187], v[22:25]
	v_mfma_f32_16x16x32_bf16 v[18:21], v[208:211], v[184:187], v[18:21]
	v_mfma_f32_16x16x32_bf16 v[6:9], v[200:203], v[192:195], v[6:9]
	v_mfma_f32_16x16x32_bf16 v[2:5], v[208:211], v[192:195], v[2:5]
	s_add_i32 s38, 0, 0x18000
	v_add_u32_e32 v160, s38, v147
	s_barrier
	ds_read_b128 v[140:143], v160
	ds_read_b128 v[152:155], v160 offset:1024
	ds_read_b128 v[156:159], v160 offset:2048
	ds_read_b128 v[160:163], v160 offset:3072
	s_add_u32 s78, s78, 0x40000
	s_addc_u32 s79, s79, 0
	s_mov_b32 m0, s73
	v_lshl_add_u64 v[196:197], s[78:79], 0, v[130:131]
	ds_read_b128 v[164:167], v151 offset:32768
	ds_read_b128 v[168:171], v151 offset:33792
	ds_read_b128 v[172:175], v151 offset:34816
	ds_read_b128 v[176:179], v151 offset:35840
	ds_read_b128 v[180:183], v151 offset:36864
	ds_read_b128 v[184:187], v151 offset:37888
	ds_read_b128 v[188:191], v151 offset:38912
	ds_read_b128 v[192:195], v151 offset:39936
	global_load_lds_dwordx4 v[196:197], off
	v_lshl_add_u64 v[196:197], s[78:79], 0, v[132:133]
	s_mov_b32 m0, s76
	s_nop 0
	global_load_lds_dwordx4 v[196:197], off
	s_waitcnt lgkmcnt(8)
	s_barrier
	s_waitcnt lgkmcnt(0)
	s_waitcnt lgkmcnt(0)
	v_mfma_f32_16x16x32_bf16 v[126:129], v[140:143], v[164:167], v[126:129]
	v_mfma_f32_16x16x32_bf16 v[122:125], v[156:159], v[164:167], v[122:125]
	v_mfma_f32_16x16x32_bf16 v[110:113], v[140:143], v[172:175], v[110:113]
	v_mfma_f32_16x16x32_bf16 v[106:109], v[156:159], v[172:175], v[106:109]
	v_mfma_f32_16x16x32_bf16 v[94:97], v[140:143], v[180:183], v[94:97]
	v_mfma_f32_16x16x32_bf16 v[90:93], v[156:159], v[180:183], v[90:93]
	v_mfma_f32_16x16x32_bf16 v[78:81], v[140:143], v[188:191], v[78:81]
	v_mfma_f32_16x16x32_bf16 v[74:77], v[156:159], v[188:191], v[74:77]
	v_mfma_f32_16x16x32_bf16 v[126:129], v[152:155], v[168:171], v[126:129]
	v_mfma_f32_16x16x32_bf16 v[122:125], v[160:163], v[168:171], v[122:125]
	v_mfma_f32_16x16x32_bf16 v[110:113], v[152:155], v[176:179], v[110:113]
	v_mfma_f32_16x16x32_bf16 v[106:109], v[160:163], v[176:179], v[106:109]
	v_mfma_f32_16x16x32_bf16 v[94:97], v[152:155], v[184:187], v[94:97]
	v_mfma_f32_16x16x32_bf16 v[90:93], v[160:163], v[184:187], v[90:93]
	v_mfma_f32_16x16x32_bf16 v[78:81], v[152:155], v[192:195], v[78:81]
	v_mfma_f32_16x16x32_bf16 v[74:77], v[160:163], v[192:195], v[74:77]
	s_barrier
	s_add_i32 s39, 0, 0x1c000
	s_add_i32 s38, s38, s46
	v_add_u32_e32 v208, s39, v147
	v_lshl_add_u64 v[144:145], v[144:145], 0, s[62:63]
	s_mov_b32 m0, s38
	ds_read_b128 v[196:199], v208
	ds_read_b128 v[200:203], v208 offset:1024
	ds_read_b128 v[204:207], v208 offset:2048
	ds_read_b128 v[208:211], v208 offset:3072
	global_load_lds_dwordx4 v[144:145], off
	v_lshl_add_u64 v[144:145], v[212:213], 0, s[62:63]
	s_add_i32 m0, s38, 0x2000
	s_nop 0
	global_load_lds_dwordx4 v[144:145], off
	s_barrier
	s_waitcnt lgkmcnt(0)
	s_waitcnt lgkmcnt(0)
	v_mfma_f32_16x16x32_bf16 v[118:121], v[196:199], v[164:167], v[118:121]
	v_mfma_f32_16x16x32_bf16 v[114:117], v[204:207], v[164:167], v[114:117]
	v_mfma_f32_16x16x32_bf16 v[102:105], v[196:199], v[172:175], v[102:105]
	v_mfma_f32_16x16x32_bf16 v[98:101], v[204:207], v[172:175], v[98:101]
	v_mfma_f32_16x16x32_bf16 v[86:89], v[196:199], v[180:183], v[86:89]
	v_mfma_f32_16x16x32_bf16 v[82:85], v[204:207], v[180:183], v[82:85]
	v_mfma_f32_16x16x32_bf16 v[70:73], v[196:199], v[188:191], v[70:73]
	v_mfma_f32_16x16x32_bf16 v[66:69], v[204:207], v[188:191], v[66:69]
	v_mfma_f32_16x16x32_bf16 v[118:121], v[200:203], v[168:171], v[118:121]
	v_mfma_f32_16x16x32_bf16 v[114:117], v[208:211], v[168:171], v[114:117]
	v_mfma_f32_16x16x32_bf16 v[102:105], v[200:203], v[176:179], v[102:105]
	v_mfma_f32_16x16x32_bf16 v[98:101], v[208:211], v[176:179], v[98:101]
	v_mfma_f32_16x16x32_bf16 v[86:89], v[200:203], v[184:187], v[86:89]
	v_mfma_f32_16x16x32_bf16 v[82:85], v[208:211], v[184:187], v[82:85]
	v_mfma_f32_16x16x32_bf16 v[70:73], v[200:203], v[192:195], v[70:73]
	v_mfma_f32_16x16x32_bf16 v[66:69], v[208:211], v[192:195], v[66:69]
	s_mov_b32 m0, s84
	v_lshl_add_u64 v[144:145], v[214:215], 0, s[62:63]
	s_barrier
	ds_read_b128 v[164:167], v151 offset:49152
	ds_read_b128 v[168:171], v151 offset:50176
	ds_read_b128 v[172:175], v151 offset:51200
	ds_read_b128 v[176:179], v151 offset:52224
	ds_read_b128 v[180:183], v151 offset:53248
	ds_read_b128 v[184:187], v151 offset:54272
	ds_read_b128 v[188:191], v151 offset:55296
	ds_read_b128 v[192:195], v151 offset:56320
	global_load_lds_dwordx4 v[144:145], off
	v_lshl_add_u64 v[144:145], v[216:217], 0, s[62:63]
	s_mov_b32 m0, s85
	s_nop 0
	global_load_lds_dwordx4 v[144:145], off
	s_barrier
; #define PG8_STAGE(bufoff, gbase, voff) do { _Pragma("unroll") for (int _i = 0; _i < 2; ++_i) \
;         __builtin_amdgcn_global_load_lds((const unsigned*)((const char*)(gbase) + (voff)[_i]), (LAS unsigned*)(lds + (bufoff) + ldsw + _i * 8192), 16, 0, 0); } while (0)
; #define PG8_MMA(ai, bj, At, Bt) do { __builtin_amdgcn_s_setprio(1); _Pragma("unroll") for (int m = 0; m < 4; ++m) _Pragma("unroll") for (int n = 0; n < 2; ++n) _Pragma("unroll") for (int k = 0; k < 2; ++k) \
;         acc[ai][bj][m][n] = __builtin_amdgcn_mfma_f32_16x16x32_bf16(Bt[n][k], At[m][k], acc[ai][bj][m][n], 0, 0, 0); __builtin_amdgcn_s_setprio(0); } while (0)
; #define PG8_WAIT_V(n) asm volatile("s_waitcnt vmcnt(" #n ")" ::: "memory")
; #define PG8_WAIT_L(n) asm volatile("s_waitcnt lgkmcnt(" #n ")" ::: "memory")
; #define PG8_BAR __builtin_amdgcn_s_barrier()
; #define PG8_SCHED __builtin_amdgcn_sched_barrier(0)
; template <class Epi, class Sched>
; __device__ __forceinline__ void gemm_phase(LAS unsigned char* lds, const Gemm g, const Sched& S, const Epi& E) {
;     ...
;             PG8_BAR; PG8_WAIT_L(0); PG8_MMA(1, 0, At, B0); PG8_BAR; PG8_SCHED;
;             PG8_STAGE(PG8_SB(1, 1), b3 + hstep, voffB);
;             PG8_WAIT_V(6); PG8_BAR; PG8_MMA(1, 1, At, B1); PG8_BAR;
;         }
	s_waitcnt lgkmcnt(0)
	s_waitcnt lgkmcnt(0)
	v_mfma_f32_16x16x32_bf16 v[62:65], v[140:143], v[164:167], v[62:65]
	v_mfma_f32_16x16x32_bf16 v[58:61], v[156:159], v[164:167], v[58:61]
	v_mfma_f32_16x16x32_bf16 v[46:49], v[140:143], v[172:175], v[46:49]
	v_mfma_f32_16x16x32_bf16 v[42:45], v[156:159], v[172:175], v[42:45]
	v_mfma_f32_16x16x32_bf16 v[30:33], v[140:143], v[180:183], v[30:33]
	v_mfma_f32_16x16x32_bf16 v[26:29], v[156:159], v[180:183], v[26:29]
	v_mfma_f32_16x16x32_bf16 v[14:17], v[140:143], v[188:191], v[14:17]
	v_mfma_f32_16x16x32_bf16 v[10:13], v[156:159], v[188:191], v[10:13]
	v_mfma_f32_16x16x32_bf16 v[62:65], v[152:155], v[168:171], v[62:65]
	v_mfma_f32_16x16x32_bf16 v[58:61], v[160:163], v[168:171], v[58:61]
	v_mfma_f32_16x16x32_bf16 v[46:49], v[152:155], v[176:179], v[46:49]
	v_mfma_f32_16x16x32_bf16 v[42:45], v[160:163], v[176:179], v[42:45]
	v_mfma_f32_16x16x32_bf16 v[30:33], v[152:155], v[184:187], v[30:33]
	v_mfma_f32_16x16x32_bf16 v[26:29], v[160:163], v[184:187], v[26:29]
	v_mfma_f32_16x16x32_bf16 v[14:17], v[152:155], v[192:195], v[14:17]
	v_mfma_f32_16x16x32_bf16 v[10:13], v[160:163], v[192:195], v[10:13]
	s_barrier
	s_add_u32 s68, s68, 0x40080
	s_addc_u32 s69, s69, 0
	s_add_i32 s38, s39, s46
	v_lshl_add_u64 v[140:141], s[68:69], 0, v[0:1]
	s_mov_b32 m0, s38
	s_nop 0
	global_load_lds_dwordx4 v[140:141], off
	v_lshl_add_u64 v[140:141], s[68:69], 0, v[134:135]
	s_add_i32 m0, s38, 0x2000
	s_nop 0
	global_load_lds_dwordx4 v[140:141], off
	s_waitcnt vmcnt(6)
	s_barrier
	v_mfma_f32_16x16x32_bf16 v[54:57], v[196:199], v[164:167], v[54:57]
	v_mfma_f32_16x16x32_bf16 v[50:53], v[204:207], v[164:167], v[50:53]
	v_mfma_f32_16x16x32_bf16 v[38:41], v[196:199], v[172:175], v[38:41]
	v_mfma_f32_16x16x32_bf16 v[34:37], v[204:207], v[172:175], v[34:37]
	v_mfma_f32_16x16x32_bf16 v[22:25], v[196:199], v[180:183], v[22:25]
	v_mfma_f32_16x16x32_bf16 v[18:21], v[204:207], v[180:183], v[18:21]
	v_mfma_f32_16x16x32_bf16 v[6:9], v[196:199], v[188:191], v[6:9]
	v_mfma_f32_16x16x32_bf16 v[2:5], v[204:207], v[188:191], v[2:5]
	v_mfma_f32_16x16x32_bf16 v[54:57], v[200:203], v[168:171], v[54:57]
	v_mfma_f32_16x16x32_bf16 v[50:53], v[208:211], v[168:171], v[50:53]
	v_mfma_f32_16x16x32_bf16 v[38:41], v[200:203], v[176:179], v[38:41]
	v_mfma_f32_16x16x32_bf16 v[34:37], v[208:211], v[176:179], v[34:37]
	v_mfma_f32_16x16x32_bf16 v[22:25], v[200:203], v[184:187], v[22:25]
	v_mfma_f32_16x16x32_bf16 v[18:21], v[208:211], v[184:187], v[18:21]
	v_mfma_f32_16x16x32_bf16 v[6:9], v[200:203], v[192:195], v[6:9]
	v_mfma_f32_16x16x32_bf16 v[2:5], v[208:211], v[192:195], v[2:5]
	s_add_i32 s17, s17, 2
	s_add_u32 s44, s44, 0x100
	s_addc_u32 s45, s45, 0
	s_add_u32 s34, s34, 0x100
	s_addc_u32 s51, s51, 0
	s_cmp_gt_u32 s17, 13
	s_barrier
	s_cbranch_scc0 .LBB0_631
; __device__ __forceinline__ void unpack8(const u32x4 w, float* f) { f[0] = bf_lo(w.x); f[1] = bf_hi(w.x); f[2] = bf_lo(w.y); f[3] = bf_hi(w.y); f[4] = bf_lo(w.z); f[5] = bf_hi(w.z); f[6] = bf_lo(w.w); f[7] = bf_hi(w.w); }
; __device__ __forceinline__ u32x4 pack8(const float* f) { u32x4 w; w.x = cvt_pk_bf16(f[0], f[1]); w.y = cvt_pk_bf16(f[2], f[3]); w.z = cvt_pk_bf16(f[4], f[5]); w.w = cvt_pk_bf16(f[6], f[7]); return w; }
; __device__ __forceinline__ float shx(float v, int m, int lane) { return __int_as_float(__builtin_amdgcn_ds_bpermute((lane ^ m) << 2, __float_as_int(v))); }
;     __device__ __forceinline__ void operator()(const f32x4 (&acc)[2][2][4][2], const Unit& u, int wr, int wc, int fr, int fq) const { if (u.kind == 0) e0(acc, u, wr, wc, fr, fq); else e1(acc, u, wr, wc, fr, fq); }
;     __device__ __forceinline__ void operator()(const f32x4 (&acc)[2][2][4][2], const Unit& u, int wr, int wc, int fr, int fq) const {
;         const int row0 = u.pm * BM + wr * 64 + fr, col0 = u.pn * BM + wc * 32 + 8 * fq;
; #pragma unroll
;         for (int ai = 0; ai < 2; ++ai)
; #pragma unroll
;             for (int m = 0; m < 4; ++m) { const int row = row0 + ai * HALF + m * 16; float ss = 0.f;
; #pragma unroll
;                 for (int bj = 0; bj < 2; ++bj) { const size_t off = (size_t)row * D + col0 + bj * HALF;
;                     float b[8], r[8]; unpack8(*(const u32x4*)(xb + off), b);
;                     const f32x4 v0 = acc[ai][bj][m][0], v1 = acc[ai][bj][m][1];
; #pragma unroll
;                     for (int j = 0; j < 4; ++j) { b[j] += v0[j]; b[4 + j] += v1[j]; }
;                     const u32x4 w = pack8(b);
;                     *(u32x4*)(xb + off) = w;
;                     unpack8(w, r);
; #pragma unroll
;                     for (int j = 0; j < 8; ++j) ss += r[j] * r[j]; }
;                 { const int ln = fr + 16 * fq; ss += shx(ss, 16, ln); ss += shx(ss, 32, ln); }
;                 if (fq == 0) rowss[(size_t)row * 16 + u.pn * 4 + wc] = ss; }
	v_lshl_add_u32 v142, s28, 8, v146
	v_ashrrev_i32_e32 v143, 31, v142
	v_lshl_or_b32 v140, s0, 8, v148
	v_lshlrev_b64 v[144:145], 11, v[142:143]
	v_ashrrev_i32_e32 v141, 31, v140
	v_lshl_add_u64 v[144:145], s[40:41], 0, v[144:145]
	v_lshl_add_u64 v[144:145], v[140:141], 1, v[144:145]
	global_load_dwordx4 v[158:161], v[144:145], off
	global_load_dwordx4 v[162:165], v[144:145], off offset:256
	s_mov_b32 s100, 0x8000
	s_mov_b32 s101, 0
	v_lshl_add_u64 v[230:231], v[144:145], 0, s[100:101]
	global_load_dwordx4 v[166:169], v[230:231], off
	global_load_dwordx4 v[170:173], v[230:231], off offset:256
	v_lshl_add_u64 v[230:231], v[230:231], 0, s[100:101]
	global_load_dwordx4 v[190:193], v[230:231], off
	global_load_dwordx4 v[194:197], v[230:231], off offset:256
	v_lshl_add_u64 v[230:231], v[230:231], 0, s[100:101]
	global_load_dwordx4 v[198:201], v[230:231], off
	global_load_dwordx4 v[202:205], v[230:231], off offset:256
	s_mov_b32 s100, 0x28000
	v_lshl_add_u64 v[230:231], v[230:231], 0, s[100:101]
	global_load_dwordx4 v[206:209], v[230:231], off
	global_load_dwordx4 v[210:213], v[230:231], off offset:256
	s_mov_b32 s100, 0x8000
	v_lshl_add_u64 v[230:231], v[230:231], 0, s[100:101]
	global_load_dwordx4 v[214:217], v[230:231], off
	global_load_dwordx4 v[218:221], v[230:231], off offset:256
	v_lshl_add_u64 v[230:231], v[230:231], 0, s[100:101]
	global_load_dwordx4 v[222:225], v[230:231], off
	global_load_dwordx4 v[226:229], v[230:231], off offset:256
	v_lshl_add_u64 v[230:231], v[230:231], 0, s[100:101]
	global_load_dwordx4 v[236:239], v[230:231], off
	global_load_dwordx4 v[248:251], v[230:231], off offset:256
	s_waitcnt vmcnt(15)
	v_mov_b64_e32 v[152:153], v[158:159]
	v_mov_b64_e32 v[154:155], v[160:161]
	v_lshlrev_b32_e32 v156, 16, v152
	v_and_b32_e32 v157, 0xffff0000, v152
	v_pk_add_f32 v[126:127], v[126:127], v[156:157]
	v_lshlrev_b32_e32 v156, 16, v154
	v_and_b32_e32 v157, 0xffff0000, v154
	v_pk_add_f32 v[156:157], v[122:123], v[156:157]
	v_lshlrev_b32_e32 v122, 16, v153
	v_and_b32_e32 v123, 0xffff0000, v153
	v_pk_add_f32 v[128:129], v[128:129], v[122:123]
	v_lshlrev_b32_e32 v122, 16, v155
	v_and_b32_e32 v123, 0xffff0000, v155
	v_pk_add_f32 v[152:153], v[124:125], v[122:123]
	v_cvt_pk_bf16_f32 v122, v126, v127
	v_cvt_pk_bf16_f32 v123, v128, v129
	v_cvt_pk_bf16_f32 v124, v156, v157
	v_cvt_pk_bf16_f32 v125, v152, v153
	global_store_dwordx4 v[144:145], v[122:125], off
	v_lshlrev_b32_e32 v126, 16, v122
	v_lshlrev_b32_e32 v127, 16, v123
	v_and_b32_e32 v122, 0xffff0000, v122
	v_mul_f32_e32 v152, v122, v122
	v_fmac_f32_e32 v152, v126, v126
	v_and_b32_e32 v123, 0xffff0000, v123
	v_fmac_f32_e32 v152, v127, v127
	v_lshlrev_b32_e32 v128, 16, v124
	v_fmac_f32_e32 v152, v123, v123
	v_and_b32_e32 v124, 0xffff0000, v124
	v_fmac_f32_e32 v152, v128, v128
	v_lshlrev_b32_e32 v129, 16, v125
	v_fmac_f32_e32 v152, v124, v124
	v_and_b32_e32 v125, 0xffff0000, v125
	v_fmac_f32_e32 v152, v129, v129
	v_fmac_f32_e32 v152, v125, v125
	s_waitcnt vmcnt(14)
	v_mov_b64_e32 v[122:123], v[162:163]
	v_mov_b64_e32 v[124:125], v[164:165]
	v_lshlrev_b32_e32 v126, 16, v122
	v_and_b32_e32 v127, 0xffff0000, v122
	v_pk_add_f32 v[118:119], v[118:119], v[126:127]
	v_lshlrev_b32_e32 v126, 16, v124
	v_and_b32_e32 v127, 0xffff0000, v124
	v_pk_add_f32 v[126:127], v[114:115], v[126:127]
	v_lshlrev_b32_e32 v114, 16, v123
	v_and_b32_e32 v115, 0xffff0000, v123
	v_pk_add_f32 v[120:121], v[120:121], v[114:115]
	v_lshlrev_b32_e32 v114, 16, v125
	v_and_b32_e32 v115, 0xffff0000, v125
	v_pk_add_f32 v[122:123], v[116:117], v[114:115]
	v_cvt_pk_bf16_f32 v114, v118, v119
	v_cvt_pk_bf16_f32 v115, v120, v121
	v_cvt_pk_bf16_f32 v116, v126, v127
	v_cvt_pk_bf16_f32 v117, v122, v123
	v_lshlrev_b32_e32 v118, 16, v114
	global_store_dwordx4 v[144:145], v[114:117], off offset:256
	v_fmac_f32_e32 v152, v118, v118
	v_lshlrev_b32_e32 v119, 16, v115
	v_and_b32_e32 v114, 0xffff0000, v114
	v_fmac_f32_e32 v152, v114, v114
	v_and_b32_e32 v115, 0xffff0000, v115
	v_fmac_f32_e32 v152, v119, v119
	v_lshlrev_b32_e32 v120, 16, v116
	v_fmac_f32_e32 v152, v115, v115
	v_and_b32_e32 v116, 0xffff0000, v116
	v_fmac_f32_e32 v152, v120, v120
	v_lshlrev_b32_e32 v121, 16, v117
	v_fmac_f32_e32 v152, v116, v116
	v_and_b32_e32 v117, 0xffff0000, v117
	v_fmac_f32_e32 v152, v121, v121
	v_fmac_f32_e32 v152, v117, v117
	ds_bpermute_b32 v114, v149, v152
	s_waitcnt lgkmcnt(0)
	v_add_f32_e32 v114, v152, v114
	ds_bpermute_b32 v115, v150, v114
	s_and_saveexec_b64 s[28:29], s[6:7]
	s_cbranch_execz .LBB0_634
	s_waitcnt lgkmcnt(0)
	v_add_f32_e32 v116, v114, v115
	s_lshl_b32 s10, s0, 2
	v_lshlrev_b64 v[114:115], 6, v[142:143]
	s_ashr_i32 s11, s10, 31
	v_lshl_add_u64 v[114:115], s[42:43], 0, v[114:115]
	v_lshl_add_u64 v[114:115], s[10:11], 2, v[114:115]
	s_lshl_b32 s58, s77, 2
	v_lshl_add_u64 v[114:115], v[114:115], 0, s[58:59]
	global_store_dword v[114:115], v116, off

; #define PG8_STAGE(bufoff, gbase, voff) do { _Pragma("unroll") for (int _i = 0; _i < 2; ++_i) \
;         __builtin_amdgcn_global_load_lds((const unsigned*)((const char*)(gbase) + (voff)[_i]), (LAS unsigned*)(lds + (bufoff) + ldsw + _i * 8192), 16, 0, 0); } while (0)
; #define PG8_LDA(dst, b, h) do { _Pragma("unroll") for (int m = 0; m < 4; ++m) _Pragma("unroll") for (int k = 0; k < 2; ++k) dst[m][k] = *(const LAS bf16x8*)(lds + PG8_SA(b, h) + aoff + m * 2048 + k * 1024); } while (0)
; #define PG8_LDB(dst, b, h) do { _Pragma("unroll") for (int n = 0; n < 2; ++n) _Pragma("unroll") for (int k = 0; k < 2; ++k) dst[n][k] = *(const LAS bf16x8*)(lds + PG8_SB(b, h) + boff + n * 2048 + k * 1024); } while (0)
; #define PG8_MMA(ai, bj, At, Bt) do { __builtin_amdgcn_s_setprio(1); _Pragma("unroll") for (int m = 0; m < 4; ++m) _Pragma("unroll") for (int n = 0; n < 2; ++n) _Pragma("unroll") for (int k = 0; k < 2; ++k) \
;         acc[ai][bj][m][n] = __builtin_amdgcn_mfma_f32_16x16x32_bf16(Bt[n][k], At[m][k], acc[ai][bj][m][n], 0, 0, 0); __builtin_amdgcn_s_setprio(0); } while (0)
; #define PG8_WAIT_L(n) asm volatile("s_waitcnt lgkmcnt(" #n ")" ::: "memory")
; #define PG8_BAR __builtin_amdgcn_s_barrier()
; #define PG8_SCHED __builtin_amdgcn_sched_barrier(0)
; template <class Epi, class Sched>
; __device__ __forceinline__ void gemm_phase(LAS unsigned char* lds, const Gemm g, const Sched& S, const Epi& E) {
;     ...
;             PG8_LDB(B0, 0, 0); PG8_SCHED; PG8_LDA(At, 0, 0); PG8_STAGE(PG8_SA(1, 1), a1 + hstep, voffA);
;             PG8_WAIT_L(8); PG8_BAR; PG8_WAIT_L(0); PG8_MMA(0, 0, At, B0); PG8_BAR; PG8_SCHED;
;             PG8_LDB(B1, 0, 1); PG8_STAGE(PG8_SB(0, 0), b2, voffB);
;             PG8_BAR; PG8_WAIT_L(0); PG8_MMA(0, 1, At, B1); PG8_BAR;
;             PG8_LDA(At, 0, 1); PG8_STAGE(PG8_SA(0, 0), a2, voffA);
;             PG8_BAR; PG8_WAIT_L(0); PG8_MMA(1, 0, At, B0); PG8_BAR; PG8_SCHED;
.LBB0_717:
	s_add_u32 s38, s44, 0xfffc0080
	s_addc_u32 s39, s45, -1
	s_add_i32 s47, 0, 0x10000
	v_add_u32_e32 v149, s47, v145
	ds_read_b128 v[140:143], v149
	ds_read_b128 v[150:153], v149 offset:1024
	ds_read_b128 v[154:157], v149 offset:2048
	ds_read_b128 v[158:161], v149 offset:3072
	s_cmp_eq_u32 s17, 12
	s_cselect_b32 s79, s29, s39
	s_cselect_b32 s78, s16, s38
	s_cselect_b32 s69, s9, s84
	s_cselect_b32 s68, s82, s83
	v_lshl_add_u64 v[194:195], s[44:45], 0, v[136:137]
	s_add_i32 m0, s36, 0xc000
	ds_read_b128 v[162:165], v148
	ds_read_b128 v[166:169], v148 offset:1024
	ds_read_b128 v[170:173], v148 offset:2048
	ds_read_b128 v[174:177], v148 offset:3072
	ds_read_b128 v[178:181], v148 offset:4096
	ds_read_b128 v[182:185], v148 offset:5120
	ds_read_b128 v[186:189], v148 offset:6144
	ds_read_b128 v[190:193], v148 offset:7168
	global_load_lds_dwordx4 v[194:195], off
	v_lshl_add_u64 v[194:195], s[44:45], 0, v[138:139]
	s_add_i32 m0, s36, 0xe000
	s_nop 0
	global_load_lds_dwordx4 v[194:195], off
	s_waitcnt lgkmcnt(8)
	s_barrier
	s_waitcnt lgkmcnt(0)
	s_waitcnt lgkmcnt(0)
	v_mfma_f32_16x16x32_bf16 v[126:129], v[140:143], v[162:165], v[126:129]
	v_mfma_f32_16x16x32_bf16 v[122:125], v[154:157], v[162:165], v[122:125]
	v_mfma_f32_16x16x32_bf16 v[118:121], v[140:143], v[170:173], v[118:121]
	v_mfma_f32_16x16x32_bf16 v[110:113], v[154:157], v[170:173], v[110:113]
	v_mfma_f32_16x16x32_bf16 v[98:101], v[140:143], v[178:181], v[98:101]
	v_mfma_f32_16x16x32_bf16 v[90:93], v[154:157], v[178:181], v[90:93]
	v_mfma_f32_16x16x32_bf16 v[86:89], v[140:143], v[186:189], v[86:89]
	v_mfma_f32_16x16x32_bf16 v[78:81], v[154:157], v[186:189], v[78:81]
	v_mfma_f32_16x16x32_bf16 v[126:129], v[150:153], v[166:169], v[126:129]
	v_mfma_f32_16x16x32_bf16 v[122:125], v[158:161], v[166:169], v[122:125]
	v_mfma_f32_16x16x32_bf16 v[118:121], v[150:153], v[174:177], v[118:121]
	v_mfma_f32_16x16x32_bf16 v[110:113], v[158:161], v[174:177], v[110:113]
	v_mfma_f32_16x16x32_bf16 v[98:101], v[150:153], v[182:185], v[98:101]
	v_mfma_f32_16x16x32_bf16 v[90:93], v[158:161], v[182:185], v[90:93]
	v_mfma_f32_16x16x32_bf16 v[86:89], v[150:153], v[190:193], v[86:89]
	v_mfma_f32_16x16x32_bf16 v[78:81], v[158:161], v[190:193], v[78:81]
	s_barrier
	s_add_i32 s38, 0, 0x14000
	s_add_i32 s39, s47, s11
	v_add_u32_e32 v149, s38, v145
	v_lshl_add_u64 v[210:211], s[68:69], 0, v[0:1]
	s_mov_b32 m0, s39
	ds_read_b128 v[194:197], v149
	ds_read_b128 v[198:201], v149 offset:1024
	ds_read_b128 v[202:205], v149 offset:2048
	ds_read_b128 v[206:209], v149 offset:3072
	global_load_lds_dwordx4 v[210:211], off
	v_lshl_add_u64 v[212:213], s[68:69], 0, v[130:131]
	s_add_i32 m0, s39, 0x2000
	s_nop 0
	global_load_lds_dwordx4 v[212:213], off
	s_barrier
	s_waitcnt lgkmcnt(0)
	s_waitcnt lgkmcnt(0)
	v_mfma_f32_16x16x32_bf16 v[114:117], v[194:197], v[162:165], v[114:117]
	v_mfma_f32_16x16x32_bf16 v[106:109], v[202:205], v[162:165], v[106:109]
	v_mfma_f32_16x16x32_bf16 v[102:105], v[194:197], v[170:173], v[102:105]
	v_mfma_f32_16x16x32_bf16 v[94:97], v[202:205], v[170:173], v[94:97]
	v_mfma_f32_16x16x32_bf16 v[82:85], v[194:197], v[178:181], v[82:85]
	v_mfma_f32_16x16x32_bf16 v[74:77], v[202:205], v[178:181], v[74:77]
	v_mfma_f32_16x16x32_bf16 v[70:73], v[194:197], v[186:189], v[70:73]
	v_mfma_f32_16x16x32_bf16 v[66:69], v[202:205], v[186:189], v[66:69]
	v_mfma_f32_16x16x32_bf16 v[114:117], v[198:201], v[166:169], v[114:117]
	v_mfma_f32_16x16x32_bf16 v[106:109], v[206:209], v[166:169], v[106:109]
	v_mfma_f32_16x16x32_bf16 v[102:105], v[198:201], v[174:177], v[102:105]
	v_mfma_f32_16x16x32_bf16 v[94:97], v[206:209], v[174:177], v[94:97]
	v_mfma_f32_16x16x32_bf16 v[82:85], v[198:201], v[182:185], v[82:85]
	v_mfma_f32_16x16x32_bf16 v[74:77], v[206:209], v[182:185], v[74:77]
	v_mfma_f32_16x16x32_bf16 v[70:73], v[198:201], v[190:193], v[70:73]
	v_mfma_f32_16x16x32_bf16 v[66:69], v[206:209], v[190:193], v[66:69]
	s_mov_b32 m0, s36
	v_lshl_add_u64 v[214:215], s[78:79], 0, v[134:135]
	s_barrier
	ds_read_b128 v[162:165], v148 offset:16384
	ds_read_b128 v[166:169], v148 offset:17408
	ds_read_b128 v[170:173], v148 offset:18432
	ds_read_b128 v[174:177], v148 offset:19456
	ds_read_b128 v[178:181], v148 offset:20480
	ds_read_b128 v[182:185], v148 offset:21504
	ds_read_b128 v[186:189], v148 offset:22528
	ds_read_b128 v[190:193], v148 offset:23552
	global_load_lds_dwordx4 v[214:215], off
	v_lshl_add_u64 v[216:217], s[78:79], 0, v[132:133]
	s_mov_b32 m0, s37
	s_nop 0
	global_load_lds_dwordx4 v[216:217], off
	s_barrier
	s_waitcnt lgkmcnt(0)
	s_waitcnt lgkmcnt(0)
	v_mfma_f32_16x16x32_bf16 v[62:65], v[140:143], v[162:165], v[62:65]
	v_mfma_f32_16x16x32_bf16 v[58:61], v[154:157], v[162:165], v[58:61]
	v_mfma_f32_16x16x32_bf16 v[54:57], v[140:143], v[170:173], v[54:57]
	v_mfma_f32_16x16x32_bf16 v[46:49], v[154:157], v[170:173], v[46:49]
	v_mfma_f32_16x16x32_bf16 v[34:37], v[140:143], v[178:181], v[34:37]
	v_mfma_f32_16x16x32_bf16 v[26:29], v[154:157], v[178:181], v[26:29]
	v_mfma_f32_16x16x32_bf16 v[22:25], v[140:143], v[186:189], v[22:25]
	v_mfma_f32_16x16x32_bf16 v[14:17], v[154:157], v[186:189], v[14:17]
	v_mfma_f32_16x16x32_bf16 v[62:65], v[150:153], v[166:169], v[62:65]
	v_mfma_f32_16x16x32_bf16 v[58:61], v[158:161], v[166:169], v[58:61]
	v_mfma_f32_16x16x32_bf16 v[54:57], v[150:153], v[174:177], v[54:57]
	v_mfma_f32_16x16x32_bf16 v[46:49], v[158:161], v[174:177], v[46:49]
	v_mfma_f32_16x16x32_bf16 v[34:37], v[150:153], v[182:185], v[34:37]
	v_mfma_f32_16x16x32_bf16 v[26:29], v[158:161], v[182:185], v[26:29]
	v_mfma_f32_16x16x32_bf16 v[22:25], v[150:153], v[190:193], v[22:25]
	v_mfma_f32_16x16x32_bf16 v[14:17], v[158:161], v[190:193], v[14:17]
	s_barrier
; #define PG8_STAGE(bufoff, gbase, voff) do { _Pragma("unroll") for (int _i = 0; _i < 2; ++_i) \
;         __builtin_amdgcn_global_load_lds((const unsigned*)((const char*)(gbase) + (voff)[_i]), (LAS unsigned*)(lds + (bufoff) + ldsw + _i * 8192), 16, 0, 0); } while (0)
; #define PG8_LDA(dst, b, h) do { _Pragma("unroll") for (int m = 0; m < 4; ++m) _Pragma("unroll") for (int k = 0; k < 2; ++k) dst[m][k] = *(const LAS bf16x8*)(lds + PG8_SA(b, h) + aoff + m * 2048 + k * 1024); } while (0)
; #define PG8_LDB(dst, b, h) do { _Pragma("unroll") for (int n = 0; n < 2; ++n) _Pragma("unroll") for (int k = 0; k < 2; ++k) dst[n][k] = *(const LAS bf16x8*)(lds + PG8_SB(b, h) + boff + n * 2048 + k * 1024); } while (0)
; #define PG8_MMA(ai, bj, At, Bt) do { __builtin_amdgcn_s_setprio(1); _Pragma("unroll") for (int m = 0; m < 4; ++m) _Pragma("unroll") for (int n = 0; n < 2; ++n) _Pragma("unroll") for (int k = 0; k < 2; ++k) \
;         acc[ai][bj][m][n] = __builtin_amdgcn_mfma_f32_16x16x32_bf16(Bt[n][k], At[m][k], acc[ai][bj][m][n], 0, 0, 0); __builtin_amdgcn_s_setprio(0); } while (0)
; #define PG8_WAIT_V(n) asm volatile("s_waitcnt vmcnt(" #n ")" ::: "memory")
; #define PG8_WAIT_L(n) asm volatile("s_waitcnt lgkmcnt(" #n ")" ::: "memory")
; #define PG8_BAR __builtin_amdgcn_s_barrier()
; #define PG8_SCHED __builtin_amdgcn_sched_barrier(0)
; template <class Epi, class Sched>
; __device__ __forceinline__ void gemm_phase(LAS unsigned char* lds, const Gemm g, const Sched& S, const Epi& E) {
;     ...
;             PG8_STAGE(PG8_SB(0, 1), b2 + hstep, voffB);
;             PG8_WAIT_V(6); PG8_BAR; PG8_MMA(1, 1, At, B1); PG8_BAR;
;             PG8_LDB(B0, 1, 0); PG8_SCHED; PG8_LDA(At, 1, 0); PG8_STAGE(PG8_SA(0, 1), a2 + hstep, voffA);
;             PG8_WAIT_L(8); PG8_BAR; PG8_WAIT_L(0); PG8_MMA(0, 0, At, B0); PG8_BAR; PG8_SCHED;
;             PG8_LDB(B1, 1, 1); PG8_STAGE(PG8_SB(1, 0), b3, voffB);
;             PG8_BAR; PG8_WAIT_L(0); PG8_MMA(0, 1, At, B1); PG8_BAR;
;             PG8_LDA(At, 1, 1); PG8_STAGE(PG8_SA(1, 0), a3, voffA);
	s_add_u32 s86, s68, 0x40000
	s_addc_u32 s87, s69, 0
	s_add_i32 s38, s38, s11
	v_lshl_add_u64 v[140:141], s[86:87], 0, v[0:1]
	s_mov_b32 m0, s38
	s_nop 0
	global_load_lds_dwordx4 v[140:141], off
	v_lshl_add_u64 v[140:141], s[86:87], 0, v[130:131]
	s_add_i32 m0, s38, 0x2000
	s_nop 0
	global_load_lds_dwordx4 v[140:141], off
	s_waitcnt vmcnt(6)
	s_barrier
	v_mfma_f32_16x16x32_bf16 v[50:53], v[194:197], v[162:165], v[50:53]
	v_mfma_f32_16x16x32_bf16 v[42:45], v[202:205], v[162:165], v[42:45]
	v_mfma_f32_16x16x32_bf16 v[38:41], v[194:197], v[170:173], v[38:41]
	v_mfma_f32_16x16x32_bf16 v[30:33], v[202:205], v[170:173], v[30:33]
	v_mfma_f32_16x16x32_bf16 v[18:21], v[194:197], v[178:181], v[18:21]
	v_mfma_f32_16x16x32_bf16 v[10:13], v[202:205], v[178:181], v[10:13]
	v_mfma_f32_16x16x32_bf16 v[6:9], v[194:197], v[186:189], v[6:9]
	v_mfma_f32_16x16x32_bf16 v[2:5], v[202:205], v[186:189], v[2:5]
	v_mfma_f32_16x16x32_bf16 v[50:53], v[198:201], v[166:169], v[50:53]
	v_mfma_f32_16x16x32_bf16 v[42:45], v[206:209], v[166:169], v[42:45]
	v_mfma_f32_16x16x32_bf16 v[38:41], v[198:201], v[174:177], v[38:41]
	v_mfma_f32_16x16x32_bf16 v[30:33], v[206:209], v[174:177], v[30:33]
	v_mfma_f32_16x16x32_bf16 v[18:21], v[198:201], v[182:185], v[18:21]
	v_mfma_f32_16x16x32_bf16 v[10:13], v[206:209], v[182:185], v[10:13]
	v_mfma_f32_16x16x32_bf16 v[6:9], v[198:201], v[190:193], v[6:9]
	v_mfma_f32_16x16x32_bf16 v[2:5], v[206:209], v[190:193], v[2:5]
	s_add_i32 s38, 0, 0x18000
	v_add_u32_e32 v149, s38, v145
	s_barrier
	ds_read_b128 v[140:143], v149
	ds_read_b128 v[150:153], v149 offset:1024
	ds_read_b128 v[154:157], v149 offset:2048
	ds_read_b128 v[158:161], v149 offset:3072
	s_add_u32 s78, s78, 0x40000
	s_addc_u32 s79, s79, 0
	s_mov_b32 m0, s46
	v_lshl_add_u64 v[194:195], s[78:79], 0, v[134:135]
	ds_read_b128 v[162:165], v148 offset:32768
	ds_read_b128 v[166:169], v148 offset:33792
	ds_read_b128 v[170:173], v148 offset:34816
	ds_read_b128 v[174:177], v148 offset:35840
	ds_read_b128 v[178:181], v148 offset:36864
	ds_read_b128 v[182:185], v148 offset:37888
	ds_read_b128 v[186:189], v148 offset:38912
	ds_read_b128 v[190:193], v148 offset:39936
	global_load_lds_dwordx4 v[194:195], off
	v_lshl_add_u64 v[194:195], s[78:79], 0, v[132:133]
	s_mov_b32 m0, s51
	s_nop 0
	global_load_lds_dwordx4 v[194:195], off
	s_waitcnt lgkmcnt(8)
	s_barrier
	s_waitcnt lgkmcnt(0)
	s_waitcnt lgkmcnt(0)
	v_mfma_f32_16x16x32_bf16 v[126:129], v[140:143], v[162:165], v[126:129]
	v_mfma_f32_16x16x32_bf16 v[122:125], v[154:157], v[162:165], v[122:125]
	v_mfma_f32_16x16x32_bf16 v[118:121], v[140:143], v[170:173], v[118:121]
	v_mfma_f32_16x16x32_bf16 v[110:113], v[154:157], v[170:173], v[110:113]
	v_mfma_f32_16x16x32_bf16 v[98:101], v[140:143], v[178:181], v[98:101]
	v_mfma_f32_16x16x32_bf16 v[90:93], v[154:157], v[178:181], v[90:93]
	v_mfma_f32_16x16x32_bf16 v[86:89], v[140:143], v[186:189], v[86:89]
	v_mfma_f32_16x16x32_bf16 v[78:81], v[154:157], v[186:189], v[78:81]
	v_mfma_f32_16x16x32_bf16 v[126:129], v[150:153], v[166:169], v[126:129]
	v_mfma_f32_16x16x32_bf16 v[122:125], v[158:161], v[166:169], v[122:125]
	v_mfma_f32_16x16x32_bf16 v[118:121], v[150:153], v[174:177], v[118:121]
	v_mfma_f32_16x16x32_bf16 v[110:113], v[158:161], v[174:177], v[110:113]
	v_mfma_f32_16x16x32_bf16 v[98:101], v[150:153], v[182:185], v[98:101]
	v_mfma_f32_16x16x32_bf16 v[90:93], v[158:161], v[182:185], v[90:93]
	v_mfma_f32_16x16x32_bf16 v[86:89], v[150:153], v[190:193], v[86:89]
	v_mfma_f32_16x16x32_bf16 v[78:81], v[158:161], v[190:193], v[78:81]
	s_barrier
	s_add_i32 s39, 0, 0x1c000
	s_add_i32 s38, s38, s11
	v_add_u32_e32 v149, s39, v145
	v_lshl_add_u64 v[210:211], v[210:211], 0, s[62:63]
	s_mov_b32 m0, s38
	ds_read_b128 v[194:197], v149
	ds_read_b128 v[198:201], v149 offset:1024
	ds_read_b128 v[202:205], v149 offset:2048
	ds_read_b128 v[206:209], v149 offset:3072
	global_load_lds_dwordx4 v[210:211], off
	v_lshl_add_u64 v[210:211], v[212:213], 0, s[62:63]
	s_add_i32 m0, s38, 0x2000
	s_nop 0
	global_load_lds_dwordx4 v[210:211], off
	s_barrier
	s_waitcnt lgkmcnt(0)
	s_waitcnt lgkmcnt(0)
	v_mfma_f32_16x16x32_bf16 v[114:117], v[194:197], v[162:165], v[114:117]
	v_mfma_f32_16x16x32_bf16 v[106:109], v[202:205], v[162:165], v[106:109]
	v_mfma_f32_16x16x32_bf16 v[102:105], v[194:197], v[170:173], v[102:105]
	v_mfma_f32_16x16x32_bf16 v[94:97], v[202:205], v[170:173], v[94:97]
	v_mfma_f32_16x16x32_bf16 v[82:85], v[194:197], v[178:181], v[82:85]
	v_mfma_f32_16x16x32_bf16 v[74:77], v[202:205], v[178:181], v[74:77]
	v_mfma_f32_16x16x32_bf16 v[70:73], v[194:197], v[186:189], v[70:73]
	v_mfma_f32_16x16x32_bf16 v[66:69], v[202:205], v[186:189], v[66:69]
	v_mfma_f32_16x16x32_bf16 v[114:117], v[198:201], v[166:169], v[114:117]
	v_mfma_f32_16x16x32_bf16 v[106:109], v[206:209], v[166:169], v[106:109]
	v_mfma_f32_16x16x32_bf16 v[102:105], v[198:201], v[174:177], v[102:105]
	v_mfma_f32_16x16x32_bf16 v[94:97], v[206:209], v[174:177], v[94:97]
	v_mfma_f32_16x16x32_bf16 v[82:85], v[198:201], v[182:185], v[82:85]
	v_mfma_f32_16x16x32_bf16 v[74:77], v[206:209], v[182:185], v[74:77]
	v_mfma_f32_16x16x32_bf16 v[70:73], v[198:201], v[190:193], v[70:73]
	v_mfma_f32_16x16x32_bf16 v[66:69], v[206:209], v[190:193], v[66:69]
	s_mov_b32 m0, s58
	v_lshl_add_u64 v[210:211], v[214:215], 0, s[62:63]
	s_barrier
	ds_read_b128 v[162:165], v148 offset:49152
	ds_read_b128 v[166:169], v148 offset:50176
	ds_read_b128 v[170:173], v148 offset:51200
	ds_read_b128 v[174:177], v148 offset:52224
	ds_read_b128 v[178:181], v148 offset:53248
	ds_read_b128 v[182:185], v148 offset:54272
	ds_read_b128 v[186:189], v148 offset:55296
	ds_read_b128 v[190:193], v148 offset:56320
	global_load_lds_dwordx4 v[210:211], off
	v_lshl_add_u64 v[210:211], v[216:217], 0, s[62:63]
	s_mov_b32 m0, s72
	s_nop 0
	global_load_lds_dwordx4 v[210:211], off
	s_barrier
; __device__ __forceinline__ unsigned cvt_pk_bf16(float lo, float hi) { const f32v2_t v = {lo, hi}; const bf16v2_t r = __builtin_convertvector(v, bf16v2_t); return __builtin_bit_cast(unsigned, r); }
; #define PG8_STAGE(bufoff, gbase, voff) do { _Pragma("unroll") for (int _i = 0; _i < 2; ++_i) \
;         __builtin_amdgcn_global_load_lds((const unsigned*)((const char*)(gbase) + (voff)[_i]), (LAS unsigned*)(lds + (bufoff) + ldsw + _i * 8192), 16, 0, 0); } while (0)
; #define PG8_MMA(ai, bj, At, Bt) do { __builtin_amdgcn_s_setprio(1); _Pragma("unroll") for (int m = 0; m < 4; ++m) _Pragma("unroll") for (int n = 0; n < 2; ++n) _Pragma("unroll") for (int k = 0; k < 2; ++k) \
;         acc[ai][bj][m][n] = __builtin_amdgcn_mfma_f32_16x16x32_bf16(Bt[n][k], At[m][k], acc[ai][bj][m][n], 0, 0, 0); __builtin_amdgcn_s_setprio(0); } while (0)
; #define PG8_WAIT_V(n) asm volatile("s_waitcnt vmcnt(" #n ")" ::: "memory")
; #define PG8_WAIT_L(n) asm volatile("s_waitcnt lgkmcnt(" #n ")" ::: "memory")
; #define PG8_BAR __builtin_amdgcn_s_barrier()
; template <class Epi, class Sched>
; __device__ __forceinline__ void gemm_phase(LAS unsigned char* lds, const Gemm g, const Sched& S, const Epi& E) {
;     ...
;             PG8_BAR; PG8_WAIT_L(0); PG8_MMA(1, 0, At, B0); PG8_BAR; PG8_SCHED;
;             PG8_STAGE(PG8_SB(1, 1), b3 + hstep, voffB);
;             PG8_WAIT_V(6); PG8_BAR; PG8_MMA(1, 1, At, B1); PG8_BAR;
;         }
;     __device__ __forceinline__ void operator()(const f32x4 (&acc)[2][2][4][2], const Unit& u, int wr, int wc, int fr, int fq) const {
;         const int row0 = u.pm * BM + wr * 64 + fr, col0 = u.pn * BM + wc * 32 + 8 * fq;
; #pragma unroll
;         for (int ai = 0; ai < 2; ++ai)
; #pragma unroll
;             for (int m = 0; m < 4; ++m) { const int row = row0 + ai * HALF + m * 16; const float rs = rl[u.idx * 256 + wr * 64 + fr + ai * HALF + m * 16];
;                 bf16_t* rowp = O + (size_t)row * ldc + col0;
; #pragma unroll
;                 for (int bj = 0; bj < 2; ++bj) { const f32x4 v0 = acc[ai][bj][m][0] * rs, v1 = acc[ai][bj][m][1] * rs;
;                     u32x4 w; w.x = cvt_pk_bf16(v0[0], v0[1]); w.y = cvt_pk_bf16(v0[2], v0[3]); w.z = cvt_pk_bf16(v1[0], v1[1]); w.w = cvt_pk_bf16(v1[2], v1[3]);
;                     if (nt_from >= 0 && u.pn >= nt_from) __builtin_nontemporal_store(w, (u32x4*)(rowp + bj * HALF)); else *(u32x4*)(rowp + bj * HALF) = w; } }
	s_waitcnt lgkmcnt(0)
	s_waitcnt lgkmcnt(0)
	v_mfma_f32_16x16x32_bf16 v[62:65], v[140:143], v[162:165], v[62:65]
	v_mfma_f32_16x16x32_bf16 v[58:61], v[154:157], v[162:165], v[58:61]
	v_mfma_f32_16x16x32_bf16 v[54:57], v[140:143], v[170:173], v[54:57]
	v_mfma_f32_16x16x32_bf16 v[46:49], v[154:157], v[170:173], v[46:49]
	v_mfma_f32_16x16x32_bf16 v[34:37], v[140:143], v[178:181], v[34:37]
	v_mfma_f32_16x16x32_bf16 v[26:29], v[154:157], v[178:181], v[26:29]
	v_mfma_f32_16x16x32_bf16 v[22:25], v[140:143], v[186:189], v[22:25]
	v_mfma_f32_16x16x32_bf16 v[14:17], v[154:157], v[186:189], v[14:17]
	v_mfma_f32_16x16x32_bf16 v[62:65], v[150:153], v[166:169], v[62:65]
	v_mfma_f32_16x16x32_bf16 v[58:61], v[158:161], v[166:169], v[58:61]
	v_mfma_f32_16x16x32_bf16 v[54:57], v[150:153], v[174:177], v[54:57]
	v_mfma_f32_16x16x32_bf16 v[46:49], v[158:161], v[174:177], v[46:49]
	v_mfma_f32_16x16x32_bf16 v[34:37], v[150:153], v[182:185], v[34:37]
	v_mfma_f32_16x16x32_bf16 v[26:29], v[158:161], v[182:185], v[26:29]
	v_mfma_f32_16x16x32_bf16 v[22:25], v[150:153], v[190:193], v[22:25]
	v_mfma_f32_16x16x32_bf16 v[14:17], v[158:161], v[190:193], v[14:17]
	s_barrier
	s_add_u32 s68, s68, 0x40080
	s_addc_u32 s69, s69, 0
	s_add_i32 s38, s39, s11
	v_lshl_add_u64 v[140:141], s[68:69], 0, v[0:1]
	s_mov_b32 m0, s38
	s_nop 0
	global_load_lds_dwordx4 v[140:141], off
	v_lshl_add_u64 v[140:141], s[68:69], 0, v[130:131]
	s_add_i32 m0, s38, 0x2000
	s_nop 0
	global_load_lds_dwordx4 v[140:141], off
	s_waitcnt vmcnt(6)
	s_barrier
	v_mfma_f32_16x16x32_bf16 v[50:53], v[194:197], v[162:165], v[50:53]
	v_mfma_f32_16x16x32_bf16 v[42:45], v[202:205], v[162:165], v[42:45]
	v_mfma_f32_16x16x32_bf16 v[38:41], v[194:197], v[170:173], v[38:41]
	v_mfma_f32_16x16x32_bf16 v[30:33], v[202:205], v[170:173], v[30:33]
	v_mfma_f32_16x16x32_bf16 v[18:21], v[194:197], v[178:181], v[18:21]
	v_mfma_f32_16x16x32_bf16 v[10:13], v[202:205], v[178:181], v[10:13]
	v_mfma_f32_16x16x32_bf16 v[6:9], v[194:197], v[186:189], v[6:9]
	v_mfma_f32_16x16x32_bf16 v[2:5], v[202:205], v[186:189], v[2:5]
	v_mfma_f32_16x16x32_bf16 v[50:53], v[198:201], v[166:169], v[50:53]
	v_mfma_f32_16x16x32_bf16 v[42:45], v[206:209], v[166:169], v[42:45]
	v_mfma_f32_16x16x32_bf16 v[38:41], v[198:201], v[174:177], v[38:41]
	v_mfma_f32_16x16x32_bf16 v[30:33], v[206:209], v[174:177], v[30:33]
	v_mfma_f32_16x16x32_bf16 v[18:21], v[198:201], v[182:185], v[18:21]
	v_mfma_f32_16x16x32_bf16 v[10:13], v[206:209], v[182:185], v[10:13]
	v_mfma_f32_16x16x32_bf16 v[6:9], v[198:201], v[190:193], v[6:9]
	v_mfma_f32_16x16x32_bf16 v[2:5], v[206:209], v[190:193], v[2:5]
	s_add_i32 s17, s17, 2
	s_add_u32 s44, s44, 0x100
	s_addc_u32 s45, s45, 0
	s_add_u32 s83, s83, 0x100
	s_addc_u32 s84, s84, 0
	s_cmp_gt_u32 s17, 13
	s_barrier
	s_cbranch_scc0 .LBB0_717
	v_lshl_add_u32 v156, s76, 10, v146
	ds_read2_b32 v[150:151], v156 offset1:16
	v_lshl_or_b32 v142, s77, 8, v147
	v_lshl_add_u32 v149, s81, 8, v144
	v_ashrrev_i32_e32 v143, 31, v142
	v_mov_b64_e32 v[140:141], s[0:1]
	s_movk_i32 s9, 0x2c00
	v_mad_i64_i32 v[152:153], s[16:17], v149, s9, v[140:141]
	v_lshlrev_b64 v[142:143], 1, v[142:143]
	s_waitcnt lgkmcnt(0)
	v_pk_mul_f32 v[128:129], v[128:129], v[150:151] op_sel_hi:[1,0]
	v_pk_mul_f32 v[126:127], v[126:127], v[150:151] op_sel_hi:[1,0]
	v_pk_mul_f32 v[154:155], v[124:125], v[150:151] op_sel_hi:[1,0]
	v_pk_mul_f32 v[124:125], v[122:123], v[150:151] op_sel_hi:[1,0]
	v_lshl_add_u64 v[152:153], v[152:153], 0, v[142:143]
	v_cvt_pk_bf16_f32 v122, v126, v127
	v_cvt_pk_bf16_f32 v123, v128, v129
	v_cvt_pk_bf16_f32 v124, v124, v125
	v_cvt_pk_bf16_f32 v125, v154, v155
	global_store_dwordx4 v[152:153], v[122:125], off
	v_pk_mul_f32 v[116:117], v[116:117], v[150:151] op_sel_hi:[1,0]
	v_pk_mul_f32 v[114:115], v[114:115], v[150:151] op_sel_hi:[1,0]
	v_pk_mul_f32 v[122:123], v[108:109], v[150:151] op_sel_hi:[1,0]
	v_pk_mul_f32 v[108:109], v[106:107], v[150:151] op_sel_hi:[1,0]
	v_cvt_pk_bf16_f32 v106, v114, v115
	v_cvt_pk_bf16_f32 v107, v116, v117
	v_cvt_pk_bf16_f32 v108, v108, v109
	v_cvt_pk_bf16_f32 v109, v122, v123
	global_store_dwordx4 v[152:153], v[106:109], off offset:256
	v_mov_b32_e32 v116, v151
	v_pk_mul_f32 v[112:113], v[112:113], v[116:117] op_sel_hi:[1,0]
	v_or_b32_e32 v106, 16, v149
	v_mad_i64_i32 v[106:107], s[16:17], v106, s9, v[140:141]
	v_lshl_add_u64 v[114:115], v[106:107], 0, v[142:143]
	v_pk_mul_f32 v[108:109], v[120:121], v[116:117] op_sel_hi:[1,0]
	v_pk_mul_f32 v[106:107], v[118:119], v[116:117] op_sel_hi:[1,0]
	v_pk_mul_f32 v[110:111], v[110:111], v[116:117] op_sel_hi:[1,0]
	v_cvt_pk_bf16_f32 v106, v106, v107
	v_cvt_pk_bf16_f32 v107, v108, v109
	v_cvt_pk_bf16_f32 v108, v110, v111
	v_cvt_pk_bf16_f32 v109, v112, v113
	global_store_dwordx4 v[114:115], v[106:109], off
	v_pk_mul_f32 v[104:105], v[104:105], v[116:117] op_sel_hi:[1,0]
	v_pk_mul_f32 v[102:103], v[102:103], v[116:117] op_sel_hi:[1,0]
	v_pk_mul_f32 v[106:107], v[96:97], v[116:117] op_sel_hi:[1,0]
	v_pk_mul_f32 v[96:97], v[94:95], v[116:117] op_sel_hi:[1,0]
	v_cvt_pk_bf16_f32 v94, v102, v103
	v_cvt_pk_bf16_f32 v95, v104, v105
	v_cvt_pk_bf16_f32 v96, v96, v97
	v_cvt_pk_bf16_f32 v97, v106, v107
	global_store_dwordx4 v[114:115], v[94:97], off offset:256
	ds_read2_b32 v[94:95], v156 offset0:32 offset1:48
	s_and_b64 vcc, exec, s[6:7]
	v_or_b32_e32 v96, 32, v149
	v_mad_i64_i32 v[96:97], s[16:17], v96, s9, v[140:141]
	s_waitcnt lgkmcnt(0)
; __device__ __forceinline__ unsigned cvt_pk_bf16(float lo, float hi) { const f32v2_t v = {lo, hi}; const bf16v2_t r = __builtin_convertvector(v, bf16v2_t); return __builtin_bit_cast(unsigned, r); }
;     __device__ __forceinline__ void operator()(const f32x4 (&acc)[2][2][4][2], const Unit& u, int wr, int wc, int fr, int fq) const { if (u.kind == 0) e0(acc, u, wr, wc, fr, fq); else e1(acc, u, wr, wc, fr, fq); }
;     __device__ __forceinline__ void operator()(const f32x4 (&acc)[2][2][4][2], const Unit& u, int wr, int wc, int fr, int fq) const {
;         const int row0 = u.pm * BM + wr * 64 + fr, col0 = u.pn * BM + wc * 32 + 8 * fq;
; #pragma unroll
;         for (int ai = 0; ai < 2; ++ai)
; #pragma unroll
;             for (int m = 0; m < 4; ++m) { const int row = row0 + ai * HALF + m * 16; const float rs = rl[u.idx * 256 + wr * 64 + fr + ai * HALF + m * 16];
;                 bf16_t* rowp = O + (size_t)row * ldc + col0;
; #pragma unroll
;                 for (int bj = 0; bj < 2; ++bj) { const f32x4 v0 = acc[ai][bj][m][0] * rs, v1 = acc[ai][bj][m][1] * rs;
;                     u32x4 w; w.x = cvt_pk_bf16(v0[0], v0[1]); w.y = cvt_pk_bf16(v0[2], v0[3]); w.z = cvt_pk_bf16(v1[0], v1[1]); w.w = cvt_pk_bf16(v1[2], v1[3]);
;                     if (nt_from >= 0 && u.pn >= nt_from) __builtin_nontemporal_store(w, (u32x4*)(rowp + bj * HALF)); else *(u32x4*)(rowp + bj * HALF) = w; } }
	v_pk_mul_f32 v[100:101], v[100:101], v[94:95] op_sel_hi:[1,0]
	v_pk_mul_f32 v[98:99], v[98:99], v[94:95] op_sel_hi:[1,0]
	v_pk_mul_f32 v[102:103], v[92:93], v[94:95] op_sel_hi:[1,0]
	v_pk_mul_f32 v[92:93], v[90:91], v[94:95] op_sel_hi:[1,0]
	v_lshl_add_u64 v[96:97], v[96:97], 0, v[142:143]
	v_cvt_pk_bf16_f32 v90, v98, v99
	v_cvt_pk_bf16_f32 v91, v100, v101
	v_cvt_pk_bf16_f32 v92, v92, v93
	v_cvt_pk_bf16_f32 v93, v102, v103
	global_store_dwordx4 v[96:97], v[90:93], off
	v_pk_mul_f32 v[84:85], v[84:85], v[94:95] op_sel_hi:[1,0]
	v_pk_mul_f32 v[82:83], v[82:83], v[94:95] op_sel_hi:[1,0]
	v_pk_mul_f32 v[90:91], v[76:77], v[94:95] op_sel_hi:[1,0]
	v_pk_mul_f32 v[76:77], v[74:75], v[94:95] op_sel_hi:[1,0]
	v_cvt_pk_bf16_f32 v74, v82, v83
	v_cvt_pk_bf16_f32 v75, v84, v85
	v_cvt_pk_bf16_f32 v76, v76, v77
	v_cvt_pk_bf16_f32 v77, v90, v91
	global_store_dwordx4 v[96:97], v[74:77], off offset:256
	v_mov_b32_e32 v84, v95
	v_pk_mul_f32 v[80:81], v[80:81], v[84:85] op_sel_hi:[1,0]
	v_or_b32_e32 v74, 48, v149
	v_mad_i64_i32 v[74:75], s[16:17], v74, s9, v[140:141]
	v_lshl_add_u64 v[82:83], v[74:75], 0, v[142:143]
	v_pk_mul_f32 v[76:77], v[88:89], v[84:85] op_sel_hi:[1,0]
	v_pk_mul_f32 v[74:75], v[86:87], v[84:85] op_sel_hi:[1,0]
	v_pk_mul_f32 v[78:79], v[78:79], v[84:85] op_sel_hi:[1,0]
	v_cvt_pk_bf16_f32 v74, v74, v75
	v_cvt_pk_bf16_f32 v75, v76, v77
	v_cvt_pk_bf16_f32 v76, v78, v79
	v_cvt_pk_bf16_f32 v77, v80, v81
	global_store_dwordx4 v[82:83], v[74:77], off
	v_pk_mul_f32 v[72:73], v[72:73], v[84:85] op_sel_hi:[1,0]
	v_pk_mul_f32 v[70:71], v[70:71], v[84:85] op_sel_hi:[1,0]
	v_pk_mul_f32 v[74:75], v[68:69], v[84:85] op_sel_hi:[1,0]
	v_pk_mul_f32 v[68:69], v[66:67], v[84:85] op_sel_hi:[1,0]
	v_cvt_pk_bf16_f32 v66, v70, v71
	v_cvt_pk_bf16_f32 v67, v72, v73
	v_cvt_pk_bf16_f32 v68, v68, v69
	v_cvt_pk_bf16_f32 v69, v74, v75
	global_store_dwordx4 v[82:83], v[66:69], off offset:256
	ds_read2_b32 v[66:67], v156 offset0:128 offset1:144
	s_mov_b32 s77, s8
	v_add_u32_e32 v68, 0x80, v149
	v_mad_i64_i32 v[68:69], s[16:17], v68, s9, v[140:141]
	s_waitcnt lgkmcnt(0)
	v_pk_mul_f32 v[64:65], v[64:65], v[66:67] op_sel_hi:[1,0]
	v_pk_mul_f32 v[62:63], v[62:63], v[66:67] op_sel_hi:[1,0]
	v_pk_mul_f32 v[70:71], v[60:61], v[66:67] op_sel_hi:[1,0]
	v_pk_mul_f32 v[60:61], v[58:59], v[66:67] op_sel_hi:[1,0]
	v_lshl_add_u64 v[68:69], v[68:69], 0, v[142:143]
	v_cvt_pk_bf16_f32 v58, v62, v63
	v_cvt_pk_bf16_f32 v59, v64, v65
	v_cvt_pk_bf16_f32 v60, v60, v61
	v_cvt_pk_bf16_f32 v61, v70, v71
	global_store_dwordx4 v[68:69], v[58:61], off
	v_pk_mul_f32 v[52:53], v[52:53], v[66:67] op_sel_hi:[1,0]
	v_pk_mul_f32 v[50:51], v[50:51], v[66:67] op_sel_hi:[1,0]
	v_pk_mul_f32 v[58:59], v[44:45], v[66:67] op_sel_hi:[1,0]
	v_pk_mul_f32 v[44:45], v[42:43], v[66:67] op_sel_hi:[1,0]
	v_cvt_pk_bf16_f32 v42, v50, v51
	v_cvt_pk_bf16_f32 v43, v52, v53
	v_cvt_pk_bf16_f32 v44, v44, v45
	v_cvt_pk_bf16_f32 v45, v58, v59
	global_store_dwordx4 v[68:69], v[42:45], off offset:256
	v_mov_b32_e32 v52, v67
	v_pk_mul_f32 v[48:49], v[48:49], v[52:53] op_sel_hi:[1,0]
	v_add_u32_e32 v42, 0x90, v149
	v_mad_i64_i32 v[42:43], s[16:17], v42, s9, v[140:141]
	v_lshl_add_u64 v[50:51], v[42:43], 0, v[142:143]
	v_pk_mul_f32 v[44:45], v[56:57], v[52:53] op_sel_hi:[1,0]
	v_pk_mul_f32 v[42:43], v[54:55], v[52:53] op_sel_hi:[1,0]
	v_pk_mul_f32 v[46:47], v[46:47], v[52:53] op_sel_hi:[1,0]
	v_cvt_pk_bf16_f32 v42, v42, v43
	v_cvt_pk_bf16_f32 v43, v44, v45
	v_cvt_pk_bf16_f32 v44, v46, v47
	v_cvt_pk_bf16_f32 v45, v48, v49
	global_store_dwordx4 v[50:51], v[42:45], off
	v_pk_mul_f32 v[40:41], v[40:41], v[52:53] op_sel_hi:[1,0]
	v_pk_mul_f32 v[38:39], v[38:39], v[52:53] op_sel_hi:[1,0]
	v_pk_mul_f32 v[42:43], v[32:33], v[52:53] op_sel_hi:[1,0]
	v_pk_mul_f32 v[32:33], v[30:31], v[52:53] op_sel_hi:[1,0]
	v_cvt_pk_bf16_f32 v30, v38, v39
	v_cvt_pk_bf16_f32 v31, v40, v41
	v_cvt_pk_bf16_f32 v32, v32, v33
	v_cvt_pk_bf16_f32 v33, v42, v43
	global_store_dwordx4 v[50:51], v[30:33], off offset:256
	ds_read2_b32 v[30:31], v156 offset0:160 offset1:176
	s_mov_b32 s81, s28
	v_add_u32_e32 v32, 0xa0, v149
	v_mad_i64_i32 v[32:33], s[16:17], v32, s9, v[140:141]
	s_waitcnt lgkmcnt(0)
	v_pk_mul_f32 v[36:37], v[36:37], v[30:31] op_sel_hi:[1,0]
	v_pk_mul_f32 v[34:35], v[34:35], v[30:31] op_sel_hi:[1,0]
	v_pk_mul_f32 v[38:39], v[28:29], v[30:31] op_sel_hi:[1,0]
	v_pk_mul_f32 v[28:29], v[26:27], v[30:31] op_sel_hi:[1,0]
	v_lshl_add_u64 v[32:33], v[32:33], 0, v[142:143]
	v_cvt_pk_bf16_f32 v26, v34, v35
	v_cvt_pk_bf16_f32 v27, v36, v37
	v_cvt_pk_bf16_f32 v28, v28, v29
	v_cvt_pk_bf16_f32 v29, v38, v39
	global_store_dwordx4 v[32:33], v[26:29], off
	v_pk_mul_f32 v[20:21], v[20:21], v[30:31] op_sel_hi:[1,0]
	v_pk_mul_f32 v[18:19], v[18:19], v[30:31] op_sel_hi:[1,0]
	v_pk_mul_f32 v[26:27], v[12:13], v[30:31] op_sel_hi:[1,0]
	v_pk_mul_f32 v[12:13], v[10:11], v[30:31] op_sel_hi:[1,0]
	v_cvt_pk_bf16_f32 v10, v18, v19
	v_cvt_pk_bf16_f32 v11, v20, v21
	v_cvt_pk_bf16_f32 v12, v12, v13
	v_cvt_pk_bf16_f32 v13, v26, v27
	global_store_dwordx4 v[32:33], v[10:13], off offset:256
	v_mov_b32_e32 v20, v31
	v_pk_mul_f32 v[16:17], v[16:17], v[20:21] op_sel_hi:[1,0]
	v_add_u32_e32 v10, 0xb0, v149
	v_mad_i64_i32 v[10:11], s[16:17], v10, s9, v[140:141]
	v_lshl_add_u64 v[18:19], v[10:11], 0, v[142:143]
	v_pk_mul_f32 v[12:13], v[24:25], v[20:21] op_sel_hi:[1,0]
	v_pk_mul_f32 v[10:11], v[22:23], v[20:21] op_sel_hi:[1,0]
	v_pk_mul_f32 v[14:15], v[14:15], v[20:21] op_sel_hi:[1,0]
	v_pk_mul_f32 v[8:9], v[8:9], v[20:21] op_sel_hi:[1,0]
	v_pk_mul_f32 v[6:7], v[6:7], v[20:21] op_sel_hi:[1,0]
	v_pk_mul_f32 v[4:5], v[4:5], v[20:21] op_sel_hi:[1,0]
	v_pk_mul_f32 v[2:3], v[2:3], v[20:21] op_sel_hi:[1,0]
	v_cvt_pk_bf16_f32 v10, v10, v11
	v_cvt_pk_bf16_f32 v11, v12, v13
	v_cvt_pk_bf16_f32 v12, v14, v15
	v_cvt_pk_bf16_f32 v13, v16, v17
	v_cvt_pk_bf16_f32 v6, v6, v7
	v_cvt_pk_bf16_f32 v7, v8, v9
	v_cvt_pk_bf16_f32 v8, v2, v3
	v_cvt_pk_bf16_f32 v9, v4, v5
	s_mov_b32 s76, s73
	s_mov_b64 s[68:69], s[42:43]
	s_mov_b64 s[44:45], s[40:41]
	global_store_dwordx4 v[18:19], v[10:13], off
	global_store_dwordx4 v[18:19], v[6:9], off offset:256
	s_cbranch_vccz .LBB0_714
	s_waitcnt vmcnt(0)
	s_cmpk_gt_u32 s10, 0xff
	v_readlane_b32 s81, v255, 6
	s_cbranch_scc1 .LBB0_721
	s_barrier

; #define PG8_STAGE(bufoff, gbase, voff) do { _Pragma("unroll") for (int _i = 0; _i < 2; ++_i) \
;         __builtin_amdgcn_global_load_lds((const unsigned*)((const char*)(gbase) + (voff)[_i]), (LAS unsigned*)(lds + (bufoff) + ldsw + _i * 8192), 16, 0, 0); } while (0)
; #define PG8_LDA(dst, b, h) do { _Pragma("unroll") for (int m = 0; m < 4; ++m) _Pragma("unroll") for (int k = 0; k < 2; ++k) dst[m][k] = *(const LAS bf16x8*)(lds + PG8_SA(b, h) + aoff + m * 2048 + k * 1024); } while (0)
; #define PG8_LDB(dst, b, h) do { _Pragma("unroll") for (int n = 0; n < 2; ++n) _Pragma("unroll") for (int k = 0; k < 2; ++k) dst[n][k] = *(const LAS bf16x8*)(lds + PG8_SB(b, h) + boff + n * 2048 + k * 1024); } while (0)
; #define PG8_MMA(ai, bj, At, Bt) do { __builtin_amdgcn_s_setprio(1); _Pragma("unroll") for (int m = 0; m < 4; ++m) _Pragma("unroll") for (int n = 0; n < 2; ++n) _Pragma("unroll") for (int k = 0; k < 2; ++k) \
;         acc[ai][bj][m][n] = __builtin_amdgcn_mfma_f32_16x16x32_bf16(Bt[n][k], At[m][k], acc[ai][bj][m][n], 0, 0, 0); __builtin_amdgcn_s_setprio(0); } while (0)
; #define PG8_WAIT_L(n) asm volatile("s_waitcnt lgkmcnt(" #n ")" ::: "memory")
; #define PG8_BAR __builtin_amdgcn_s_barrier()
; #define PG8_SCHED __builtin_amdgcn_sched_barrier(0)
; template <class Epi, class Sched>
; __device__ __forceinline__ void gemm_phase(LAS unsigned char* lds, const Gemm g, const Sched& S, const Epi& E) {
;     ...
;             PG8_LDB(B0, 0, 0); PG8_SCHED; PG8_LDA(At, 0, 0); PG8_STAGE(PG8_SA(1, 1), a1 + hstep, voffA);
;             PG8_WAIT_L(8); PG8_BAR; PG8_WAIT_L(0); PG8_MMA(0, 0, At, B0); PG8_BAR; PG8_SCHED;
;             PG8_LDB(B1, 0, 1); PG8_STAGE(PG8_SB(0, 0), b2, voffB);
;             PG8_BAR; PG8_WAIT_L(0); PG8_MMA(0, 1, At, B1); PG8_BAR;
;             PG8_LDA(At, 0, 1); PG8_STAGE(PG8_SA(0, 0), a2, voffA);
;             PG8_BAR; PG8_WAIT_L(0); PG8_MMA(1, 0, At, B0); PG8_BAR; PG8_SCHED;
.LBB0_851:
	s_add_u32 s44, s28, 0x100
	s_addc_u32 s45, s29, 0
	s_add_i32 s34, 0, 0x10000
	v_add_u32_e32 v144, s34, v147
	ds_read_b128 v[140:143], v144
	ds_read_b128 v[152:155], v144 offset:1024
	ds_read_b128 v[156:159], v144 offset:2048
	ds_read_b128 v[160:163], v144 offset:3072
	s_cmp_eq_u32 s17, 40
	s_cselect_b32 s79, s9, s45
	s_cselect_b32 s78, s8, s44
	s_cselect_b32 s69, s1, s16
	s_cselect_b32 s68, s0, s11
	v_lshl_add_u64 v[144:145], s[28:29], 0, v[136:137]
	s_add_i32 m0, s73, 0xc000
	ds_read_b128 v[164:167], v151
	ds_read_b128 v[168:171], v151 offset:1024
	ds_read_b128 v[172:175], v151 offset:2048
	ds_read_b128 v[176:179], v151 offset:3072
	ds_read_b128 v[180:183], v151 offset:4096
	ds_read_b128 v[184:187], v151 offset:5120
	ds_read_b128 v[188:191], v151 offset:6144
	ds_read_b128 v[192:195], v151 offset:7168
	global_load_lds_dwordx4 v[144:145], off
	v_lshl_add_u64 v[144:145], s[28:29], 0, v[138:139]
	s_add_i32 m0, s73, 0xe000
	s_nop 0
	global_load_lds_dwordx4 v[144:145], off
	s_waitcnt lgkmcnt(8)
	s_barrier
	s_waitcnt lgkmcnt(0)
	s_waitcnt lgkmcnt(0)
	v_mfma_f32_16x16x32_bf16 v[126:129], v[140:143], v[164:167], v[126:129]
	v_mfma_f32_16x16x32_bf16 v[122:125], v[156:159], v[164:167], v[122:125]
	v_mfma_f32_16x16x32_bf16 v[110:113], v[140:143], v[172:175], v[110:113]
	v_mfma_f32_16x16x32_bf16 v[106:109], v[156:159], v[172:175], v[106:109]
	v_mfma_f32_16x16x32_bf16 v[94:97], v[140:143], v[180:183], v[94:97]
	v_mfma_f32_16x16x32_bf16 v[90:93], v[156:159], v[180:183], v[90:93]
	v_mfma_f32_16x16x32_bf16 v[78:81], v[140:143], v[188:191], v[78:81]
	v_mfma_f32_16x16x32_bf16 v[74:77], v[156:159], v[188:191], v[74:77]
	v_mfma_f32_16x16x32_bf16 v[126:129], v[152:155], v[168:171], v[126:129]
	v_mfma_f32_16x16x32_bf16 v[122:125], v[160:163], v[168:171], v[122:125]
	v_mfma_f32_16x16x32_bf16 v[110:113], v[152:155], v[176:179], v[110:113]
	v_mfma_f32_16x16x32_bf16 v[106:109], v[160:163], v[176:179], v[106:109]
	v_mfma_f32_16x16x32_bf16 v[94:97], v[152:155], v[184:187], v[94:97]
	v_mfma_f32_16x16x32_bf16 v[90:93], v[160:163], v[184:187], v[90:93]
	v_mfma_f32_16x16x32_bf16 v[78:81], v[152:155], v[192:195], v[78:81]
	v_mfma_f32_16x16x32_bf16 v[74:77], v[160:163], v[192:195], v[74:77]
	s_barrier
	s_add_i32 s38, 0, 0x14000
	v_add_u32_e32 v144, s38, v147
	s_add_i32 s28, s34, s72
	ds_read_b128 v[196:199], v144
	ds_read_b128 v[200:203], v144 offset:1024
	ds_read_b128 v[204:207], v144 offset:2048
	ds_read_b128 v[208:211], v144 offset:3072
	v_lshl_add_u64 v[144:145], s[68:69], 0, v[0:1]
	s_mov_b32 m0, s28
	v_lshl_add_u64 v[212:213], s[68:69], 0, v[134:135]
	global_load_lds_dwordx4 v[144:145], off
	s_add_i32 m0, s28, 0x2000
	s_nop 0
	global_load_lds_dwordx4 v[212:213], off
	s_barrier
	s_waitcnt lgkmcnt(0)
	s_waitcnt lgkmcnt(0)
	v_mfma_f32_16x16x32_bf16 v[118:121], v[196:199], v[164:167], v[118:121]
	v_mfma_f32_16x16x32_bf16 v[114:117], v[204:207], v[164:167], v[114:117]
	v_mfma_f32_16x16x32_bf16 v[102:105], v[196:199], v[172:175], v[102:105]
	v_mfma_f32_16x16x32_bf16 v[98:101], v[204:207], v[172:175], v[98:101]
	v_mfma_f32_16x16x32_bf16 v[86:89], v[196:199], v[180:183], v[86:89]
	v_mfma_f32_16x16x32_bf16 v[82:85], v[204:207], v[180:183], v[82:85]
	v_mfma_f32_16x16x32_bf16 v[70:73], v[196:199], v[188:191], v[70:73]
	v_mfma_f32_16x16x32_bf16 v[66:69], v[204:207], v[188:191], v[66:69]
	v_mfma_f32_16x16x32_bf16 v[118:121], v[200:203], v[168:171], v[118:121]
	v_mfma_f32_16x16x32_bf16 v[114:117], v[208:211], v[168:171], v[114:117]
	v_mfma_f32_16x16x32_bf16 v[102:105], v[200:203], v[176:179], v[102:105]
	v_mfma_f32_16x16x32_bf16 v[98:101], v[208:211], v[176:179], v[98:101]
	v_mfma_f32_16x16x32_bf16 v[86:89], v[200:203], v[184:187], v[86:89]
	v_mfma_f32_16x16x32_bf16 v[82:85], v[208:211], v[184:187], v[82:85]
	v_mfma_f32_16x16x32_bf16 v[70:73], v[200:203], v[192:195], v[70:73]
	v_mfma_f32_16x16x32_bf16 v[66:69], v[208:211], v[192:195], v[66:69]
	s_mov_b32 m0, s73
	v_lshl_add_u64 v[214:215], s[78:79], 0, v[130:131]
	s_barrier
	ds_read_b128 v[164:167], v151 offset:16384
	ds_read_b128 v[168:171], v151 offset:17408
	ds_read_b128 v[172:175], v151 offset:18432
	ds_read_b128 v[176:179], v151 offset:19456
	ds_read_b128 v[180:183], v151 offset:20480
	ds_read_b128 v[184:187], v151 offset:21504
	ds_read_b128 v[188:191], v151 offset:22528
	ds_read_b128 v[192:195], v151 offset:23552
	global_load_lds_dwordx4 v[214:215], off
	v_lshl_add_u64 v[216:217], s[78:79], 0, v[132:133]
	s_mov_b32 m0, s76
	s_nop 0
	global_load_lds_dwordx4 v[216:217], off
	s_barrier
	s_waitcnt lgkmcnt(0)
	s_waitcnt lgkmcnt(0)
	v_mfma_f32_16x16x32_bf16 v[62:65], v[140:143], v[164:167], v[62:65]
	v_mfma_f32_16x16x32_bf16 v[58:61], v[156:159], v[164:167], v[58:61]
	v_mfma_f32_16x16x32_bf16 v[46:49], v[140:143], v[172:175], v[46:49]
	v_mfma_f32_16x16x32_bf16 v[42:45], v[156:159], v[172:175], v[42:45]
	v_mfma_f32_16x16x32_bf16 v[30:33], v[140:143], v[180:183], v[30:33]
	v_mfma_f32_16x16x32_bf16 v[26:29], v[156:159], v[180:183], v[26:29]
	v_mfma_f32_16x16x32_bf16 v[14:17], v[140:143], v[188:191], v[14:17]
	v_mfma_f32_16x16x32_bf16 v[10:13], v[156:159], v[188:191], v[10:13]
	v_mfma_f32_16x16x32_bf16 v[62:65], v[152:155], v[168:171], v[62:65]
	v_mfma_f32_16x16x32_bf16 v[58:61], v[160:163], v[168:171], v[58:61]
	v_mfma_f32_16x16x32_bf16 v[46:49], v[152:155], v[176:179], v[46:49]
	v_mfma_f32_16x16x32_bf16 v[42:45], v[160:163], v[176:179], v[42:45]
	v_mfma_f32_16x16x32_bf16 v[30:33], v[152:155], v[184:187], v[30:33]
	v_mfma_f32_16x16x32_bf16 v[26:29], v[160:163], v[184:187], v[26:29]
	v_mfma_f32_16x16x32_bf16 v[14:17], v[152:155], v[192:195], v[14:17]
	v_mfma_f32_16x16x32_bf16 v[10:13], v[160:163], v[192:195], v[10:13]
	s_barrier
; #define PG8_STAGE(bufoff, gbase, voff) do { _Pragma("unroll") for (int _i = 0; _i < 2; ++_i) \
;         __builtin_amdgcn_global_load_lds((const unsigned*)((const char*)(gbase) + (voff)[_i]), (LAS unsigned*)(lds + (bufoff) + ldsw + _i * 8192), 16, 0, 0); } while (0)
; #define PG8_LDA(dst, b, h) do { _Pragma("unroll") for (int m = 0; m < 4; ++m) _Pragma("unroll") for (int k = 0; k < 2; ++k) dst[m][k] = *(const LAS bf16x8*)(lds + PG8_SA(b, h) + aoff + m * 2048 + k * 1024); } while (0)
; #define PG8_LDB(dst, b, h) do { _Pragma("unroll") for (int n = 0; n < 2; ++n) _Pragma("unroll") for (int k = 0; k < 2; ++k) dst[n][k] = *(const LAS bf16x8*)(lds + PG8_SB(b, h) + boff + n * 2048 + k * 1024); } while (0)
; #define PG8_MMA(ai, bj, At, Bt) do { __builtin_amdgcn_s_setprio(1); _Pragma("unroll") for (int m = 0; m < 4; ++m) _Pragma("unroll") for (int n = 0; n < 2; ++n) _Pragma("unroll") for (int k = 0; k < 2; ++k) \
;         acc[ai][bj][m][n] = __builtin_amdgcn_mfma_f32_16x16x32_bf16(Bt[n][k], At[m][k], acc[ai][bj][m][n], 0, 0, 0); __builtin_amdgcn_s_setprio(0); } while (0)
; #define PG8_WAIT_V(n) asm volatile("s_waitcnt vmcnt(" #n ")" ::: "memory")
; #define PG8_WAIT_L(n) asm volatile("s_waitcnt lgkmcnt(" #n ")" ::: "memory")
; #define PG8_BAR __builtin_amdgcn_s_barrier()
; #define PG8_SCHED __builtin_amdgcn_sched_barrier(0)
; template <class Epi, class Sched>
; __device__ __forceinline__ void gemm_phase(LAS unsigned char* lds, const Gemm g, const Sched& S, const Epi& E) {
;     ...
;             PG8_STAGE(PG8_SB(0, 1), b2 + hstep, voffB);
;             PG8_WAIT_V(6); PG8_BAR; PG8_MMA(1, 1, At, B1); PG8_BAR;
;             PG8_LDB(B0, 1, 0); PG8_SCHED; PG8_LDA(At, 1, 0); PG8_STAGE(PG8_SA(0, 1), a2 + hstep, voffA);
;             PG8_WAIT_L(8); PG8_BAR; PG8_WAIT_L(0); PG8_MMA(0, 0, At, B0); PG8_BAR; PG8_SCHED;
;             PG8_LDB(B1, 1, 1); PG8_STAGE(PG8_SB(1, 0), b3, voffB);
;             PG8_BAR; PG8_WAIT_L(0); PG8_MMA(0, 1, At, B1); PG8_BAR;
;             PG8_LDA(At, 1, 1); PG8_STAGE(PG8_SA(1, 0), a3, voffA);
	s_add_u32 s28, s68, 0xb0000
	s_addc_u32 s29, s69, 0
	s_add_i32 s34, s38, s72
	v_lshl_add_u64 v[140:141], s[28:29], 0, v[0:1]
	s_mov_b32 m0, s34
	s_nop 0
	global_load_lds_dwordx4 v[140:141], off
	v_lshl_add_u64 v[140:141], s[28:29], 0, v[134:135]
	s_add_i32 m0, s34, 0x2000
	s_nop 0
	global_load_lds_dwordx4 v[140:141], off
	s_waitcnt vmcnt(6)
	s_barrier
	v_mfma_f32_16x16x32_bf16 v[54:57], v[196:199], v[164:167], v[54:57]
	v_mfma_f32_16x16x32_bf16 v[50:53], v[204:207], v[164:167], v[50:53]
	v_mfma_f32_16x16x32_bf16 v[38:41], v[196:199], v[172:175], v[38:41]
	v_mfma_f32_16x16x32_bf16 v[34:37], v[204:207], v[172:175], v[34:37]
	v_mfma_f32_16x16x32_bf16 v[22:25], v[196:199], v[180:183], v[22:25]
	v_mfma_f32_16x16x32_bf16 v[18:21], v[204:207], v[180:183], v[18:21]
	v_mfma_f32_16x16x32_bf16 v[6:9], v[196:199], v[188:191], v[6:9]
	v_mfma_f32_16x16x32_bf16 v[2:5], v[204:207], v[188:191], v[2:5]
	v_mfma_f32_16x16x32_bf16 v[54:57], v[200:203], v[168:171], v[54:57]
	v_mfma_f32_16x16x32_bf16 v[50:53], v[208:211], v[168:171], v[50:53]
	v_mfma_f32_16x16x32_bf16 v[38:41], v[200:203], v[176:179], v[38:41]
	v_mfma_f32_16x16x32_bf16 v[34:37], v[208:211], v[176:179], v[34:37]
	v_mfma_f32_16x16x32_bf16 v[22:25], v[200:203], v[184:187], v[22:25]
	v_mfma_f32_16x16x32_bf16 v[18:21], v[208:211], v[184:187], v[18:21]
	v_mfma_f32_16x16x32_bf16 v[6:9], v[200:203], v[192:195], v[6:9]
	v_mfma_f32_16x16x32_bf16 v[2:5], v[208:211], v[192:195], v[2:5]
	s_add_i32 s34, 0, 0x18000
	v_add_u32_e32 v160, s34, v147
	s_barrier
	ds_read_b128 v[140:143], v160
	ds_read_b128 v[152:155], v160 offset:1024
	ds_read_b128 v[156:159], v160 offset:2048
	ds_read_b128 v[160:163], v160 offset:3072
	s_add_u32 s28, s78, 0xb0000
	s_addc_u32 s29, s79, 0
	s_mov_b32 m0, s77
	v_lshl_add_u64 v[196:197], s[28:29], 0, v[130:131]
	ds_read_b128 v[164:167], v151 offset:32768
	ds_read_b128 v[168:171], v151 offset:33792
	ds_read_b128 v[172:175], v151 offset:34816
	ds_read_b128 v[176:179], v151 offset:35840
	ds_read_b128 v[180:183], v151 offset:36864
	ds_read_b128 v[184:187], v151 offset:37888
	ds_read_b128 v[188:191], v151 offset:38912
	ds_read_b128 v[192:195], v151 offset:39936
	global_load_lds_dwordx4 v[196:197], off
	v_lshl_add_u64 v[196:197], s[28:29], 0, v[132:133]
	s_mov_b32 m0, s82
	s_nop 0
	global_load_lds_dwordx4 v[196:197], off
	s_waitcnt lgkmcnt(8)
	s_barrier
	s_waitcnt lgkmcnt(0)
	s_waitcnt lgkmcnt(0)
	v_mfma_f32_16x16x32_bf16 v[126:129], v[140:143], v[164:167], v[126:129]
	v_mfma_f32_16x16x32_bf16 v[122:125], v[156:159], v[164:167], v[122:125]
	v_mfma_f32_16x16x32_bf16 v[110:113], v[140:143], v[172:175], v[110:113]
	v_mfma_f32_16x16x32_bf16 v[106:109], v[156:159], v[172:175], v[106:109]
	v_mfma_f32_16x16x32_bf16 v[94:97], v[140:143], v[180:183], v[94:97]
	v_mfma_f32_16x16x32_bf16 v[90:93], v[156:159], v[180:183], v[90:93]
	v_mfma_f32_16x16x32_bf16 v[78:81], v[140:143], v[188:191], v[78:81]
	v_mfma_f32_16x16x32_bf16 v[74:77], v[156:159], v[188:191], v[74:77]
	v_mfma_f32_16x16x32_bf16 v[126:129], v[152:155], v[168:171], v[126:129]
	v_mfma_f32_16x16x32_bf16 v[122:125], v[160:163], v[168:171], v[122:125]
	v_mfma_f32_16x16x32_bf16 v[110:113], v[152:155], v[176:179], v[110:113]
	v_mfma_f32_16x16x32_bf16 v[106:109], v[160:163], v[176:179], v[106:109]
	v_mfma_f32_16x16x32_bf16 v[94:97], v[152:155], v[184:187], v[94:97]
	v_mfma_f32_16x16x32_bf16 v[90:93], v[160:163], v[184:187], v[90:93]
	v_mfma_f32_16x16x32_bf16 v[78:81], v[152:155], v[192:195], v[78:81]
	v_mfma_f32_16x16x32_bf16 v[74:77], v[160:163], v[192:195], v[74:77]
	s_barrier
	s_add_i32 s38, 0, 0x1c000
	s_add_i32 s28, s34, s72
	v_add_u32_e32 v208, s38, v147
	v_lshl_add_u64 v[144:145], v[144:145], 0, s[62:63]
	s_mov_b32 m0, s28
	ds_read_b128 v[196:199], v208
	ds_read_b128 v[200:203], v208 offset:1024
	ds_read_b128 v[204:207], v208 offset:2048
	ds_read_b128 v[208:211], v208 offset:3072
	global_load_lds_dwordx4 v[144:145], off
	v_lshl_add_u64 v[144:145], v[212:213], 0, s[62:63]
	s_add_i32 m0, s28, 0x2000
	s_nop 0
	global_load_lds_dwordx4 v[144:145], off
	s_barrier
	s_waitcnt lgkmcnt(0)
	s_waitcnt lgkmcnt(0)
	v_mfma_f32_16x16x32_bf16 v[118:121], v[196:199], v[164:167], v[118:121]
	v_mfma_f32_16x16x32_bf16 v[114:117], v[204:207], v[164:167], v[114:117]
	v_mfma_f32_16x16x32_bf16 v[102:105], v[196:199], v[172:175], v[102:105]
	v_mfma_f32_16x16x32_bf16 v[98:101], v[204:207], v[172:175], v[98:101]
	v_mfma_f32_16x16x32_bf16 v[86:89], v[196:199], v[180:183], v[86:89]
	v_mfma_f32_16x16x32_bf16 v[82:85], v[204:207], v[180:183], v[82:85]
	v_mfma_f32_16x16x32_bf16 v[70:73], v[196:199], v[188:191], v[70:73]
	v_mfma_f32_16x16x32_bf16 v[66:69], v[204:207], v[188:191], v[66:69]
	v_mfma_f32_16x16x32_bf16 v[118:121], v[200:203], v[168:171], v[118:121]
	v_mfma_f32_16x16x32_bf16 v[114:117], v[208:211], v[168:171], v[114:117]
	v_mfma_f32_16x16x32_bf16 v[102:105], v[200:203], v[176:179], v[102:105]
	v_mfma_f32_16x16x32_bf16 v[98:101], v[208:211], v[176:179], v[98:101]
	v_mfma_f32_16x16x32_bf16 v[86:89], v[200:203], v[184:187], v[86:89]
	v_mfma_f32_16x16x32_bf16 v[82:85], v[208:211], v[184:187], v[82:85]
	v_mfma_f32_16x16x32_bf16 v[70:73], v[200:203], v[192:195], v[70:73]
	v_mfma_f32_16x16x32_bf16 v[66:69], v[208:211], v[192:195], v[66:69]
	s_mov_b32 m0, s84
	v_lshl_add_u64 v[144:145], v[214:215], 0, s[62:63]
	s_barrier
	ds_read_b128 v[164:167], v151 offset:49152
	ds_read_b128 v[168:171], v151 offset:50176
	ds_read_b128 v[172:175], v151 offset:51200
	ds_read_b128 v[176:179], v151 offset:52224
	ds_read_b128 v[180:183], v151 offset:53248
	ds_read_b128 v[184:187], v151 offset:54272
	ds_read_b128 v[188:191], v151 offset:55296
	ds_read_b128 v[192:195], v151 offset:56320
	global_load_lds_dwordx4 v[144:145], off
	v_lshl_add_u64 v[144:145], v[216:217], 0, s[62:63]
	s_mov_b32 m0, s85
	s_nop 0
	global_load_lds_dwordx4 v[144:145], off
	s_barrier
; #define PG8_STAGE(bufoff, gbase, voff) do { _Pragma("unroll") for (int _i = 0; _i < 2; ++_i) \
;         __builtin_amdgcn_global_load_lds((const unsigned*)((const char*)(gbase) + (voff)[_i]), (LAS unsigned*)(lds + (bufoff) + ldsw + _i * 8192), 16, 0, 0); } while (0)
; #define PG8_MMA(ai, bj, At, Bt) do { __builtin_amdgcn_s_setprio(1); _Pragma("unroll") for (int m = 0; m < 4; ++m) _Pragma("unroll") for (int n = 0; n < 2; ++n) _Pragma("unroll") for (int k = 0; k < 2; ++k) \
;         acc[ai][bj][m][n] = __builtin_amdgcn_mfma_f32_16x16x32_bf16(Bt[n][k], At[m][k], acc[ai][bj][m][n], 0, 0, 0); __builtin_amdgcn_s_setprio(0); } while (0)
; #define PG8_WAIT_V(n) asm volatile("s_waitcnt vmcnt(" #n ")" ::: "memory")
; #define PG8_WAIT_L(n) asm volatile("s_waitcnt lgkmcnt(" #n ")" ::: "memory")
; #define PG8_BAR __builtin_amdgcn_s_barrier()
; #define PG8_SCHED __builtin_amdgcn_sched_barrier(0)
; template <class Epi, class Sched>
; __device__ __forceinline__ void gemm_phase(LAS unsigned char* lds, const Gemm g, const Sched& S, const Epi& E) {
;     ...
;             PG8_BAR; PG8_WAIT_L(0); PG8_MMA(1, 0, At, B0); PG8_BAR; PG8_SCHED;
;             PG8_STAGE(PG8_SB(1, 1), b3 + hstep, voffB);
;             PG8_WAIT_V(6); PG8_BAR; PG8_MMA(1, 1, At, B1); PG8_BAR;
;         }
	s_waitcnt lgkmcnt(0)
	s_waitcnt lgkmcnt(0)
	v_mfma_f32_16x16x32_bf16 v[62:65], v[140:143], v[164:167], v[62:65]
	v_mfma_f32_16x16x32_bf16 v[58:61], v[156:159], v[164:167], v[58:61]
	v_mfma_f32_16x16x32_bf16 v[46:49], v[140:143], v[172:175], v[46:49]
	v_mfma_f32_16x16x32_bf16 v[42:45], v[156:159], v[172:175], v[42:45]
	v_mfma_f32_16x16x32_bf16 v[30:33], v[140:143], v[180:183], v[30:33]
	v_mfma_f32_16x16x32_bf16 v[26:29], v[156:159], v[180:183], v[26:29]
	v_mfma_f32_16x16x32_bf16 v[14:17], v[140:143], v[188:191], v[14:17]
	v_mfma_f32_16x16x32_bf16 v[10:13], v[156:159], v[188:191], v[10:13]
	v_mfma_f32_16x16x32_bf16 v[62:65], v[152:155], v[168:171], v[62:65]
	v_mfma_f32_16x16x32_bf16 v[58:61], v[160:163], v[168:171], v[58:61]
	v_mfma_f32_16x16x32_bf16 v[46:49], v[152:155], v[176:179], v[46:49]
	v_mfma_f32_16x16x32_bf16 v[42:45], v[160:163], v[176:179], v[42:45]
	v_mfma_f32_16x16x32_bf16 v[30:33], v[152:155], v[184:187], v[30:33]
	v_mfma_f32_16x16x32_bf16 v[26:29], v[160:163], v[184:187], v[26:29]
	v_mfma_f32_16x16x32_bf16 v[14:17], v[152:155], v[192:195], v[14:17]
	v_mfma_f32_16x16x32_bf16 v[10:13], v[160:163], v[192:195], v[10:13]
	s_barrier
	s_add_u32 s28, s68, 0xb0080
	s_addc_u32 s29, s69, 0
	s_add_i32 s34, s38, s72
	v_lshl_add_u64 v[140:141], s[28:29], 0, v[0:1]
	s_mov_b32 m0, s34
	s_nop 0
	global_load_lds_dwordx4 v[140:141], off
	v_lshl_add_u64 v[140:141], s[28:29], 0, v[134:135]
	s_add_i32 m0, s34, 0x2000
	s_nop 0
	global_load_lds_dwordx4 v[140:141], off
	s_waitcnt vmcnt(6)
	s_barrier
	v_mfma_f32_16x16x32_bf16 v[54:57], v[196:199], v[164:167], v[54:57]
	v_mfma_f32_16x16x32_bf16 v[50:53], v[204:207], v[164:167], v[50:53]
	v_mfma_f32_16x16x32_bf16 v[38:41], v[196:199], v[172:175], v[38:41]
	v_mfma_f32_16x16x32_bf16 v[34:37], v[204:207], v[172:175], v[34:37]
	v_mfma_f32_16x16x32_bf16 v[22:25], v[196:199], v[180:183], v[22:25]
	v_mfma_f32_16x16x32_bf16 v[18:21], v[204:207], v[180:183], v[18:21]
	v_mfma_f32_16x16x32_bf16 v[6:9], v[196:199], v[188:191], v[6:9]
	v_mfma_f32_16x16x32_bf16 v[2:5], v[204:207], v[188:191], v[2:5]
	v_mfma_f32_16x16x32_bf16 v[54:57], v[200:203], v[168:171], v[54:57]
	v_mfma_f32_16x16x32_bf16 v[50:53], v[208:211], v[168:171], v[50:53]
	v_mfma_f32_16x16x32_bf16 v[38:41], v[200:203], v[176:179], v[38:41]
	v_mfma_f32_16x16x32_bf16 v[34:37], v[208:211], v[176:179], v[34:37]
	v_mfma_f32_16x16x32_bf16 v[22:25], v[200:203], v[184:187], v[22:25]
	v_mfma_f32_16x16x32_bf16 v[18:21], v[208:211], v[184:187], v[18:21]
	v_mfma_f32_16x16x32_bf16 v[6:9], v[200:203], v[192:195], v[6:9]
	v_mfma_f32_16x16x32_bf16 v[2:5], v[208:211], v[192:195], v[2:5]
	s_add_i32 s17, s17, 2
	s_add_u32 s11, s11, 0x100
	s_addc_u32 s16, s16, 0
	s_cmp_gt_u32 s17, 41
	s_mov_b64 s[28:29], s[44:45]
	s_barrier
	s_cbranch_scc0 .LBB0_851
; __device__ __forceinline__ void unpack8(const u32x4 w, float* f) { f[0] = bf_lo(w.x); f[1] = bf_hi(w.x); f[2] = bf_lo(w.y); f[3] = bf_hi(w.y); f[4] = bf_lo(w.z); f[5] = bf_hi(w.z); f[6] = bf_lo(w.w); f[7] = bf_hi(w.w); }
; __device__ __forceinline__ u32x4 pack8(const float* f) { u32x4 w; w.x = cvt_pk_bf16(f[0], f[1]); w.y = cvt_pk_bf16(f[2], f[3]); w.z = cvt_pk_bf16(f[4], f[5]); w.w = cvt_pk_bf16(f[6], f[7]); return w; }
; __device__ __forceinline__ float shx(float v, int m, int lane) { return __int_as_float(__builtin_amdgcn_ds_bpermute((lane ^ m) << 2, __float_as_int(v))); }
;     __device__ __forceinline__ void operator()(const f32x4 (&acc)[2][2][4][2], const Unit& u, int wr, int wc, int fr, int fq) const { if (u.kind == 0) e0(acc, u, wr, wc, fr, fq); else e1(acc, u, wr, wc, fr, fq); }
;     __device__ __forceinline__ void operator()(const f32x4 (&acc)[2][2][4][2], const Unit& u, int wr, int wc, int fr, int fq) const {
;         const int row0 = u.pm * BM + wr * 64 + fr, col0 = u.pn * BM + wc * 32 + 8 * fq;
; #pragma unroll
;         for (int ai = 0; ai < 2; ++ai)
; #pragma unroll
;             for (int m = 0; m < 4; ++m) { const int row = row0 + ai * HALF + m * 16; float ss = 0.f;
; #pragma unroll
;                 for (int bj = 0; bj < 2; ++bj) { const size_t off = (size_t)row * D + col0 + bj * HALF;
;                     float b[8], r[8]; unpack8(*(const u32x4*)(xb + off), b);
;                     const f32x4 v0 = acc[ai][bj][m][0], v1 = acc[ai][bj][m][1];
; #pragma unroll
;                     for (int j = 0; j < 4; ++j) { b[j] += v0[j]; b[4 + j] += v1[j]; }
;                     const u32x4 w = pack8(b);
;                     *(u32x4*)(xb + off) = w;
;                     unpack8(w, r);
; #pragma unroll
;                     for (int j = 0; j < 8; ++j) ss += r[j] * r[j]; }
;                 { const int ln = fr + 16 * fq; ss += shx(ss, 16, ln); ss += shx(ss, 32, ln); }
;                 if (fq == 0) rowss[(size_t)row * 16 + u.pn * 4 + wc] = ss; }
	v_lshl_add_u32 v142, s10, 8, v146
	v_ashrrev_i32_e32 v143, 31, v142
	v_lshl_or_b32 v140, s37, 8, v148
	v_lshlrev_b64 v[144:145], 11, v[142:143]
	v_ashrrev_i32_e32 v141, 31, v140
	v_lshl_add_u64 v[144:145], s[40:41], 0, v[144:145]
	v_lshl_add_u64 v[144:145], v[140:141], 1, v[144:145]
	global_load_dwordx4 v[158:161], v[144:145], off
	global_load_dwordx4 v[162:165], v[144:145], off offset:256
	s_mov_b32 s100, 0x8000
	s_mov_b32 s101, 0
	v_lshl_add_u64 v[230:231], v[144:145], 0, s[100:101]
	global_load_dwordx4 v[166:169], v[230:231], off
	global_load_dwordx4 v[170:173], v[230:231], off offset:256
	v_lshl_add_u64 v[230:231], v[230:231], 0, s[100:101]
	global_load_dwordx4 v[190:193], v[230:231], off
	global_load_dwordx4 v[194:197], v[230:231], off offset:256
	v_lshl_add_u64 v[230:231], v[230:231], 0, s[100:101]
	global_load_dwordx4 v[198:201], v[230:231], off
	global_load_dwordx4 v[202:205], v[230:231], off offset:256
	s_mov_b32 s100, 0x28000
	v_lshl_add_u64 v[230:231], v[230:231], 0, s[100:101]
	global_load_dwordx4 v[206:209], v[230:231], off
	global_load_dwordx4 v[210:213], v[230:231], off offset:256
	s_mov_b32 s100, 0x8000
	v_lshl_add_u64 v[230:231], v[230:231], 0, s[100:101]
	global_load_dwordx4 v[214:217], v[230:231], off
	global_load_dwordx4 v[218:221], v[230:231], off offset:256
	v_lshl_add_u64 v[230:231], v[230:231], 0, s[100:101]
	global_load_dwordx4 v[222:225], v[230:231], off
	global_load_dwordx4 v[226:229], v[230:231], off offset:256
	v_lshl_add_u64 v[230:231], v[230:231], 0, s[100:101]
	global_load_dwordx4 v[236:239], v[230:231], off
	global_load_dwordx4 v[248:251], v[230:231], off offset:256
	s_waitcnt vmcnt(15)
	v_mov_b64_e32 v[152:153], v[158:159]
	v_mov_b64_e32 v[154:155], v[160:161]
	v_lshlrev_b32_e32 v156, 16, v152
	v_and_b32_e32 v157, 0xffff0000, v152
	v_pk_add_f32 v[126:127], v[126:127], v[156:157]
	v_lshlrev_b32_e32 v156, 16, v154
	v_and_b32_e32 v157, 0xffff0000, v154
	v_pk_add_f32 v[156:157], v[122:123], v[156:157]
	v_lshlrev_b32_e32 v122, 16, v153
	v_and_b32_e32 v123, 0xffff0000, v153
	v_pk_add_f32 v[128:129], v[128:129], v[122:123]
	v_lshlrev_b32_e32 v122, 16, v155
	v_and_b32_e32 v123, 0xffff0000, v155
	v_pk_add_f32 v[152:153], v[124:125], v[122:123]
	v_cvt_pk_bf16_f32 v122, v126, v127
	v_cvt_pk_bf16_f32 v123, v128, v129
	v_cvt_pk_bf16_f32 v124, v156, v157
	v_cvt_pk_bf16_f32 v125, v152, v153
	global_store_dwordx4 v[144:145], v[122:125], off
	v_lshlrev_b32_e32 v126, 16, v122
	v_lshlrev_b32_e32 v127, 16, v123
	v_and_b32_e32 v122, 0xffff0000, v122
	v_mul_f32_e32 v152, v122, v122
	v_fmac_f32_e32 v152, v126, v126
	v_and_b32_e32 v123, 0xffff0000, v123
	v_fmac_f32_e32 v152, v127, v127
	v_lshlrev_b32_e32 v128, 16, v124
	v_fmac_f32_e32 v152, v123, v123
	v_and_b32_e32 v124, 0xffff0000, v124
	v_fmac_f32_e32 v152, v128, v128
	v_lshlrev_b32_e32 v129, 16, v125
	v_fmac_f32_e32 v152, v124, v124
	v_and_b32_e32 v125, 0xffff0000, v125
	v_fmac_f32_e32 v152, v129, v129
	v_fmac_f32_e32 v152, v125, v125
	s_waitcnt vmcnt(14)
	v_mov_b64_e32 v[122:123], v[162:163]
	v_mov_b64_e32 v[124:125], v[164:165]
	v_lshlrev_b32_e32 v126, 16, v122
	v_and_b32_e32 v127, 0xffff0000, v122
	v_pk_add_f32 v[118:119], v[118:119], v[126:127]
	v_lshlrev_b32_e32 v126, 16, v124
	v_and_b32_e32 v127, 0xffff0000, v124
	v_pk_add_f32 v[126:127], v[114:115], v[126:127]
	v_lshlrev_b32_e32 v114, 16, v123
	v_and_b32_e32 v115, 0xffff0000, v123
	v_pk_add_f32 v[120:121], v[120:121], v[114:115]
	v_lshlrev_b32_e32 v114, 16, v125
	v_and_b32_e32 v115, 0xffff0000, v125
	v_pk_add_f32 v[122:123], v[116:117], v[114:115]
	v_cvt_pk_bf16_f32 v114, v118, v119
	v_cvt_pk_bf16_f32 v115, v120, v121
	v_cvt_pk_bf16_f32 v116, v126, v127
	v_cvt_pk_bf16_f32 v117, v122, v123
	v_lshlrev_b32_e32 v118, 16, v114
	global_store_dwordx4 v[144:145], v[114:117], off offset:256
	v_fmac_f32_e32 v152, v118, v118
	v_lshlrev_b32_e32 v119, 16, v115
	v_and_b32_e32 v114, 0xffff0000, v114
	v_fmac_f32_e32 v152, v114, v114
	v_and_b32_e32 v115, 0xffff0000, v115
	v_fmac_f32_e32 v152, v119, v119
	v_lshlrev_b32_e32 v120, 16, v116
	v_fmac_f32_e32 v152, v115, v115
	v_and_b32_e32 v116, 0xffff0000, v116
	v_fmac_f32_e32 v152, v120, v120
	v_lshlrev_b32_e32 v121, 16, v117
	v_fmac_f32_e32 v152, v116, v116
	v_and_b32_e32 v117, 0xffff0000, v117
	v_fmac_f32_e32 v152, v121, v121
	v_fmac_f32_e32 v152, v117, v117
	ds_bpermute_b32 v114, v149, v152
	s_waitcnt lgkmcnt(0)
	v_add_f32_e32 v114, v152, v114
	ds_bpermute_b32 v115, v150, v114
	s_and_saveexec_b64 s[28:29], s[4:5]
	s_cbranch_execz .LBB0_854
	s_waitcnt lgkmcnt(0)
	v_add_f32_e32 v116, v114, v115
	s_lshl_b32 s10, s37, 2
	v_lshlrev_b64 v[114:115], 6, v[142:143]
	s_ashr_i32 s11, s10, 31
	v_lshl_add_u64 v[114:115], s[42:43], 0, v[114:115]
	v_lshl_add_u64 v[114:115], s[10:11], 2, v[114:115]
	s_lshl_b32 s58, s83, 2
	v_lshl_add_u64 v[114:115], v[114:115], 0, s[58:59]
	global_store_dword v[114:115], v116, off
